# triangular solve: A rows read as b32 (4x less LDS traffic) and broadcast inside quads by DPP quad_perm on the FMA operand, 12 reads in flight, plus s_setprio 2 on the solve waves
# speedup vs baseline: 1.0078x; 1.0078x over previous
.LBB0_807:
	s_or_b64 exec, exec, s[0:1]
	v_lshl_add_u32 v11, v1, 2, s76
	v_and_b32_e32 v255, 3, v180
	v_lshl_add_u32 v255, v255, 2, v11
	ds_read_u16 v238, v18 offset:544
	ds_read_b32 v239, v16 offset:8
	ds_read_b32 v254, v15 offset:8
	ds_read_b32 v240, v255 offset:256
	s_waitcnt lgkmcnt(0)
	v_mul_f32_dpp v4, v240, v2 quad_perm:[0,0,0,0] row_mask:0xf bank_mask:0xf
	ds_read_b32 v240, v255 offset:512
	v_sub_f32_e32 v3, v3, v4
	v_lshlrev_b32_e32 v4, 16, v238
	v_mul_f32_e32 v4, v239, v4
	s_and_saveexec_b64 s[0:1], s[16:17]
	s_cbranch_execz .LBB0_809
	v_mul_f32_e32 v4, v4, v254
.LBB0_809:
	s_or_b64 exec, exec, s[0:1]
	ds_read_u16 v238, v18 offset:816
	ds_read_b32 v239, v16 offset:12
	ds_read_b32 v254, v15 offset:12
	s_waitcnt lgkmcnt(3)
	v_mul_f32_dpp v5, v240, v2 quad_perm:[0,0,0,0] row_mask:0xf bank_mask:0xf
	v_mul_f32_dpp v6, v240, v3 quad_perm:[1,1,1,1] row_mask:0xf bank_mask:0xf
	ds_read_b32 v240, v255 offset:768
	v_add_f32_e32 v5, v5, v6
	v_sub_f32_e32 v4, v4, v5
	s_waitcnt lgkmcnt(1)
	v_lshlrev_b32_e32 v5, 16, v238
	v_mul_f32_e32 v5, v239, v5
	s_and_saveexec_b64 s[0:1], s[16:17]
	s_cbranch_execz .LBB0_811
	v_mul_f32_e32 v5, v5, v254
.LBB0_811:
	s_or_b64 exec, exec, s[0:1]
	ds_read_u16 v238, v18 offset:1088
	ds_read_b32 v239, v16 offset:16
	ds_read_b32 v254, v15 offset:16
	s_waitcnt lgkmcnt(3)
	v_mul_f32_dpp v6, v240, v2 quad_perm:[0,0,0,0] row_mask:0xf bank_mask:0xf
	v_mul_f32_dpp v7, v240, v3 quad_perm:[1,1,1,1] row_mask:0xf bank_mask:0xf
	v_mul_f32_dpp v8, v240, v4 quad_perm:[2,2,2,2] row_mask:0xf bank_mask:0xf
	ds_read_b32 v240, v255 offset:1024
	v_add_f32_e32 v6, v6, v7
	v_add_f32_e32 v6, v8, v6
	v_sub_f32_e32 v5, v5, v6
	s_waitcnt lgkmcnt(1)
	v_lshlrev_b32_e32 v6, 16, v238
	v_mul_f32_e32 v6, v239, v6
	s_and_saveexec_b64 s[0:1], s[16:17]
	s_cbranch_execz .LBB0_813
	v_mul_f32_e32 v6, v6, v254
.LBB0_813:
	s_or_b64 exec, exec, s[0:1]
	ds_read_u16 v238, v18 offset:1360
	ds_read_b32 v239, v16 offset:20
	ds_read_b32 v254, v15 offset:20
	s_waitcnt lgkmcnt(3)
	v_mul_f32_dpp v7, v240, v2 quad_perm:[0,0,0,0] row_mask:0xf bank_mask:0xf
	v_mul_f32_dpp v8, v240, v3 quad_perm:[1,1,1,1] row_mask:0xf bank_mask:0xf
	v_mul_f32_dpp v9, v240, v4 quad_perm:[2,2,2,2] row_mask:0xf bank_mask:0xf
	v_mul_f32_dpp v10, v240, v5 quad_perm:[3,3,3,3] row_mask:0xf bank_mask:0xf
	ds_read_b32 v240, v255 offset:1280
	ds_read_b32 v241, v255 offset:1296
	v_add_f32_e32 v7, v7, v8
	v_add_f32_e32 v8, v9, v10
	v_add_f32_e32 v7, v7, v8
	v_sub_f32_e32 v6, v6, v7
	s_waitcnt lgkmcnt(2)
	v_lshlrev_b32_e32 v7, 16, v238
	v_mul_f32_e32 v7, v239, v7
	s_and_saveexec_b64 s[0:1], s[16:17]
	s_cbranch_execz .LBB0_815
	v_mul_f32_e32 v7, v7, v254
.LBB0_815:
	s_or_b64 exec, exec, s[0:1]
	ds_read_u16 v238, v18 offset:1632
	ds_read_b32 v239, v16 offset:24
	ds_read_b32 v254, v15 offset:24
	s_waitcnt lgkmcnt(4)
	v_mul_f32_dpp v8, v240, v2 quad_perm:[0,0,0,0] row_mask:0xf bank_mask:0xf
	v_mul_f32_dpp v9, v240, v3 quad_perm:[1,1,1,1] row_mask:0xf bank_mask:0xf
	v_mul_f32_dpp v10, v240, v4 quad_perm:[2,2,2,2] row_mask:0xf bank_mask:0xf
	v_mul_f32_dpp v12, v240, v5 quad_perm:[3,3,3,3] row_mask:0xf bank_mask:0xf
	s_waitcnt lgkmcnt(3)
	v_fmac_f32_dpp v8, v241, v6 quad_perm:[0,0,0,0] row_mask:0xf bank_mask:0xf
	ds_read_b32 v240, v255 offset:1536
	ds_read_b32 v241, v255 offset:1552
	v_add_f32_e32 v8, v9, v8
	v_add_f32_e32 v9, v10, v12
	v_add_f32_e32 v8, v9, v8
	v_sub_f32_e32 v7, v7, v8
	s_waitcnt lgkmcnt(2)
	v_lshlrev_b32_e32 v8, 16, v238
	v_mul_f32_e32 v8, v239, v8
	s_and_saveexec_b64 s[0:1], s[16:17]
	s_cbranch_execz .LBB0_817
	v_mul_f32_e32 v8, v8, v254
.LBB0_817:
	s_or_b64 exec, exec, s[0:1]
	ds_read_u16 v238, v18 offset:1904
	ds_read_b32 v239, v16 offset:28
	ds_read_b32 v254, v15 offset:28
	s_waitcnt lgkmcnt(4)
	v_mul_f32_dpp v9, v240, v2 quad_perm:[0,0,0,0] row_mask:0xf bank_mask:0xf
	v_mul_f32_dpp v10, v240, v3 quad_perm:[1,1,1,1] row_mask:0xf bank_mask:0xf
	v_mul_f32_dpp v12, v240, v4 quad_perm:[2,2,2,2] row_mask:0xf bank_mask:0xf
	v_mul_f32_dpp v13, v240, v5 quad_perm:[3,3,3,3] row_mask:0xf bank_mask:0xf
	s_waitcnt lgkmcnt(3)
	v_fmac_f32_dpp v9, v241, v6 quad_perm:[0,0,0,0] row_mask:0xf bank_mask:0xf
	v_fmac_f32_dpp v10, v241, v7 quad_perm:[1,1,1,1] row_mask:0xf bank_mask:0xf
	ds_read_b32 v240, v255 offset:1792
	ds_read_b32 v241, v255 offset:1808
	v_add_f32_e32 v9, v9, v10
	v_add_f32_e32 v10, v12, v13
	v_add_f32_e32 v9, v10, v9
	v_sub_f32_e32 v8, v8, v9
	s_waitcnt lgkmcnt(2)
	v_lshlrev_b32_e32 v9, 16, v238
	v_mul_f32_e32 v9, v239, v9
	s_and_saveexec_b64 s[0:1], s[16:17]
	s_cbranch_execz .LBB0_819
	v_mul_f32_e32 v9, v9, v254
.LBB0_819:
	s_or_b64 exec, exec, s[0:1]
	ds_read_u16 v238, v18 offset:2176
	ds_read_b32 v239, v16 offset:32
	ds_read_b32 v254, v15 offset:32
	s_waitcnt lgkmcnt(4)
	v_mul_f32_dpp v10, v240, v2 quad_perm:[0,0,0,0] row_mask:0xf bank_mask:0xf
	v_mul_f32_dpp v12, v240, v3 quad_perm:[1,1,1,1] row_mask:0xf bank_mask:0xf
	v_mul_f32_dpp v13, v240, v4 quad_perm:[2,2,2,2] row_mask:0xf bank_mask:0xf
	v_mul_f32_dpp v14, v240, v5 quad_perm:[3,3,3,3] row_mask:0xf bank_mask:0xf
	s_waitcnt lgkmcnt(3)
	v_fmac_f32_dpp v10, v241, v6 quad_perm:[0,0,0,0] row_mask:0xf bank_mask:0xf
	v_fmac_f32_dpp v12, v241, v7 quad_perm:[1,1,1,1] row_mask:0xf bank_mask:0xf
	v_fmac_f32_dpp v13, v241, v8 quad_perm:[2,2,2,2] row_mask:0xf bank_mask:0xf
	ds_read_b32 v240, v255 offset:2048
	ds_read_b32 v241, v255 offset:2064
	v_add_f32_e32 v10, v10, v12
	v_add_f32_e32 v12, v14, v13
	v_add_f32_e32 v10, v10, v12
	v_sub_f32_e32 v9, v9, v10
	s_waitcnt lgkmcnt(2)
	v_lshlrev_b32_e32 v10, 16, v238
	v_mul_f32_e32 v10, v239, v10
	s_and_saveexec_b64 s[0:1], s[16:17]
	s_cbranch_execz .LBB0_821
	v_mul_f32_e32 v10, v10, v254
.LBB0_821:
	s_or_b64 exec, exec, s[0:1]
	ds_read_u16 v238, v18 offset:2448
	ds_read_b32 v239, v16 offset:36
	ds_read_b32 v254, v15 offset:36
	s_waitcnt lgkmcnt(4)
	v_mul_f32_dpp v12, v240, v2 quad_perm:[0,0,0,0] row_mask:0xf bank_mask:0xf
	v_mul_f32_dpp v13, v240, v3 quad_perm:[1,1,1,1] row_mask:0xf bank_mask:0xf
	v_mul_f32_dpp v14, v240, v4 quad_perm:[2,2,2,2] row_mask:0xf bank_mask:0xf
	v_mul_f32_dpp v17, v240, v5 quad_perm:[3,3,3,3] row_mask:0xf bank_mask:0xf
	s_waitcnt lgkmcnt(3)
	v_fmac_f32_dpp v12, v241, v6 quad_perm:[0,0,0,0] row_mask:0xf bank_mask:0xf
	v_fmac_f32_dpp v13, v241, v7 quad_perm:[1,1,1,1] row_mask:0xf bank_mask:0xf
	v_fmac_f32_dpp v14, v241, v8 quad_perm:[2,2,2,2] row_mask:0xf bank_mask:0xf
	v_fmac_f32_dpp v17, v241, v9 quad_perm:[3,3,3,3] row_mask:0xf bank_mask:0xf
	ds_read_b32 v240, v255 offset:2304
	ds_read_b32 v241, v255 offset:2320
	ds_read_b32 v242, v255 offset:2336
	v_add_f32_e32 v12, v12, v13
	v_add_f32_e32 v13, v14, v17
	v_add_f32_e32 v12, v12, v13
	v_sub_f32_e32 v10, v10, v12
	s_waitcnt lgkmcnt(3)
	v_lshlrev_b32_e32 v12, 16, v238
	v_mul_f32_e32 v12, v239, v12
	s_and_saveexec_b64 s[0:1], s[16:17]
	s_cbranch_execz .LBB0_823
	v_mul_f32_e32 v12, v12, v254
.LBB0_823:
	s_or_b64 exec, exec, s[0:1]
	ds_read_u16 v238, v18 offset:2720
	ds_read_b32 v239, v16 offset:40
	ds_read_b32 v254, v15 offset:40
	s_waitcnt lgkmcnt(5)
	v_mul_f32_dpp v13, v240, v2 quad_perm:[0,0,0,0] row_mask:0xf bank_mask:0xf
	v_mul_f32_dpp v14, v240, v3 quad_perm:[1,1,1,1] row_mask:0xf bank_mask:0xf
	v_mul_f32_dpp v17, v240, v4 quad_perm:[2,2,2,2] row_mask:0xf bank_mask:0xf
	v_mul_f32_dpp v19, v240, v5 quad_perm:[3,3,3,3] row_mask:0xf bank_mask:0xf
	s_waitcnt lgkmcnt(4)
	v_fmac_f32_dpp v13, v241, v6 quad_perm:[0,0,0,0] row_mask:0xf bank_mask:0xf
	v_fmac_f32_dpp v14, v241, v7 quad_perm:[1,1,1,1] row_mask:0xf bank_mask:0xf
	v_fmac_f32_dpp v17, v241, v8 quad_perm:[2,2,2,2] row_mask:0xf bank_mask:0xf
	v_fmac_f32_dpp v19, v241, v9 quad_perm:[3,3,3,3] row_mask:0xf bank_mask:0xf
	s_waitcnt lgkmcnt(3)
	v_fmac_f32_dpp v13, v242, v10 quad_perm:[0,0,0,0] row_mask:0xf bank_mask:0xf
	ds_read_b32 v240, v255 offset:2560
	ds_read_b32 v241, v255 offset:2576
	ds_read_b32 v242, v255 offset:2592
	v_add_f32_e32 v13, v14, v13
	v_add_f32_e32 v14, v17, v19
	v_add_f32_e32 v13, v14, v13
	v_sub_f32_e32 v12, v12, v13
	s_waitcnt lgkmcnt(3)
	v_lshlrev_b32_e32 v13, 16, v238
	v_mul_f32_e32 v13, v239, v13
	s_and_saveexec_b64 s[0:1], s[16:17]
	s_cbranch_execz .LBB0_825
	v_mul_f32_e32 v13, v13, v254
.LBB0_825:
	s_or_b64 exec, exec, s[0:1]
	ds_read_u16 v238, v18 offset:2992
	ds_read_b32 v239, v16 offset:44
	ds_read_b32 v254, v15 offset:44
	s_waitcnt lgkmcnt(5)
	v_mul_f32_dpp v14, v240, v2 quad_perm:[0,0,0,0] row_mask:0xf bank_mask:0xf
	v_mul_f32_dpp v17, v240, v3 quad_perm:[1,1,1,1] row_mask:0xf bank_mask:0xf
	v_mul_f32_dpp v19, v240, v4 quad_perm:[2,2,2,2] row_mask:0xf bank_mask:0xf
	v_mul_f32_dpp v28, v240, v5 quad_perm:[3,3,3,3] row_mask:0xf bank_mask:0xf
	s_waitcnt lgkmcnt(4)
	v_fmac_f32_dpp v14, v241, v6 quad_perm:[0,0,0,0] row_mask:0xf bank_mask:0xf
	v_fmac_f32_dpp v17, v241, v7 quad_perm:[1,1,1,1] row_mask:0xf bank_mask:0xf
	v_fmac_f32_dpp v19, v241, v8 quad_perm:[2,2,2,2] row_mask:0xf bank_mask:0xf
	v_fmac_f32_dpp v28, v241, v9 quad_perm:[3,3,3,3] row_mask:0xf bank_mask:0xf
	s_waitcnt lgkmcnt(3)
	v_fmac_f32_dpp v14, v242, v10 quad_perm:[0,0,0,0] row_mask:0xf bank_mask:0xf
	v_fmac_f32_dpp v17, v242, v12 quad_perm:[1,1,1,1] row_mask:0xf bank_mask:0xf
	ds_read_b32 v240, v255 offset:2816
	ds_read_b32 v241, v255 offset:2832
	ds_read_b32 v242, v255 offset:2848
	v_add_f32_e32 v14, v14, v17
	v_add_f32_e32 v17, v19, v28
	v_add_f32_e32 v14, v17, v14
	v_sub_f32_e32 v13, v13, v14
	s_waitcnt lgkmcnt(3)
	v_lshlrev_b32_e32 v14, 16, v238
	v_mul_f32_e32 v14, v239, v14
	s_and_saveexec_b64 s[0:1], s[16:17]
	s_cbranch_execz .LBB0_827
	v_mul_f32_e32 v14, v14, v254
.LBB0_827:
	s_or_b64 exec, exec, s[0:1]
	ds_read_u16 v238, v18 offset:3264
	ds_read_b32 v239, v16 offset:48
	ds_read_b32 v254, v15 offset:48
	s_waitcnt lgkmcnt(5)
	v_mul_f32_dpp v17, v240, v2 quad_perm:[0,0,0,0] row_mask:0xf bank_mask:0xf
	v_mul_f32_dpp v19, v240, v3 quad_perm:[1,1,1,1] row_mask:0xf bank_mask:0xf
	v_mul_f32_dpp v28, v240, v4 quad_perm:[2,2,2,2] row_mask:0xf bank_mask:0xf
	v_mul_f32_dpp v35, v240, v5 quad_perm:[3,3,3,3] row_mask:0xf bank_mask:0xf
	s_waitcnt lgkmcnt(4)
	v_fmac_f32_dpp v17, v241, v6 quad_perm:[0,0,0,0] row_mask:0xf bank_mask:0xf
	v_fmac_f32_dpp v19, v241, v7 quad_perm:[1,1,1,1] row_mask:0xf bank_mask:0xf
	v_fmac_f32_dpp v28, v241, v8 quad_perm:[2,2,2,2] row_mask:0xf bank_mask:0xf
	v_fmac_f32_dpp v35, v241, v9 quad_perm:[3,3,3,3] row_mask:0xf bank_mask:0xf
	s_waitcnt lgkmcnt(3)
	v_fmac_f32_dpp v17, v242, v10 quad_perm:[0,0,0,0] row_mask:0xf bank_mask:0xf
	v_fmac_f32_dpp v19, v242, v12 quad_perm:[1,1,1,1] row_mask:0xf bank_mask:0xf
	v_fmac_f32_dpp v28, v242, v13 quad_perm:[2,2,2,2] row_mask:0xf bank_mask:0xf
	ds_read_b32 v240, v255 offset:3072
	ds_read_b32 v241, v255 offset:3088
	ds_read_b32 v242, v255 offset:3104
	v_add_f32_e32 v17, v17, v19
	v_add_f32_e32 v19, v35, v28
	v_add_f32_e32 v17, v17, v19
	v_sub_f32_e32 v14, v14, v17
	s_waitcnt lgkmcnt(3)
	v_lshlrev_b32_e32 v17, 16, v238
	v_mul_f32_e32 v17, v239, v17
	s_and_saveexec_b64 s[0:1], s[16:17]
	s_cbranch_execz .LBB0_829
	v_mul_f32_e32 v17, v17, v254
.LBB0_829:
	s_or_b64 exec, exec, s[0:1]
	ds_read_u16 v238, v18 offset:3536
	ds_read_b32 v239, v16 offset:52
	ds_read_b32 v254, v15 offset:52
	s_waitcnt lgkmcnt(5)
	v_mul_f32_dpp v19, v240, v2 quad_perm:[0,0,0,0] row_mask:0xf bank_mask:0xf
	v_mul_f32_dpp v28, v240, v3 quad_perm:[1,1,1,1] row_mask:0xf bank_mask:0xf
	v_mul_f32_dpp v35, v240, v4 quad_perm:[2,2,2,2] row_mask:0xf bank_mask:0xf
	v_mul_f32_dpp v36, v240, v5 quad_perm:[3,3,3,3] row_mask:0xf bank_mask:0xf
	s_waitcnt lgkmcnt(4)
	v_fmac_f32_dpp v19, v241, v6 quad_perm:[0,0,0,0] row_mask:0xf bank_mask:0xf
	v_fmac_f32_dpp v28, v241, v7 quad_perm:[1,1,1,1] row_mask:0xf bank_mask:0xf
	v_fmac_f32_dpp v35, v241, v8 quad_perm:[2,2,2,2] row_mask:0xf bank_mask:0xf
	v_fmac_f32_dpp v36, v241, v9 quad_perm:[3,3,3,3] row_mask:0xf bank_mask:0xf
	s_waitcnt lgkmcnt(3)
	v_fmac_f32_dpp v19, v242, v10 quad_perm:[0,0,0,0] row_mask:0xf bank_mask:0xf
	v_fmac_f32_dpp v28, v242, v12 quad_perm:[1,1,1,1] row_mask:0xf bank_mask:0xf
	v_fmac_f32_dpp v35, v242, v13 quad_perm:[2,2,2,2] row_mask:0xf bank_mask:0xf
	v_fmac_f32_dpp v36, v242, v14 quad_perm:[3,3,3,3] row_mask:0xf bank_mask:0xf
	ds_read_b32 v240, v255 offset:3328
	ds_read_b32 v241, v255 offset:3344
	ds_read_b32 v242, v255 offset:3360
	ds_read_b32 v243, v255 offset:3376
	v_add_f32_e32 v19, v19, v28
	v_add_f32_e32 v28, v35, v36
	v_add_f32_e32 v19, v19, v28
	v_sub_f32_e32 v17, v17, v19
	s_waitcnt lgkmcnt(4)
	v_lshlrev_b32_e32 v19, 16, v238
	v_mul_f32_e32 v19, v239, v19
	s_and_saveexec_b64 s[0:1], s[16:17]
	s_cbranch_execz .LBB0_831
	v_mul_f32_e32 v19, v19, v254
.LBB0_831:
	s_or_b64 exec, exec, s[0:1]
	ds_read_u16 v238, v18 offset:3808
	ds_read_b32 v239, v16 offset:56
	ds_read_b32 v254, v15 offset:56
	s_waitcnt lgkmcnt(6)
	v_mul_f32_dpp v28, v240, v2 quad_perm:[0,0,0,0] row_mask:0xf bank_mask:0xf
	v_mul_f32_dpp v35, v240, v3 quad_perm:[1,1,1,1] row_mask:0xf bank_mask:0xf
	v_mul_f32_dpp v36, v240, v4 quad_perm:[2,2,2,2] row_mask:0xf bank_mask:0xf
	v_mul_f32_dpp v37, v240, v5 quad_perm:[3,3,3,3] row_mask:0xf bank_mask:0xf
	s_waitcnt lgkmcnt(5)
	v_fmac_f32_dpp v28, v241, v6 quad_perm:[0,0,0,0] row_mask:0xf bank_mask:0xf
	v_fmac_f32_dpp v35, v241, v7 quad_perm:[1,1,1,1] row_mask:0xf bank_mask:0xf
	v_fmac_f32_dpp v36, v241, v8 quad_perm:[2,2,2,2] row_mask:0xf bank_mask:0xf
	v_fmac_f32_dpp v37, v241, v9 quad_perm:[3,3,3,3] row_mask:0xf bank_mask:0xf
	s_waitcnt lgkmcnt(4)
	v_fmac_f32_dpp v28, v242, v10 quad_perm:[0,0,0,0] row_mask:0xf bank_mask:0xf
	v_fmac_f32_dpp v35, v242, v12 quad_perm:[1,1,1,1] row_mask:0xf bank_mask:0xf
	v_fmac_f32_dpp v36, v242, v13 quad_perm:[2,2,2,2] row_mask:0xf bank_mask:0xf
	v_fmac_f32_dpp v37, v242, v14 quad_perm:[3,3,3,3] row_mask:0xf bank_mask:0xf
	s_waitcnt lgkmcnt(3)
	v_fmac_f32_dpp v28, v243, v17 quad_perm:[0,0,0,0] row_mask:0xf bank_mask:0xf
	ds_read_b32 v240, v255 offset:3584
	ds_read_b32 v241, v255 offset:3600
	ds_read_b32 v242, v255 offset:3616
	ds_read_b32 v243, v255 offset:3632
	v_add_f32_e32 v28, v35, v28
	v_add_f32_e32 v35, v36, v37
	v_add_f32_e32 v28, v35, v28
	v_sub_f32_e32 v19, v19, v28
	s_waitcnt lgkmcnt(4)
	v_lshlrev_b32_e32 v28, 16, v238
	v_mul_f32_e32 v28, v239, v28
	s_and_saveexec_b64 s[0:1], s[16:17]
	s_cbranch_execz .LBB0_833
	v_mul_f32_e32 v28, v28, v254
.LBB0_833:
	s_or_b64 exec, exec, s[0:1]
	ds_read_u16 v238, v18 offset:4080
	ds_read_b32 v239, v16 offset:60
	ds_read_b32 v254, v15 offset:60
	s_waitcnt lgkmcnt(6)
	v_mul_f32_dpp v35, v240, v2 quad_perm:[0,0,0,0] row_mask:0xf bank_mask:0xf
	v_mul_f32_dpp v36, v240, v3 quad_perm:[1,1,1,1] row_mask:0xf bank_mask:0xf
	v_mul_f32_dpp v37, v240, v4 quad_perm:[2,2,2,2] row_mask:0xf bank_mask:0xf
	v_mul_f32_dpp v38, v240, v5 quad_perm:[3,3,3,3] row_mask:0xf bank_mask:0xf
	s_waitcnt lgkmcnt(5)
	v_fmac_f32_dpp v35, v241, v6 quad_perm:[0,0,0,0] row_mask:0xf bank_mask:0xf
	v_fmac_f32_dpp v36, v241, v7 quad_perm:[1,1,1,1] row_mask:0xf bank_mask:0xf
	v_fmac_f32_dpp v37, v241, v8 quad_perm:[2,2,2,2] row_mask:0xf bank_mask:0xf
	v_fmac_f32_dpp v38, v241, v9 quad_perm:[3,3,3,3] row_mask:0xf bank_mask:0xf
	s_waitcnt lgkmcnt(4)
	v_fmac_f32_dpp v35, v242, v10 quad_perm:[0,0,0,0] row_mask:0xf bank_mask:0xf
	v_fmac_f32_dpp v36, v242, v12 quad_perm:[1,1,1,1] row_mask:0xf bank_mask:0xf
	v_fmac_f32_dpp v37, v242, v13 quad_perm:[2,2,2,2] row_mask:0xf bank_mask:0xf
	v_fmac_f32_dpp v38, v242, v14 quad_perm:[3,3,3,3] row_mask:0xf bank_mask:0xf
	s_waitcnt lgkmcnt(3)
	v_fmac_f32_dpp v35, v243, v17 quad_perm:[0,0,0,0] row_mask:0xf bank_mask:0xf
	v_fmac_f32_dpp v36, v243, v19 quad_perm:[1,1,1,1] row_mask:0xf bank_mask:0xf
	ds_read_b32 v240, v255 offset:3840
	ds_read_b32 v241, v255 offset:3856
	ds_read_b32 v242, v255 offset:3872
	ds_read_b32 v243, v255 offset:3888
	v_add_f32_e32 v35, v35, v36
	v_add_f32_e32 v36, v37, v38
	v_add_f32_e32 v35, v36, v35
	v_sub_f32_e32 v28, v28, v35
	s_waitcnt lgkmcnt(4)
	v_lshlrev_b32_e32 v35, 16, v238
	v_mul_f32_e32 v35, v239, v35
	s_and_saveexec_b64 s[0:1], s[16:17]
	s_cbranch_execz .LBB0_835
	v_mul_f32_e32 v35, v35, v254
.LBB0_835:
	s_or_b64 exec, exec, s[0:1]
	ds_read_u16 v238, v18 offset:4352
	ds_read_b32 v239, v16 offset:64
	ds_read_b32 v254, v15 offset:64
	s_waitcnt lgkmcnt(6)
	v_mul_f32_dpp v36, v240, v2 quad_perm:[0,0,0,0] row_mask:0xf bank_mask:0xf
	v_mul_f32_dpp v37, v240, v3 quad_perm:[1,1,1,1] row_mask:0xf bank_mask:0xf
	v_mul_f32_dpp v38, v240, v4 quad_perm:[2,2,2,2] row_mask:0xf bank_mask:0xf
	v_mul_f32_dpp v39, v240, v5 quad_perm:[3,3,3,3] row_mask:0xf bank_mask:0xf
	s_waitcnt lgkmcnt(5)
	v_fmac_f32_dpp v36, v241, v6 quad_perm:[0,0,0,0] row_mask:0xf bank_mask:0xf
	v_fmac_f32_dpp v37, v241, v7 quad_perm:[1,1,1,1] row_mask:0xf bank_mask:0xf
	v_fmac_f32_dpp v38, v241, v8 quad_perm:[2,2,2,2] row_mask:0xf bank_mask:0xf
	v_fmac_f32_dpp v39, v241, v9 quad_perm:[3,3,3,3] row_mask:0xf bank_mask:0xf
	s_waitcnt lgkmcnt(4)
	v_fmac_f32_dpp v36, v242, v10 quad_perm:[0,0,0,0] row_mask:0xf bank_mask:0xf
	v_fmac_f32_dpp v37, v242, v12 quad_perm:[1,1,1,1] row_mask:0xf bank_mask:0xf
	v_fmac_f32_dpp v38, v242, v13 quad_perm:[2,2,2,2] row_mask:0xf bank_mask:0xf
	v_fmac_f32_dpp v39, v242, v14 quad_perm:[3,3,3,3] row_mask:0xf bank_mask:0xf
	s_waitcnt lgkmcnt(3)
	v_fmac_f32_dpp v36, v243, v17 quad_perm:[0,0,0,0] row_mask:0xf bank_mask:0xf
	v_fmac_f32_dpp v37, v243, v19 quad_perm:[1,1,1,1] row_mask:0xf bank_mask:0xf
	v_fmac_f32_dpp v38, v243, v28 quad_perm:[2,2,2,2] row_mask:0xf bank_mask:0xf
	ds_read_b32 v240, v255 offset:4096
	ds_read_b32 v241, v255 offset:4112
	ds_read_b32 v242, v255 offset:4128
	ds_read_b32 v243, v255 offset:4144
	v_add_f32_e32 v36, v36, v37
	v_add_f32_e32 v37, v39, v38
	v_add_f32_e32 v36, v36, v37
	v_sub_f32_e32 v35, v35, v36
	s_waitcnt lgkmcnt(4)
	v_lshlrev_b32_e32 v36, 16, v238
	v_mul_f32_e32 v36, v239, v36
	s_and_saveexec_b64 s[0:1], s[16:17]
	s_cbranch_execz .LBB0_837
	v_mul_f32_e32 v36, v36, v254
.LBB0_837:
	s_or_b64 exec, exec, s[0:1]
	ds_read_u16 v238, v18 offset:4624
	ds_read_b32 v239, v16 offset:68
	ds_read_b32 v254, v15 offset:68
	s_waitcnt lgkmcnt(6)
	v_mul_f32_dpp v37, v240, v2 quad_perm:[0,0,0,0] row_mask:0xf bank_mask:0xf
	v_mul_f32_dpp v38, v240, v3 quad_perm:[1,1,1,1] row_mask:0xf bank_mask:0xf
	v_mul_f32_dpp v39, v240, v4 quad_perm:[2,2,2,2] row_mask:0xf bank_mask:0xf
	v_mul_f32_dpp v40, v240, v5 quad_perm:[3,3,3,3] row_mask:0xf bank_mask:0xf
	s_waitcnt lgkmcnt(5)
	v_fmac_f32_dpp v37, v241, v6 quad_perm:[0,0,0,0] row_mask:0xf bank_mask:0xf
	v_fmac_f32_dpp v38, v241, v7 quad_perm:[1,1,1,1] row_mask:0xf bank_mask:0xf
	v_fmac_f32_dpp v39, v241, v8 quad_perm:[2,2,2,2] row_mask:0xf bank_mask:0xf
	v_fmac_f32_dpp v40, v241, v9 quad_perm:[3,3,3,3] row_mask:0xf bank_mask:0xf
	s_waitcnt lgkmcnt(4)
	v_fmac_f32_dpp v37, v242, v10 quad_perm:[0,0,0,0] row_mask:0xf bank_mask:0xf
	v_fmac_f32_dpp v38, v242, v12 quad_perm:[1,1,1,1] row_mask:0xf bank_mask:0xf
	v_fmac_f32_dpp v39, v242, v13 quad_perm:[2,2,2,2] row_mask:0xf bank_mask:0xf
	v_fmac_f32_dpp v40, v242, v14 quad_perm:[3,3,3,3] row_mask:0xf bank_mask:0xf
	s_waitcnt lgkmcnt(3)
	v_fmac_f32_dpp v37, v243, v17 quad_perm:[0,0,0,0] row_mask:0xf bank_mask:0xf
	v_fmac_f32_dpp v38, v243, v19 quad_perm:[1,1,1,1] row_mask:0xf bank_mask:0xf
	v_fmac_f32_dpp v39, v243, v28 quad_perm:[2,2,2,2] row_mask:0xf bank_mask:0xf
	v_fmac_f32_dpp v40, v243, v35 quad_perm:[3,3,3,3] row_mask:0xf bank_mask:0xf
	ds_read_b32 v240, v255 offset:4352
	ds_read_b32 v241, v255 offset:4368
	ds_read_b32 v242, v255 offset:4384
	ds_read_b32 v243, v255 offset:4400
	ds_read_b32 v244, v255 offset:4416
	v_add_f32_e32 v37, v37, v38
	v_add_f32_e32 v38, v39, v40
	v_add_f32_e32 v37, v37, v38
	v_sub_f32_e32 v36, v36, v37
	s_waitcnt lgkmcnt(5)
	v_lshlrev_b32_e32 v37, 16, v238
	v_mul_f32_e32 v37, v239, v37
	s_and_saveexec_b64 s[0:1], s[16:17]
	s_cbranch_execz .LBB0_839
	v_mul_f32_e32 v37, v37, v254
.LBB0_839:
	s_or_b64 exec, exec, s[0:1]
	ds_read_u16 v238, v18 offset:4896
	ds_read_b32 v239, v16 offset:72
	ds_read_b32 v254, v15 offset:72
	s_waitcnt lgkmcnt(7)
	v_mul_f32_dpp v54, v240, v2 quad_perm:[0,0,0,0] row_mask:0xf bank_mask:0xf
	v_mul_f32_dpp v55, v240, v3 quad_perm:[1,1,1,1] row_mask:0xf bank_mask:0xf
	v_mul_f32_dpp v56, v240, v4 quad_perm:[2,2,2,2] row_mask:0xf bank_mask:0xf
	v_mul_f32_dpp v57, v240, v5 quad_perm:[3,3,3,3] row_mask:0xf bank_mask:0xf
	s_waitcnt lgkmcnt(6)
	v_fmac_f32_dpp v54, v241, v6 quad_perm:[0,0,0,0] row_mask:0xf bank_mask:0xf
	v_fmac_f32_dpp v55, v241, v7 quad_perm:[1,1,1,1] row_mask:0xf bank_mask:0xf
	v_fmac_f32_dpp v56, v241, v8 quad_perm:[2,2,2,2] row_mask:0xf bank_mask:0xf
	v_fmac_f32_dpp v57, v241, v9 quad_perm:[3,3,3,3] row_mask:0xf bank_mask:0xf
	s_waitcnt lgkmcnt(5)
	v_fmac_f32_dpp v54, v242, v10 quad_perm:[0,0,0,0] row_mask:0xf bank_mask:0xf
	v_fmac_f32_dpp v55, v242, v12 quad_perm:[1,1,1,1] row_mask:0xf bank_mask:0xf
	v_fmac_f32_dpp v56, v242, v13 quad_perm:[2,2,2,2] row_mask:0xf bank_mask:0xf
	v_fmac_f32_dpp v57, v242, v14 quad_perm:[3,3,3,3] row_mask:0xf bank_mask:0xf
	s_waitcnt lgkmcnt(4)
	v_fmac_f32_dpp v54, v243, v17 quad_perm:[0,0,0,0] row_mask:0xf bank_mask:0xf
	v_fmac_f32_dpp v55, v243, v19 quad_perm:[1,1,1,1] row_mask:0xf bank_mask:0xf
	v_fmac_f32_dpp v56, v243, v28 quad_perm:[2,2,2,2] row_mask:0xf bank_mask:0xf
	v_fmac_f32_dpp v57, v243, v35 quad_perm:[3,3,3,3] row_mask:0xf bank_mask:0xf
	s_waitcnt lgkmcnt(3)
	v_fmac_f32_dpp v54, v244, v36 quad_perm:[0,0,0,0] row_mask:0xf bank_mask:0xf
	ds_read_b32 v240, v255 offset:4608
	ds_read_b32 v241, v255 offset:4624
	ds_read_b32 v242, v255 offset:4640
	ds_read_b32 v243, v255 offset:4656
	ds_read_b32 v244, v255 offset:4672
	v_add_f32_e32 v38, v55, v54
	v_add_f32_e32 v39, v56, v57
	v_add_f32_e32 v38, v39, v38
	v_sub_f32_e32 v37, v37, v38
	s_waitcnt lgkmcnt(5)
	v_lshlrev_b32_e32 v38, 16, v238
	v_mul_f32_e32 v38, v239, v38
	s_and_saveexec_b64 s[0:1], s[16:17]
	s_cbranch_execz .LBB0_841
	v_mul_f32_e32 v38, v38, v254
.LBB0_841:
	s_or_b64 exec, exec, s[0:1]
	ds_read_u16 v238, v18 offset:5168
	ds_read_b32 v239, v16 offset:76
	ds_read_b32 v254, v15 offset:76
	s_waitcnt lgkmcnt(7)
	v_mul_f32_dpp v39, v240, v2 quad_perm:[0,0,0,0] row_mask:0xf bank_mask:0xf
	v_mul_f32_dpp v56, v240, v3 quad_perm:[1,1,1,1] row_mask:0xf bank_mask:0xf
	v_mul_f32_dpp v57, v240, v4 quad_perm:[2,2,2,2] row_mask:0xf bank_mask:0xf
	v_mul_f32_dpp v58, v240, v5 quad_perm:[3,3,3,3] row_mask:0xf bank_mask:0xf
	s_waitcnt lgkmcnt(6)
	v_fmac_f32_dpp v39, v241, v6 quad_perm:[0,0,0,0] row_mask:0xf bank_mask:0xf
	v_fmac_f32_dpp v56, v241, v7 quad_perm:[1,1,1,1] row_mask:0xf bank_mask:0xf
	v_fmac_f32_dpp v57, v241, v8 quad_perm:[2,2,2,2] row_mask:0xf bank_mask:0xf
	v_fmac_f32_dpp v58, v241, v9 quad_perm:[3,3,3,3] row_mask:0xf bank_mask:0xf
	s_waitcnt lgkmcnt(5)
	v_fmac_f32_dpp v39, v242, v10 quad_perm:[0,0,0,0] row_mask:0xf bank_mask:0xf
	v_fmac_f32_dpp v56, v242, v12 quad_perm:[1,1,1,1] row_mask:0xf bank_mask:0xf
	v_fmac_f32_dpp v57, v242, v13 quad_perm:[2,2,2,2] row_mask:0xf bank_mask:0xf
	v_fmac_f32_dpp v58, v242, v14 quad_perm:[3,3,3,3] row_mask:0xf bank_mask:0xf
	s_waitcnt lgkmcnt(4)
	v_fmac_f32_dpp v39, v243, v17 quad_perm:[0,0,0,0] row_mask:0xf bank_mask:0xf
	v_fmac_f32_dpp v56, v243, v19 quad_perm:[1,1,1,1] row_mask:0xf bank_mask:0xf
	v_fmac_f32_dpp v57, v243, v28 quad_perm:[2,2,2,2] row_mask:0xf bank_mask:0xf
	v_fmac_f32_dpp v58, v243, v35 quad_perm:[3,3,3,3] row_mask:0xf bank_mask:0xf
	s_waitcnt lgkmcnt(3)
	v_fmac_f32_dpp v39, v244, v36 quad_perm:[0,0,0,0] row_mask:0xf bank_mask:0xf
	v_fmac_f32_dpp v56, v244, v37 quad_perm:[1,1,1,1] row_mask:0xf bank_mask:0xf
	ds_read_b32 v240, v255 offset:4864
	ds_read_b32 v241, v255 offset:4880
	ds_read_b32 v242, v255 offset:4896
	ds_read_b32 v243, v255 offset:4912
	ds_read_b32 v244, v255 offset:4928
	v_add_f32_e32 v39, v39, v56
	v_add_f32_e32 v40, v57, v58
	v_add_f32_e32 v39, v40, v39
	v_sub_f32_e32 v38, v38, v39
	s_waitcnt lgkmcnt(5)
	v_lshlrev_b32_e32 v39, 16, v238
	v_mul_f32_e32 v39, v239, v39
	s_and_saveexec_b64 s[0:1], s[16:17]
	s_cbranch_execz .LBB0_843
	v_mul_f32_e32 v39, v39, v254
.LBB0_843:
	s_or_b64 exec, exec, s[0:1]
	ds_read_u16 v238, v18 offset:5440
	ds_read_b32 v239, v16 offset:80
	ds_read_b32 v254, v15 offset:80
	s_waitcnt lgkmcnt(7)
	v_mul_f32_dpp v56, v240, v2 quad_perm:[0,0,0,0] row_mask:0xf bank_mask:0xf
	v_mul_f32_dpp v57, v240, v3 quad_perm:[1,1,1,1] row_mask:0xf bank_mask:0xf
	v_mul_f32_dpp v58, v240, v4 quad_perm:[2,2,2,2] row_mask:0xf bank_mask:0xf
	v_mul_f32_dpp v59, v240, v5 quad_perm:[3,3,3,3] row_mask:0xf bank_mask:0xf
	s_waitcnt lgkmcnt(6)
	v_fmac_f32_dpp v56, v241, v6 quad_perm:[0,0,0,0] row_mask:0xf bank_mask:0xf
	v_fmac_f32_dpp v57, v241, v7 quad_perm:[1,1,1,1] row_mask:0xf bank_mask:0xf
	v_fmac_f32_dpp v58, v241, v8 quad_perm:[2,2,2,2] row_mask:0xf bank_mask:0xf
	v_fmac_f32_dpp v59, v241, v9 quad_perm:[3,3,3,3] row_mask:0xf bank_mask:0xf
	s_waitcnt lgkmcnt(5)
	v_fmac_f32_dpp v56, v242, v10 quad_perm:[0,0,0,0] row_mask:0xf bank_mask:0xf
	v_fmac_f32_dpp v57, v242, v12 quad_perm:[1,1,1,1] row_mask:0xf bank_mask:0xf
	v_fmac_f32_dpp v58, v242, v13 quad_perm:[2,2,2,2] row_mask:0xf bank_mask:0xf
	v_fmac_f32_dpp v59, v242, v14 quad_perm:[3,3,3,3] row_mask:0xf bank_mask:0xf
	s_waitcnt lgkmcnt(4)
	v_fmac_f32_dpp v56, v243, v17 quad_perm:[0,0,0,0] row_mask:0xf bank_mask:0xf
	v_fmac_f32_dpp v57, v243, v19 quad_perm:[1,1,1,1] row_mask:0xf bank_mask:0xf
	v_fmac_f32_dpp v58, v243, v28 quad_perm:[2,2,2,2] row_mask:0xf bank_mask:0xf
	v_fmac_f32_dpp v59, v243, v35 quad_perm:[3,3,3,3] row_mask:0xf bank_mask:0xf
	s_waitcnt lgkmcnt(3)
	v_fmac_f32_dpp v56, v244, v36 quad_perm:[0,0,0,0] row_mask:0xf bank_mask:0xf
	v_fmac_f32_dpp v57, v244, v37 quad_perm:[1,1,1,1] row_mask:0xf bank_mask:0xf
	v_fmac_f32_dpp v58, v244, v38 quad_perm:[2,2,2,2] row_mask:0xf bank_mask:0xf
	ds_read_b32 v240, v255 offset:5120
	ds_read_b32 v241, v255 offset:5136
	ds_read_b32 v242, v255 offset:5152
	ds_read_b32 v243, v255 offset:5168
	ds_read_b32 v244, v255 offset:5184
	v_add_f32_e32 v40, v56, v57
	v_add_f32_e32 v41, v59, v58
	v_add_f32_e32 v40, v40, v41
	v_sub_f32_e32 v39, v39, v40
	s_waitcnt lgkmcnt(5)
	v_lshlrev_b32_e32 v40, 16, v238
	v_mul_f32_e32 v40, v239, v40
	s_and_saveexec_b64 s[0:1], s[16:17]
	s_cbranch_execz .LBB0_845
	v_mul_f32_e32 v40, v40, v254
.LBB0_845:
	s_or_b64 exec, exec, s[0:1]
	ds_read_u16 v238, v18 offset:5712
	ds_read_b32 v239, v16 offset:84
	ds_read_b32 v254, v15 offset:84
	s_waitcnt lgkmcnt(7)
	v_mul_f32_dpp v41, v240, v2 quad_perm:[0,0,0,0] row_mask:0xf bank_mask:0xf
	v_mul_f32_dpp v58, v240, v3 quad_perm:[1,1,1,1] row_mask:0xf bank_mask:0xf
	v_mul_f32_dpp v59, v240, v4 quad_perm:[2,2,2,2] row_mask:0xf bank_mask:0xf
	v_mul_f32_dpp v60, v240, v5 quad_perm:[3,3,3,3] row_mask:0xf bank_mask:0xf
	s_waitcnt lgkmcnt(6)
	v_fmac_f32_dpp v41, v241, v6 quad_perm:[0,0,0,0] row_mask:0xf bank_mask:0xf
	v_fmac_f32_dpp v58, v241, v7 quad_perm:[1,1,1,1] row_mask:0xf bank_mask:0xf
	v_fmac_f32_dpp v59, v241, v8 quad_perm:[2,2,2,2] row_mask:0xf bank_mask:0xf
	v_fmac_f32_dpp v60, v241, v9 quad_perm:[3,3,3,3] row_mask:0xf bank_mask:0xf
	s_waitcnt lgkmcnt(5)
	v_fmac_f32_dpp v41, v242, v10 quad_perm:[0,0,0,0] row_mask:0xf bank_mask:0xf
	v_fmac_f32_dpp v58, v242, v12 quad_perm:[1,1,1,1] row_mask:0xf bank_mask:0xf
	v_fmac_f32_dpp v59, v242, v13 quad_perm:[2,2,2,2] row_mask:0xf bank_mask:0xf
	v_fmac_f32_dpp v60, v242, v14 quad_perm:[3,3,3,3] row_mask:0xf bank_mask:0xf
	s_waitcnt lgkmcnt(4)
	v_fmac_f32_dpp v41, v243, v17 quad_perm:[0,0,0,0] row_mask:0xf bank_mask:0xf
	v_fmac_f32_dpp v58, v243, v19 quad_perm:[1,1,1,1] row_mask:0xf bank_mask:0xf
	v_fmac_f32_dpp v59, v243, v28 quad_perm:[2,2,2,2] row_mask:0xf bank_mask:0xf
	v_fmac_f32_dpp v60, v243, v35 quad_perm:[3,3,3,3] row_mask:0xf bank_mask:0xf
	s_waitcnt lgkmcnt(3)
	v_fmac_f32_dpp v41, v244, v36 quad_perm:[0,0,0,0] row_mask:0xf bank_mask:0xf
	v_fmac_f32_dpp v58, v244, v37 quad_perm:[1,1,1,1] row_mask:0xf bank_mask:0xf
	v_fmac_f32_dpp v59, v244, v38 quad_perm:[2,2,2,2] row_mask:0xf bank_mask:0xf
	v_fmac_f32_dpp v60, v244, v39 quad_perm:[3,3,3,3] row_mask:0xf bank_mask:0xf
	ds_read_b32 v240, v255 offset:5376
	ds_read_b32 v241, v255 offset:5392
	ds_read_b32 v242, v255 offset:5408
	ds_read_b32 v243, v255 offset:5424
	ds_read_b32 v244, v255 offset:5440
	ds_read_b32 v245, v255 offset:5456
	v_add_f32_e32 v41, v41, v58
	v_add_f32_e32 v42, v59, v60
	v_add_f32_e32 v41, v41, v42
	v_sub_f32_e32 v40, v40, v41
	s_waitcnt lgkmcnt(6)
	v_lshlrev_b32_e32 v41, 16, v238
	v_mul_f32_e32 v41, v239, v41
	s_and_saveexec_b64 s[0:1], s[16:17]
	s_cbranch_execz .LBB0_847
	v_mul_f32_e32 v41, v41, v254
.LBB0_847:
	s_or_b64 exec, exec, s[0:1]
	ds_read_u16 v238, v18 offset:5984
	ds_read_b32 v239, v16 offset:88
	ds_read_b32 v254, v15 offset:88
	s_waitcnt lgkmcnt(8)
	v_mul_f32_dpp v58, v240, v2 quad_perm:[0,0,0,0] row_mask:0xf bank_mask:0xf
	v_mul_f32_dpp v59, v240, v3 quad_perm:[1,1,1,1] row_mask:0xf bank_mask:0xf
	v_mul_f32_dpp v60, v240, v4 quad_perm:[2,2,2,2] row_mask:0xf bank_mask:0xf
	v_mul_f32_dpp v61, v240, v5 quad_perm:[3,3,3,3] row_mask:0xf bank_mask:0xf
	s_waitcnt lgkmcnt(7)
	v_fmac_f32_dpp v58, v241, v6 quad_perm:[0,0,0,0] row_mask:0xf bank_mask:0xf
	v_fmac_f32_dpp v59, v241, v7 quad_perm:[1,1,1,1] row_mask:0xf bank_mask:0xf
	v_fmac_f32_dpp v60, v241, v8 quad_perm:[2,2,2,2] row_mask:0xf bank_mask:0xf
	v_fmac_f32_dpp v61, v241, v9 quad_perm:[3,3,3,3] row_mask:0xf bank_mask:0xf
	s_waitcnt lgkmcnt(6)
	v_fmac_f32_dpp v58, v242, v10 quad_perm:[0,0,0,0] row_mask:0xf bank_mask:0xf
	v_fmac_f32_dpp v59, v242, v12 quad_perm:[1,1,1,1] row_mask:0xf bank_mask:0xf
	v_fmac_f32_dpp v60, v242, v13 quad_perm:[2,2,2,2] row_mask:0xf bank_mask:0xf
	v_fmac_f32_dpp v61, v242, v14 quad_perm:[3,3,3,3] row_mask:0xf bank_mask:0xf
	s_waitcnt lgkmcnt(5)
	v_fmac_f32_dpp v58, v243, v17 quad_perm:[0,0,0,0] row_mask:0xf bank_mask:0xf
	v_fmac_f32_dpp v59, v243, v19 quad_perm:[1,1,1,1] row_mask:0xf bank_mask:0xf
	v_fmac_f32_dpp v60, v243, v28 quad_perm:[2,2,2,2] row_mask:0xf bank_mask:0xf
	v_fmac_f32_dpp v61, v243, v35 quad_perm:[3,3,3,3] row_mask:0xf bank_mask:0xf
	s_waitcnt lgkmcnt(4)
	v_fmac_f32_dpp v58, v244, v36 quad_perm:[0,0,0,0] row_mask:0xf bank_mask:0xf
	v_fmac_f32_dpp v59, v244, v37 quad_perm:[1,1,1,1] row_mask:0xf bank_mask:0xf
	v_fmac_f32_dpp v60, v244, v38 quad_perm:[2,2,2,2] row_mask:0xf bank_mask:0xf
	v_fmac_f32_dpp v61, v244, v39 quad_perm:[3,3,3,3] row_mask:0xf bank_mask:0xf
	s_waitcnt lgkmcnt(3)
	v_fmac_f32_dpp v58, v245, v40 quad_perm:[0,0,0,0] row_mask:0xf bank_mask:0xf
	ds_read_b32 v240, v255 offset:5632
	ds_read_b32 v241, v255 offset:5648
	ds_read_b32 v242, v255 offset:5664
	ds_read_b32 v243, v255 offset:5680
	ds_read_b32 v244, v255 offset:5696
	ds_read_b32 v245, v255 offset:5712
	v_add_f32_e32 v42, v59, v58
	v_add_f32_e32 v43, v60, v61
	v_add_f32_e32 v42, v43, v42
	v_sub_f32_e32 v41, v41, v42
	s_waitcnt lgkmcnt(6)
	v_lshlrev_b32_e32 v42, 16, v238
	v_mul_f32_e32 v42, v239, v42
	s_and_saveexec_b64 s[0:1], s[16:17]
	s_cbranch_execz .LBB0_849
	v_mul_f32_e32 v42, v42, v254
.LBB0_849:
	s_or_b64 exec, exec, s[0:1]
	ds_read_u16 v238, v18 offset:6256
	ds_read_b32 v239, v16 offset:92
	ds_read_b32 v254, v15 offset:92
	s_waitcnt lgkmcnt(8)
	v_mul_f32_dpp v43, v240, v2 quad_perm:[0,0,0,0] row_mask:0xf bank_mask:0xf
	v_mul_f32_dpp v60, v240, v3 quad_perm:[1,1,1,1] row_mask:0xf bank_mask:0xf
	v_mul_f32_dpp v61, v240, v4 quad_perm:[2,2,2,2] row_mask:0xf bank_mask:0xf
	v_mul_f32_dpp v62, v240, v5 quad_perm:[3,3,3,3] row_mask:0xf bank_mask:0xf
	s_waitcnt lgkmcnt(7)
	v_fmac_f32_dpp v43, v241, v6 quad_perm:[0,0,0,0] row_mask:0xf bank_mask:0xf
	v_fmac_f32_dpp v60, v241, v7 quad_perm:[1,1,1,1] row_mask:0xf bank_mask:0xf
	v_fmac_f32_dpp v61, v241, v8 quad_perm:[2,2,2,2] row_mask:0xf bank_mask:0xf
	v_fmac_f32_dpp v62, v241, v9 quad_perm:[3,3,3,3] row_mask:0xf bank_mask:0xf
	s_waitcnt lgkmcnt(6)
	v_fmac_f32_dpp v43, v242, v10 quad_perm:[0,0,0,0] row_mask:0xf bank_mask:0xf
	v_fmac_f32_dpp v60, v242, v12 quad_perm:[1,1,1,1] row_mask:0xf bank_mask:0xf
	v_fmac_f32_dpp v61, v242, v13 quad_perm:[2,2,2,2] row_mask:0xf bank_mask:0xf
	v_fmac_f32_dpp v62, v242, v14 quad_perm:[3,3,3,3] row_mask:0xf bank_mask:0xf
	s_waitcnt lgkmcnt(5)
	v_fmac_f32_dpp v43, v243, v17 quad_perm:[0,0,0,0] row_mask:0xf bank_mask:0xf
	v_fmac_f32_dpp v60, v243, v19 quad_perm:[1,1,1,1] row_mask:0xf bank_mask:0xf
	v_fmac_f32_dpp v61, v243, v28 quad_perm:[2,2,2,2] row_mask:0xf bank_mask:0xf
	v_fmac_f32_dpp v62, v243, v35 quad_perm:[3,3,3,3] row_mask:0xf bank_mask:0xf
	s_waitcnt lgkmcnt(4)
	v_fmac_f32_dpp v43, v244, v36 quad_perm:[0,0,0,0] row_mask:0xf bank_mask:0xf
	v_fmac_f32_dpp v60, v244, v37 quad_perm:[1,1,1,1] row_mask:0xf bank_mask:0xf
	v_fmac_f32_dpp v61, v244, v38 quad_perm:[2,2,2,2] row_mask:0xf bank_mask:0xf
	v_fmac_f32_dpp v62, v244, v39 quad_perm:[3,3,3,3] row_mask:0xf bank_mask:0xf
	s_waitcnt lgkmcnt(3)
	v_fmac_f32_dpp v43, v245, v40 quad_perm:[0,0,0,0] row_mask:0xf bank_mask:0xf
	v_fmac_f32_dpp v60, v245, v41 quad_perm:[1,1,1,1] row_mask:0xf bank_mask:0xf
	ds_read_b32 v240, v255 offset:5888
	ds_read_b32 v241, v255 offset:5904
	ds_read_b32 v242, v255 offset:5920
	ds_read_b32 v243, v255 offset:5936
	ds_read_b32 v244, v255 offset:5952
	ds_read_b32 v245, v255 offset:5968
	v_add_f32_e32 v43, v43, v60
	v_add_f32_e32 v44, v61, v62
	v_add_f32_e32 v43, v44, v43
	v_sub_f32_e32 v42, v42, v43
	s_waitcnt lgkmcnt(6)
	v_lshlrev_b32_e32 v43, 16, v238
	v_mul_f32_e32 v43, v239, v43
	s_and_saveexec_b64 s[0:1], s[16:17]
	s_cbranch_execz .LBB0_851
	v_mul_f32_e32 v43, v43, v254
.LBB0_851:
	s_or_b64 exec, exec, s[0:1]
	ds_read_u16 v238, v18 offset:6528
	ds_read_b32 v239, v16 offset:96
	ds_read_b32 v254, v15 offset:96
	s_waitcnt lgkmcnt(8)
	v_mul_f32_dpp v60, v240, v2 quad_perm:[0,0,0,0] row_mask:0xf bank_mask:0xf
	v_mul_f32_dpp v61, v240, v3 quad_perm:[1,1,1,1] row_mask:0xf bank_mask:0xf
	v_mul_f32_dpp v62, v240, v4 quad_perm:[2,2,2,2] row_mask:0xf bank_mask:0xf
	v_mul_f32_dpp v63, v240, v5 quad_perm:[3,3,3,3] row_mask:0xf bank_mask:0xf
	s_waitcnt lgkmcnt(7)
	v_fmac_f32_dpp v60, v241, v6 quad_perm:[0,0,0,0] row_mask:0xf bank_mask:0xf
	v_fmac_f32_dpp v61, v241, v7 quad_perm:[1,1,1,1] row_mask:0xf bank_mask:0xf
	v_fmac_f32_dpp v62, v241, v8 quad_perm:[2,2,2,2] row_mask:0xf bank_mask:0xf
	v_fmac_f32_dpp v63, v241, v9 quad_perm:[3,3,3,3] row_mask:0xf bank_mask:0xf
	s_waitcnt lgkmcnt(6)
	v_fmac_f32_dpp v60, v242, v10 quad_perm:[0,0,0,0] row_mask:0xf bank_mask:0xf
	v_fmac_f32_dpp v61, v242, v12 quad_perm:[1,1,1,1] row_mask:0xf bank_mask:0xf
	v_fmac_f32_dpp v62, v242, v13 quad_perm:[2,2,2,2] row_mask:0xf bank_mask:0xf
	v_fmac_f32_dpp v63, v242, v14 quad_perm:[3,3,3,3] row_mask:0xf bank_mask:0xf
	s_waitcnt lgkmcnt(5)
	v_fmac_f32_dpp v60, v243, v17 quad_perm:[0,0,0,0] row_mask:0xf bank_mask:0xf
	v_fmac_f32_dpp v61, v243, v19 quad_perm:[1,1,1,1] row_mask:0xf bank_mask:0xf
	v_fmac_f32_dpp v62, v243, v28 quad_perm:[2,2,2,2] row_mask:0xf bank_mask:0xf
	v_fmac_f32_dpp v63, v243, v35 quad_perm:[3,3,3,3] row_mask:0xf bank_mask:0xf
	s_waitcnt lgkmcnt(4)
	v_fmac_f32_dpp v60, v244, v36 quad_perm:[0,0,0,0] row_mask:0xf bank_mask:0xf
	v_fmac_f32_dpp v61, v244, v37 quad_perm:[1,1,1,1] row_mask:0xf bank_mask:0xf
	v_fmac_f32_dpp v62, v244, v38 quad_perm:[2,2,2,2] row_mask:0xf bank_mask:0xf
	v_fmac_f32_dpp v63, v244, v39 quad_perm:[3,3,3,3] row_mask:0xf bank_mask:0xf
	s_waitcnt lgkmcnt(3)
	v_fmac_f32_dpp v60, v245, v40 quad_perm:[0,0,0,0] row_mask:0xf bank_mask:0xf
	v_fmac_f32_dpp v61, v245, v41 quad_perm:[1,1,1,1] row_mask:0xf bank_mask:0xf
	v_fmac_f32_dpp v62, v245, v42 quad_perm:[2,2,2,2] row_mask:0xf bank_mask:0xf
	ds_read_b32 v240, v255 offset:6144
	ds_read_b32 v241, v255 offset:6160
	ds_read_b32 v242, v255 offset:6176
	ds_read_b32 v243, v255 offset:6192
	ds_read_b32 v244, v255 offset:6208
	ds_read_b32 v245, v255 offset:6224
	v_add_f32_e32 v44, v60, v61
	v_add_f32_e32 v45, v63, v62
	v_add_f32_e32 v44, v44, v45
	v_sub_f32_e32 v43, v43, v44
	s_waitcnt lgkmcnt(6)
	v_lshlrev_b32_e32 v44, 16, v238
	v_mul_f32_e32 v44, v239, v44
	s_and_saveexec_b64 s[0:1], s[16:17]
	s_cbranch_execz .LBB0_853
	v_mul_f32_e32 v44, v44, v254
.LBB0_853:
	s_or_b64 exec, exec, s[0:1]
	ds_read_u16 v238, v18 offset:6800
	ds_read_b32 v239, v16 offset:100
	ds_read_b32 v254, v15 offset:100
	s_waitcnt lgkmcnt(8)
	v_mul_f32_dpp v45, v240, v2 quad_perm:[0,0,0,0] row_mask:0xf bank_mask:0xf
	v_mul_f32_dpp v62, v240, v3 quad_perm:[1,1,1,1] row_mask:0xf bank_mask:0xf
	v_mul_f32_dpp v63, v240, v4 quad_perm:[2,2,2,2] row_mask:0xf bank_mask:0xf
	v_mul_f32_dpp v64, v240, v5 quad_perm:[3,3,3,3] row_mask:0xf bank_mask:0xf
	s_waitcnt lgkmcnt(7)
	v_fmac_f32_dpp v45, v241, v6 quad_perm:[0,0,0,0] row_mask:0xf bank_mask:0xf
	v_fmac_f32_dpp v62, v241, v7 quad_perm:[1,1,1,1] row_mask:0xf bank_mask:0xf
	v_fmac_f32_dpp v63, v241, v8 quad_perm:[2,2,2,2] row_mask:0xf bank_mask:0xf
	v_fmac_f32_dpp v64, v241, v9 quad_perm:[3,3,3,3] row_mask:0xf bank_mask:0xf
	s_waitcnt lgkmcnt(6)
	v_fmac_f32_dpp v45, v242, v10 quad_perm:[0,0,0,0] row_mask:0xf bank_mask:0xf
	v_fmac_f32_dpp v62, v242, v12 quad_perm:[1,1,1,1] row_mask:0xf bank_mask:0xf
	v_fmac_f32_dpp v63, v242, v13 quad_perm:[2,2,2,2] row_mask:0xf bank_mask:0xf
	v_fmac_f32_dpp v64, v242, v14 quad_perm:[3,3,3,3] row_mask:0xf bank_mask:0xf
	s_waitcnt lgkmcnt(5)
	v_fmac_f32_dpp v45, v243, v17 quad_perm:[0,0,0,0] row_mask:0xf bank_mask:0xf
	v_fmac_f32_dpp v62, v243, v19 quad_perm:[1,1,1,1] row_mask:0xf bank_mask:0xf
	v_fmac_f32_dpp v63, v243, v28 quad_perm:[2,2,2,2] row_mask:0xf bank_mask:0xf
	v_fmac_f32_dpp v64, v243, v35 quad_perm:[3,3,3,3] row_mask:0xf bank_mask:0xf
	s_waitcnt lgkmcnt(4)
	v_fmac_f32_dpp v45, v244, v36 quad_perm:[0,0,0,0] row_mask:0xf bank_mask:0xf
	v_fmac_f32_dpp v62, v244, v37 quad_perm:[1,1,1,1] row_mask:0xf bank_mask:0xf
	v_fmac_f32_dpp v63, v244, v38 quad_perm:[2,2,2,2] row_mask:0xf bank_mask:0xf
	v_fmac_f32_dpp v64, v244, v39 quad_perm:[3,3,3,3] row_mask:0xf bank_mask:0xf
	s_waitcnt lgkmcnt(3)
	v_fmac_f32_dpp v45, v245, v40 quad_perm:[0,0,0,0] row_mask:0xf bank_mask:0xf
	v_fmac_f32_dpp v62, v245, v41 quad_perm:[1,1,1,1] row_mask:0xf bank_mask:0xf
	v_fmac_f32_dpp v63, v245, v42 quad_perm:[2,2,2,2] row_mask:0xf bank_mask:0xf
	v_fmac_f32_dpp v64, v245, v43 quad_perm:[3,3,3,3] row_mask:0xf bank_mask:0xf
	ds_read_b32 v240, v255 offset:6400
	ds_read_b32 v241, v255 offset:6416
	ds_read_b32 v242, v255 offset:6432
	ds_read_b32 v243, v255 offset:6448
	ds_read_b32 v244, v255 offset:6464
	ds_read_b32 v245, v255 offset:6480
	ds_read_b32 v246, v255 offset:6496
	v_add_f32_e32 v45, v45, v62
	v_add_f32_e32 v46, v63, v64
	v_add_f32_e32 v45, v45, v46
	v_sub_f32_e32 v44, v44, v45
	s_waitcnt lgkmcnt(7)
	v_lshlrev_b32_e32 v45, 16, v238
	v_mul_f32_e32 v45, v239, v45
	s_and_saveexec_b64 s[0:1], s[16:17]
	s_cbranch_execz .LBB0_855
	v_mul_f32_e32 v45, v45, v254
.LBB0_855:
	s_or_b64 exec, exec, s[0:1]
	ds_read_u16 v238, v18 offset:7072
	ds_read_b32 v239, v16 offset:104
	ds_read_b32 v254, v15 offset:104
	s_waitcnt lgkmcnt(9)
	v_mul_f32_dpp v62, v240, v2 quad_perm:[0,0,0,0] row_mask:0xf bank_mask:0xf
	v_mul_f32_dpp v63, v240, v3 quad_perm:[1,1,1,1] row_mask:0xf bank_mask:0xf
	v_mul_f32_dpp v64, v240, v4 quad_perm:[2,2,2,2] row_mask:0xf bank_mask:0xf
	v_mul_f32_dpp v65, v240, v5 quad_perm:[3,3,3,3] row_mask:0xf bank_mask:0xf
	s_waitcnt lgkmcnt(8)
	v_fmac_f32_dpp v62, v241, v6 quad_perm:[0,0,0,0] row_mask:0xf bank_mask:0xf
	v_fmac_f32_dpp v63, v241, v7 quad_perm:[1,1,1,1] row_mask:0xf bank_mask:0xf
	v_fmac_f32_dpp v64, v241, v8 quad_perm:[2,2,2,2] row_mask:0xf bank_mask:0xf
	v_fmac_f32_dpp v65, v241, v9 quad_perm:[3,3,3,3] row_mask:0xf bank_mask:0xf
	s_waitcnt lgkmcnt(7)
	v_fmac_f32_dpp v62, v242, v10 quad_perm:[0,0,0,0] row_mask:0xf bank_mask:0xf
	v_fmac_f32_dpp v63, v242, v12 quad_perm:[1,1,1,1] row_mask:0xf bank_mask:0xf
	v_fmac_f32_dpp v64, v242, v13 quad_perm:[2,2,2,2] row_mask:0xf bank_mask:0xf
	v_fmac_f32_dpp v65, v242, v14 quad_perm:[3,3,3,3] row_mask:0xf bank_mask:0xf
	s_waitcnt lgkmcnt(6)
	v_fmac_f32_dpp v62, v243, v17 quad_perm:[0,0,0,0] row_mask:0xf bank_mask:0xf
	v_fmac_f32_dpp v63, v243, v19 quad_perm:[1,1,1,1] row_mask:0xf bank_mask:0xf
	v_fmac_f32_dpp v64, v243, v28 quad_perm:[2,2,2,2] row_mask:0xf bank_mask:0xf
	v_fmac_f32_dpp v65, v243, v35 quad_perm:[3,3,3,3] row_mask:0xf bank_mask:0xf
	s_waitcnt lgkmcnt(5)
	v_fmac_f32_dpp v62, v244, v36 quad_perm:[0,0,0,0] row_mask:0xf bank_mask:0xf
	v_fmac_f32_dpp v63, v244, v37 quad_perm:[1,1,1,1] row_mask:0xf bank_mask:0xf
	v_fmac_f32_dpp v64, v244, v38 quad_perm:[2,2,2,2] row_mask:0xf bank_mask:0xf
	v_fmac_f32_dpp v65, v244, v39 quad_perm:[3,3,3,3] row_mask:0xf bank_mask:0xf
	s_waitcnt lgkmcnt(4)
	v_fmac_f32_dpp v62, v245, v40 quad_perm:[0,0,0,0] row_mask:0xf bank_mask:0xf
	v_fmac_f32_dpp v63, v245, v41 quad_perm:[1,1,1,1] row_mask:0xf bank_mask:0xf
	v_fmac_f32_dpp v64, v245, v42 quad_perm:[2,2,2,2] row_mask:0xf bank_mask:0xf
	v_fmac_f32_dpp v65, v245, v43 quad_perm:[3,3,3,3] row_mask:0xf bank_mask:0xf
	s_waitcnt lgkmcnt(3)
	v_fmac_f32_dpp v62, v246, v44 quad_perm:[0,0,0,0] row_mask:0xf bank_mask:0xf
	ds_read_b32 v240, v255 offset:6656
	ds_read_b32 v241, v255 offset:6672
	ds_read_b32 v242, v255 offset:6688
	ds_read_b32 v243, v255 offset:6704
	ds_read_b32 v244, v255 offset:6720
	ds_read_b32 v245, v255 offset:6736
	ds_read_b32 v246, v255 offset:6752
	v_add_f32_e32 v46, v63, v62
	v_add_f32_e32 v47, v64, v65
	v_add_f32_e32 v46, v47, v46
	v_sub_f32_e32 v45, v45, v46
	s_waitcnt lgkmcnt(7)
	v_lshlrev_b32_e32 v46, 16, v238
	v_mul_f32_e32 v46, v239, v46
	s_and_saveexec_b64 s[0:1], s[16:17]
	s_cbranch_execz .LBB0_857
	v_mul_f32_e32 v46, v46, v254
.LBB0_857:
	s_or_b64 exec, exec, s[0:1]
	ds_read_u16 v238, v18 offset:7344
	ds_read_b32 v239, v16 offset:108
	ds_read_b32 v254, v15 offset:108
	s_waitcnt lgkmcnt(9)
	v_mul_f32_dpp v47, v240, v2 quad_perm:[0,0,0,0] row_mask:0xf bank_mask:0xf
	v_mul_f32_dpp v64, v240, v3 quad_perm:[1,1,1,1] row_mask:0xf bank_mask:0xf
	v_mul_f32_dpp v65, v240, v4 quad_perm:[2,2,2,2] row_mask:0xf bank_mask:0xf
	v_mul_f32_dpp v66, v240, v5 quad_perm:[3,3,3,3] row_mask:0xf bank_mask:0xf
	s_waitcnt lgkmcnt(8)
	v_fmac_f32_dpp v47, v241, v6 quad_perm:[0,0,0,0] row_mask:0xf bank_mask:0xf
	v_fmac_f32_dpp v64, v241, v7 quad_perm:[1,1,1,1] row_mask:0xf bank_mask:0xf
	v_fmac_f32_dpp v65, v241, v8 quad_perm:[2,2,2,2] row_mask:0xf bank_mask:0xf
	v_fmac_f32_dpp v66, v241, v9 quad_perm:[3,3,3,3] row_mask:0xf bank_mask:0xf
	s_waitcnt lgkmcnt(7)
	v_fmac_f32_dpp v47, v242, v10 quad_perm:[0,0,0,0] row_mask:0xf bank_mask:0xf
	v_fmac_f32_dpp v64, v242, v12 quad_perm:[1,1,1,1] row_mask:0xf bank_mask:0xf
	v_fmac_f32_dpp v65, v242, v13 quad_perm:[2,2,2,2] row_mask:0xf bank_mask:0xf
	v_fmac_f32_dpp v66, v242, v14 quad_perm:[3,3,3,3] row_mask:0xf bank_mask:0xf
	s_waitcnt lgkmcnt(6)
	v_fmac_f32_dpp v47, v243, v17 quad_perm:[0,0,0,0] row_mask:0xf bank_mask:0xf
	v_fmac_f32_dpp v64, v243, v19 quad_perm:[1,1,1,1] row_mask:0xf bank_mask:0xf
	v_fmac_f32_dpp v65, v243, v28 quad_perm:[2,2,2,2] row_mask:0xf bank_mask:0xf
	v_fmac_f32_dpp v66, v243, v35 quad_perm:[3,3,3,3] row_mask:0xf bank_mask:0xf
	s_waitcnt lgkmcnt(5)
	v_fmac_f32_dpp v47, v244, v36 quad_perm:[0,0,0,0] row_mask:0xf bank_mask:0xf
	v_fmac_f32_dpp v64, v244, v37 quad_perm:[1,1,1,1] row_mask:0xf bank_mask:0xf
	v_fmac_f32_dpp v65, v244, v38 quad_perm:[2,2,2,2] row_mask:0xf bank_mask:0xf
	v_fmac_f32_dpp v66, v244, v39 quad_perm:[3,3,3,3] row_mask:0xf bank_mask:0xf
	s_waitcnt lgkmcnt(4)
	v_fmac_f32_dpp v47, v245, v40 quad_perm:[0,0,0,0] row_mask:0xf bank_mask:0xf
	v_fmac_f32_dpp v64, v245, v41 quad_perm:[1,1,1,1] row_mask:0xf bank_mask:0xf
	v_fmac_f32_dpp v65, v245, v42 quad_perm:[2,2,2,2] row_mask:0xf bank_mask:0xf
	v_fmac_f32_dpp v66, v245, v43 quad_perm:[3,3,3,3] row_mask:0xf bank_mask:0xf
	s_waitcnt lgkmcnt(3)
	v_fmac_f32_dpp v47, v246, v44 quad_perm:[0,0,0,0] row_mask:0xf bank_mask:0xf
	v_fmac_f32_dpp v64, v246, v45 quad_perm:[1,1,1,1] row_mask:0xf bank_mask:0xf
	ds_read_b32 v240, v255 offset:6912
	ds_read_b32 v241, v255 offset:6928
	ds_read_b32 v242, v255 offset:6944
	ds_read_b32 v243, v255 offset:6960
	ds_read_b32 v244, v255 offset:6976
	ds_read_b32 v245, v255 offset:6992
	ds_read_b32 v246, v255 offset:7008
	v_add_f32_e32 v47, v47, v64
	v_add_f32_e32 v48, v65, v66
	v_add_f32_e32 v47, v48, v47
	v_sub_f32_e32 v46, v46, v47
	s_waitcnt lgkmcnt(7)
	v_lshlrev_b32_e32 v47, 16, v238
	v_mul_f32_e32 v47, v239, v47
	s_and_saveexec_b64 s[0:1], s[16:17]
	s_cbranch_execz .LBB0_859
	v_mul_f32_e32 v47, v47, v254
.LBB0_859:
	s_or_b64 exec, exec, s[0:1]
	ds_read_u16 v238, v18 offset:7616
	ds_read_b32 v239, v16 offset:112
	ds_read_b32 v254, v15 offset:112
	s_waitcnt lgkmcnt(9)
	v_mul_f32_dpp v64, v240, v2 quad_perm:[0,0,0,0] row_mask:0xf bank_mask:0xf
	v_mul_f32_dpp v65, v240, v3 quad_perm:[1,1,1,1] row_mask:0xf bank_mask:0xf
	v_mul_f32_dpp v66, v240, v4 quad_perm:[2,2,2,2] row_mask:0xf bank_mask:0xf
	v_mul_f32_dpp v67, v240, v5 quad_perm:[3,3,3,3] row_mask:0xf bank_mask:0xf
	s_waitcnt lgkmcnt(8)
	v_fmac_f32_dpp v64, v241, v6 quad_perm:[0,0,0,0] row_mask:0xf bank_mask:0xf
	v_fmac_f32_dpp v65, v241, v7 quad_perm:[1,1,1,1] row_mask:0xf bank_mask:0xf
	v_fmac_f32_dpp v66, v241, v8 quad_perm:[2,2,2,2] row_mask:0xf bank_mask:0xf
	v_fmac_f32_dpp v67, v241, v9 quad_perm:[3,3,3,3] row_mask:0xf bank_mask:0xf
	s_waitcnt lgkmcnt(7)
	v_fmac_f32_dpp v64, v242, v10 quad_perm:[0,0,0,0] row_mask:0xf bank_mask:0xf
	v_fmac_f32_dpp v65, v242, v12 quad_perm:[1,1,1,1] row_mask:0xf bank_mask:0xf
	v_fmac_f32_dpp v66, v242, v13 quad_perm:[2,2,2,2] row_mask:0xf bank_mask:0xf
	v_fmac_f32_dpp v67, v242, v14 quad_perm:[3,3,3,3] row_mask:0xf bank_mask:0xf
	s_waitcnt lgkmcnt(6)
	v_fmac_f32_dpp v64, v243, v17 quad_perm:[0,0,0,0] row_mask:0xf bank_mask:0xf
	v_fmac_f32_dpp v65, v243, v19 quad_perm:[1,1,1,1] row_mask:0xf bank_mask:0xf
	v_fmac_f32_dpp v66, v243, v28 quad_perm:[2,2,2,2] row_mask:0xf bank_mask:0xf
	v_fmac_f32_dpp v67, v243, v35 quad_perm:[3,3,3,3] row_mask:0xf bank_mask:0xf
	s_waitcnt lgkmcnt(5)
	v_fmac_f32_dpp v64, v244, v36 quad_perm:[0,0,0,0] row_mask:0xf bank_mask:0xf
	v_fmac_f32_dpp v65, v244, v37 quad_perm:[1,1,1,1] row_mask:0xf bank_mask:0xf
	v_fmac_f32_dpp v66, v244, v38 quad_perm:[2,2,2,2] row_mask:0xf bank_mask:0xf
	v_fmac_f32_dpp v67, v244, v39 quad_perm:[3,3,3,3] row_mask:0xf bank_mask:0xf
	s_waitcnt lgkmcnt(4)
	v_fmac_f32_dpp v64, v245, v40 quad_perm:[0,0,0,0] row_mask:0xf bank_mask:0xf
	v_fmac_f32_dpp v65, v245, v41 quad_perm:[1,1,1,1] row_mask:0xf bank_mask:0xf
	v_fmac_f32_dpp v66, v245, v42 quad_perm:[2,2,2,2] row_mask:0xf bank_mask:0xf
	v_fmac_f32_dpp v67, v245, v43 quad_perm:[3,3,3,3] row_mask:0xf bank_mask:0xf
	s_waitcnt lgkmcnt(3)
	v_fmac_f32_dpp v64, v246, v44 quad_perm:[0,0,0,0] row_mask:0xf bank_mask:0xf
	v_fmac_f32_dpp v65, v246, v45 quad_perm:[1,1,1,1] row_mask:0xf bank_mask:0xf
	v_fmac_f32_dpp v66, v246, v46 quad_perm:[2,2,2,2] row_mask:0xf bank_mask:0xf
	ds_read_b32 v240, v255 offset:7168
	ds_read_b32 v241, v255 offset:7184
	ds_read_b32 v242, v255 offset:7200
	ds_read_b32 v243, v255 offset:7216
	ds_read_b32 v244, v255 offset:7232
	ds_read_b32 v245, v255 offset:7248
	ds_read_b32 v246, v255 offset:7264
	v_add_f32_e32 v48, v64, v65
	v_add_f32_e32 v49, v67, v66
	v_add_f32_e32 v48, v48, v49
	v_sub_f32_e32 v47, v47, v48
	s_waitcnt lgkmcnt(7)
	v_lshlrev_b32_e32 v48, 16, v238
	v_mul_f32_e32 v48, v239, v48
	s_and_saveexec_b64 s[0:1], s[16:17]
	s_cbranch_execz .LBB0_861
	v_mul_f32_e32 v48, v48, v254
.LBB0_861:
	s_or_b64 exec, exec, s[0:1]
	ds_read_u16 v238, v18 offset:7888
	ds_read_b32 v239, v16 offset:116
	ds_read_b32 v254, v15 offset:116
	s_waitcnt lgkmcnt(9)
	v_mul_f32_dpp v49, v240, v2 quad_perm:[0,0,0,0] row_mask:0xf bank_mask:0xf
	v_mul_f32_dpp v66, v240, v3 quad_perm:[1,1,1,1] row_mask:0xf bank_mask:0xf
	v_mul_f32_dpp v67, v240, v4 quad_perm:[2,2,2,2] row_mask:0xf bank_mask:0xf
	v_mul_f32_dpp v68, v240, v5 quad_perm:[3,3,3,3] row_mask:0xf bank_mask:0xf
	s_waitcnt lgkmcnt(8)
	v_fmac_f32_dpp v49, v241, v6 quad_perm:[0,0,0,0] row_mask:0xf bank_mask:0xf
	v_fmac_f32_dpp v66, v241, v7 quad_perm:[1,1,1,1] row_mask:0xf bank_mask:0xf
	v_fmac_f32_dpp v67, v241, v8 quad_perm:[2,2,2,2] row_mask:0xf bank_mask:0xf
	v_fmac_f32_dpp v68, v241, v9 quad_perm:[3,3,3,3] row_mask:0xf bank_mask:0xf
	s_waitcnt lgkmcnt(7)
	v_fmac_f32_dpp v49, v242, v10 quad_perm:[0,0,0,0] row_mask:0xf bank_mask:0xf
	v_fmac_f32_dpp v66, v242, v12 quad_perm:[1,1,1,1] row_mask:0xf bank_mask:0xf
	v_fmac_f32_dpp v67, v242, v13 quad_perm:[2,2,2,2] row_mask:0xf bank_mask:0xf
	v_fmac_f32_dpp v68, v242, v14 quad_perm:[3,3,3,3] row_mask:0xf bank_mask:0xf
	s_waitcnt lgkmcnt(6)
	v_fmac_f32_dpp v49, v243, v17 quad_perm:[0,0,0,0] row_mask:0xf bank_mask:0xf
	v_fmac_f32_dpp v66, v243, v19 quad_perm:[1,1,1,1] row_mask:0xf bank_mask:0xf
	v_fmac_f32_dpp v67, v243, v28 quad_perm:[2,2,2,2] row_mask:0xf bank_mask:0xf
	v_fmac_f32_dpp v68, v243, v35 quad_perm:[3,3,3,3] row_mask:0xf bank_mask:0xf
	s_waitcnt lgkmcnt(5)
	v_fmac_f32_dpp v49, v244, v36 quad_perm:[0,0,0,0] row_mask:0xf bank_mask:0xf
	v_fmac_f32_dpp v66, v244, v37 quad_perm:[1,1,1,1] row_mask:0xf bank_mask:0xf
	v_fmac_f32_dpp v67, v244, v38 quad_perm:[2,2,2,2] row_mask:0xf bank_mask:0xf
	v_fmac_f32_dpp v68, v244, v39 quad_perm:[3,3,3,3] row_mask:0xf bank_mask:0xf
	s_waitcnt lgkmcnt(4)
	v_fmac_f32_dpp v49, v245, v40 quad_perm:[0,0,0,0] row_mask:0xf bank_mask:0xf
	v_fmac_f32_dpp v66, v245, v41 quad_perm:[1,1,1,1] row_mask:0xf bank_mask:0xf
	v_fmac_f32_dpp v67, v245, v42 quad_perm:[2,2,2,2] row_mask:0xf bank_mask:0xf
	v_fmac_f32_dpp v68, v245, v43 quad_perm:[3,3,3,3] row_mask:0xf bank_mask:0xf
	s_waitcnt lgkmcnt(3)
	v_fmac_f32_dpp v49, v246, v44 quad_perm:[0,0,0,0] row_mask:0xf bank_mask:0xf
	v_fmac_f32_dpp v66, v246, v45 quad_perm:[1,1,1,1] row_mask:0xf bank_mask:0xf
	v_fmac_f32_dpp v67, v246, v46 quad_perm:[2,2,2,2] row_mask:0xf bank_mask:0xf
	v_fmac_f32_dpp v68, v246, v47 quad_perm:[3,3,3,3] row_mask:0xf bank_mask:0xf
	ds_read_b32 v240, v255 offset:7424
	ds_read_b32 v241, v255 offset:7440
	ds_read_b32 v242, v255 offset:7456
	ds_read_b32 v243, v255 offset:7472
	ds_read_b32 v244, v255 offset:7488
	ds_read_b32 v245, v255 offset:7504
	ds_read_b32 v246, v255 offset:7520
	ds_read_b32 v247, v255 offset:7536
	v_add_f32_e32 v49, v49, v66
	v_add_f32_e32 v50, v67, v68
	v_add_f32_e32 v49, v49, v50
	v_sub_f32_e32 v48, v48, v49
	s_waitcnt lgkmcnt(8)
	v_lshlrev_b32_e32 v49, 16, v238
	v_mul_f32_e32 v49, v239, v49
	s_and_saveexec_b64 s[0:1], s[16:17]
	s_cbranch_execz .LBB0_863
	v_mul_f32_e32 v49, v49, v254
.LBB0_863:
	s_or_b64 exec, exec, s[0:1]
	ds_read_u16 v238, v18 offset:8160
	ds_read_b32 v239, v16 offset:120
	ds_read_b32 v254, v15 offset:120
	s_waitcnt lgkmcnt(10)
	v_mul_f32_dpp v66, v240, v2 quad_perm:[0,0,0,0] row_mask:0xf bank_mask:0xf
	v_mul_f32_dpp v67, v240, v3 quad_perm:[1,1,1,1] row_mask:0xf bank_mask:0xf
	v_mul_f32_dpp v68, v240, v4 quad_perm:[2,2,2,2] row_mask:0xf bank_mask:0xf
	v_mul_f32_dpp v69, v240, v5 quad_perm:[3,3,3,3] row_mask:0xf bank_mask:0xf
	s_waitcnt lgkmcnt(9)
	v_fmac_f32_dpp v66, v241, v6 quad_perm:[0,0,0,0] row_mask:0xf bank_mask:0xf
	v_fmac_f32_dpp v67, v241, v7 quad_perm:[1,1,1,1] row_mask:0xf bank_mask:0xf
	v_fmac_f32_dpp v68, v241, v8 quad_perm:[2,2,2,2] row_mask:0xf bank_mask:0xf
	v_fmac_f32_dpp v69, v241, v9 quad_perm:[3,3,3,3] row_mask:0xf bank_mask:0xf
	s_waitcnt lgkmcnt(8)
	v_fmac_f32_dpp v66, v242, v10 quad_perm:[0,0,0,0] row_mask:0xf bank_mask:0xf
	v_fmac_f32_dpp v67, v242, v12 quad_perm:[1,1,1,1] row_mask:0xf bank_mask:0xf
	v_fmac_f32_dpp v68, v242, v13 quad_perm:[2,2,2,2] row_mask:0xf bank_mask:0xf
	v_fmac_f32_dpp v69, v242, v14 quad_perm:[3,3,3,3] row_mask:0xf bank_mask:0xf
	s_waitcnt lgkmcnt(7)
	v_fmac_f32_dpp v66, v243, v17 quad_perm:[0,0,0,0] row_mask:0xf bank_mask:0xf
	v_fmac_f32_dpp v67, v243, v19 quad_perm:[1,1,1,1] row_mask:0xf bank_mask:0xf
	v_fmac_f32_dpp v68, v243, v28 quad_perm:[2,2,2,2] row_mask:0xf bank_mask:0xf
	v_fmac_f32_dpp v69, v243, v35 quad_perm:[3,3,3,3] row_mask:0xf bank_mask:0xf
	s_waitcnt lgkmcnt(6)
	v_fmac_f32_dpp v66, v244, v36 quad_perm:[0,0,0,0] row_mask:0xf bank_mask:0xf
	v_fmac_f32_dpp v67, v244, v37 quad_perm:[1,1,1,1] row_mask:0xf bank_mask:0xf
	v_fmac_f32_dpp v68, v244, v38 quad_perm:[2,2,2,2] row_mask:0xf bank_mask:0xf
	v_fmac_f32_dpp v69, v244, v39 quad_perm:[3,3,3,3] row_mask:0xf bank_mask:0xf
	s_waitcnt lgkmcnt(5)
	v_fmac_f32_dpp v66, v245, v40 quad_perm:[0,0,0,0] row_mask:0xf bank_mask:0xf
	v_fmac_f32_dpp v67, v245, v41 quad_perm:[1,1,1,1] row_mask:0xf bank_mask:0xf
	v_fmac_f32_dpp v68, v245, v42 quad_perm:[2,2,2,2] row_mask:0xf bank_mask:0xf
	v_fmac_f32_dpp v69, v245, v43 quad_perm:[3,3,3,3] row_mask:0xf bank_mask:0xf
	s_waitcnt lgkmcnt(4)
	v_fmac_f32_dpp v66, v246, v44 quad_perm:[0,0,0,0] row_mask:0xf bank_mask:0xf
	v_fmac_f32_dpp v67, v246, v45 quad_perm:[1,1,1,1] row_mask:0xf bank_mask:0xf
	v_fmac_f32_dpp v68, v246, v46 quad_perm:[2,2,2,2] row_mask:0xf bank_mask:0xf
	v_fmac_f32_dpp v69, v246, v47 quad_perm:[3,3,3,3] row_mask:0xf bank_mask:0xf
	s_waitcnt lgkmcnt(3)
	v_fmac_f32_dpp v66, v247, v48 quad_perm:[0,0,0,0] row_mask:0xf bank_mask:0xf
	ds_read_b32 v240, v255 offset:7680
	ds_read_b32 v241, v255 offset:7696
	ds_read_b32 v242, v255 offset:7712
	ds_read_b32 v243, v255 offset:7728
	ds_read_b32 v244, v255 offset:7744
	ds_read_b32 v245, v255 offset:7760
	ds_read_b32 v246, v255 offset:7776
	ds_read_b32 v247, v255 offset:7792
	v_add_f32_e32 v50, v67, v66
	v_add_f32_e32 v51, v68, v69
	v_add_f32_e32 v50, v51, v50
	v_sub_f32_e32 v49, v49, v50
	s_waitcnt lgkmcnt(8)
	v_lshlrev_b32_e32 v50, 16, v238
	v_mul_f32_e32 v50, v239, v50
	s_and_saveexec_b64 s[0:1], s[16:17]
	s_cbranch_execz .LBB0_865
	v_mul_f32_e32 v50, v50, v254
.LBB0_865:
	s_or_b64 exec, exec, s[0:1]
	ds_read_u16 v238, v18 offset:8432
	ds_read_b32 v239, v16 offset:124
	ds_read_b32 v254, v15 offset:124
	s_waitcnt lgkmcnt(10)
	v_mul_f32_dpp v51, v240, v2 quad_perm:[0,0,0,0] row_mask:0xf bank_mask:0xf
	v_mul_f32_dpp v68, v240, v3 quad_perm:[1,1,1,1] row_mask:0xf bank_mask:0xf
	v_mul_f32_dpp v69, v240, v4 quad_perm:[2,2,2,2] row_mask:0xf bank_mask:0xf
	v_mul_f32_dpp v70, v240, v5 quad_perm:[3,3,3,3] row_mask:0xf bank_mask:0xf
	s_waitcnt lgkmcnt(9)
	v_fmac_f32_dpp v51, v241, v6 quad_perm:[0,0,0,0] row_mask:0xf bank_mask:0xf
	v_fmac_f32_dpp v68, v241, v7 quad_perm:[1,1,1,1] row_mask:0xf bank_mask:0xf
	v_fmac_f32_dpp v69, v241, v8 quad_perm:[2,2,2,2] row_mask:0xf bank_mask:0xf
	v_fmac_f32_dpp v70, v241, v9 quad_perm:[3,3,3,3] row_mask:0xf bank_mask:0xf
	s_waitcnt lgkmcnt(8)
	v_fmac_f32_dpp v51, v242, v10 quad_perm:[0,0,0,0] row_mask:0xf bank_mask:0xf
	v_fmac_f32_dpp v68, v242, v12 quad_perm:[1,1,1,1] row_mask:0xf bank_mask:0xf
	v_fmac_f32_dpp v69, v242, v13 quad_perm:[2,2,2,2] row_mask:0xf bank_mask:0xf
	v_fmac_f32_dpp v70, v242, v14 quad_perm:[3,3,3,3] row_mask:0xf bank_mask:0xf
	s_waitcnt lgkmcnt(7)
	v_fmac_f32_dpp v51, v243, v17 quad_perm:[0,0,0,0] row_mask:0xf bank_mask:0xf
	v_fmac_f32_dpp v68, v243, v19 quad_perm:[1,1,1,1] row_mask:0xf bank_mask:0xf
	v_fmac_f32_dpp v69, v243, v28 quad_perm:[2,2,2,2] row_mask:0xf bank_mask:0xf
	v_fmac_f32_dpp v70, v243, v35 quad_perm:[3,3,3,3] row_mask:0xf bank_mask:0xf
	s_waitcnt lgkmcnt(6)
	v_fmac_f32_dpp v51, v244, v36 quad_perm:[0,0,0,0] row_mask:0xf bank_mask:0xf
	v_fmac_f32_dpp v68, v244, v37 quad_perm:[1,1,1,1] row_mask:0xf bank_mask:0xf
	v_fmac_f32_dpp v69, v244, v38 quad_perm:[2,2,2,2] row_mask:0xf bank_mask:0xf
	v_fmac_f32_dpp v70, v244, v39 quad_perm:[3,3,3,3] row_mask:0xf bank_mask:0xf
	s_waitcnt lgkmcnt(5)
	v_fmac_f32_dpp v51, v245, v40 quad_perm:[0,0,0,0] row_mask:0xf bank_mask:0xf
	v_fmac_f32_dpp v68, v245, v41 quad_perm:[1,1,1,1] row_mask:0xf bank_mask:0xf
	v_fmac_f32_dpp v69, v245, v42 quad_perm:[2,2,2,2] row_mask:0xf bank_mask:0xf
	v_fmac_f32_dpp v70, v245, v43 quad_perm:[3,3,3,3] row_mask:0xf bank_mask:0xf
	s_waitcnt lgkmcnt(4)
	v_fmac_f32_dpp v51, v246, v44 quad_perm:[0,0,0,0] row_mask:0xf bank_mask:0xf
	v_fmac_f32_dpp v68, v246, v45 quad_perm:[1,1,1,1] row_mask:0xf bank_mask:0xf
	v_fmac_f32_dpp v69, v246, v46 quad_perm:[2,2,2,2] row_mask:0xf bank_mask:0xf
	v_fmac_f32_dpp v70, v246, v47 quad_perm:[3,3,3,3] row_mask:0xf bank_mask:0xf
	s_waitcnt lgkmcnt(3)
	v_fmac_f32_dpp v51, v247, v48 quad_perm:[0,0,0,0] row_mask:0xf bank_mask:0xf
	v_fmac_f32_dpp v68, v247, v49 quad_perm:[1,1,1,1] row_mask:0xf bank_mask:0xf
	ds_read_b32 v240, v255 offset:7936
	ds_read_b32 v241, v255 offset:7952
	ds_read_b32 v242, v255 offset:7968
	ds_read_b32 v243, v255 offset:7984
	ds_read_b32 v244, v255 offset:8000
	ds_read_b32 v245, v255 offset:8016
	ds_read_b32 v246, v255 offset:8032
	ds_read_b32 v247, v255 offset:8048
	v_add_f32_e32 v51, v51, v68
	v_add_f32_e32 v52, v69, v70
	v_add_f32_e32 v51, v52, v51
	v_sub_f32_e32 v50, v50, v51
	s_waitcnt lgkmcnt(8)
	v_lshlrev_b32_e32 v51, 16, v238
	v_mul_f32_e32 v51, v239, v51
	s_and_saveexec_b64 s[0:1], s[16:17]
	s_cbranch_execz .LBB0_867
	v_mul_f32_e32 v51, v51, v254
.LBB0_867:
	s_or_b64 exec, exec, s[0:1]
	ds_read_u16 v238, v18 offset:8704
	ds_read_b32 v239, v16 offset:128
	ds_read_b32 v254, v15 offset:128
	s_waitcnt lgkmcnt(10)
	v_mul_f32_dpp v68, v240, v2 quad_perm:[0,0,0,0] row_mask:0xf bank_mask:0xf
	v_mul_f32_dpp v69, v240, v3 quad_perm:[1,1,1,1] row_mask:0xf bank_mask:0xf
	v_mul_f32_dpp v70, v240, v4 quad_perm:[2,2,2,2] row_mask:0xf bank_mask:0xf
	v_mul_f32_dpp v71, v240, v5 quad_perm:[3,3,3,3] row_mask:0xf bank_mask:0xf
	s_waitcnt lgkmcnt(9)
	v_fmac_f32_dpp v68, v241, v6 quad_perm:[0,0,0,0] row_mask:0xf bank_mask:0xf
	v_fmac_f32_dpp v69, v241, v7 quad_perm:[1,1,1,1] row_mask:0xf bank_mask:0xf
	v_fmac_f32_dpp v70, v241, v8 quad_perm:[2,2,2,2] row_mask:0xf bank_mask:0xf
	v_fmac_f32_dpp v71, v241, v9 quad_perm:[3,3,3,3] row_mask:0xf bank_mask:0xf
	s_waitcnt lgkmcnt(8)
	v_fmac_f32_dpp v68, v242, v10 quad_perm:[0,0,0,0] row_mask:0xf bank_mask:0xf
	v_fmac_f32_dpp v69, v242, v12 quad_perm:[1,1,1,1] row_mask:0xf bank_mask:0xf
	v_fmac_f32_dpp v70, v242, v13 quad_perm:[2,2,2,2] row_mask:0xf bank_mask:0xf
	v_fmac_f32_dpp v71, v242, v14 quad_perm:[3,3,3,3] row_mask:0xf bank_mask:0xf
	s_waitcnt lgkmcnt(7)
	v_fmac_f32_dpp v68, v243, v17 quad_perm:[0,0,0,0] row_mask:0xf bank_mask:0xf
	v_fmac_f32_dpp v69, v243, v19 quad_perm:[1,1,1,1] row_mask:0xf bank_mask:0xf
	v_fmac_f32_dpp v70, v243, v28 quad_perm:[2,2,2,2] row_mask:0xf bank_mask:0xf
	v_fmac_f32_dpp v71, v243, v35 quad_perm:[3,3,3,3] row_mask:0xf bank_mask:0xf
	s_waitcnt lgkmcnt(6)
	v_fmac_f32_dpp v68, v244, v36 quad_perm:[0,0,0,0] row_mask:0xf bank_mask:0xf
	v_fmac_f32_dpp v69, v244, v37 quad_perm:[1,1,1,1] row_mask:0xf bank_mask:0xf
	v_fmac_f32_dpp v70, v244, v38 quad_perm:[2,2,2,2] row_mask:0xf bank_mask:0xf
	v_fmac_f32_dpp v71, v244, v39 quad_perm:[3,3,3,3] row_mask:0xf bank_mask:0xf
	s_waitcnt lgkmcnt(5)
	v_fmac_f32_dpp v68, v245, v40 quad_perm:[0,0,0,0] row_mask:0xf bank_mask:0xf
	v_fmac_f32_dpp v69, v245, v41 quad_perm:[1,1,1,1] row_mask:0xf bank_mask:0xf
	v_fmac_f32_dpp v70, v245, v42 quad_perm:[2,2,2,2] row_mask:0xf bank_mask:0xf
	v_fmac_f32_dpp v71, v245, v43 quad_perm:[3,3,3,3] row_mask:0xf bank_mask:0xf
	s_waitcnt lgkmcnt(4)
	v_fmac_f32_dpp v68, v246, v44 quad_perm:[0,0,0,0] row_mask:0xf bank_mask:0xf
	v_fmac_f32_dpp v69, v246, v45 quad_perm:[1,1,1,1] row_mask:0xf bank_mask:0xf
	v_fmac_f32_dpp v70, v246, v46 quad_perm:[2,2,2,2] row_mask:0xf bank_mask:0xf
	v_fmac_f32_dpp v71, v246, v47 quad_perm:[3,3,3,3] row_mask:0xf bank_mask:0xf
	s_waitcnt lgkmcnt(3)
	v_fmac_f32_dpp v68, v247, v48 quad_perm:[0,0,0,0] row_mask:0xf bank_mask:0xf
	v_fmac_f32_dpp v69, v247, v49 quad_perm:[1,1,1,1] row_mask:0xf bank_mask:0xf
	v_fmac_f32_dpp v70, v247, v50 quad_perm:[2,2,2,2] row_mask:0xf bank_mask:0xf
	ds_read_b32 v240, v255 offset:8192
	ds_read_b32 v241, v255 offset:8208
	ds_read_b32 v242, v255 offset:8224
	ds_read_b32 v243, v255 offset:8240
	ds_read_b32 v244, v255 offset:8256
	ds_read_b32 v245, v255 offset:8272
	ds_read_b32 v246, v255 offset:8288
	ds_read_b32 v247, v255 offset:8304
	v_add_f32_e32 v52, v68, v69
	v_add_f32_e32 v53, v71, v70
	v_add_f32_e32 v52, v52, v53
	v_sub_f32_e32 v51, v51, v52
	s_waitcnt lgkmcnt(8)
	v_lshlrev_b32_e32 v52, 16, v238
	v_mul_f32_e32 v52, v239, v52
	s_and_saveexec_b64 s[0:1], s[16:17]
	s_cbranch_execz .LBB0_869
	v_mul_f32_e32 v52, v52, v254
.LBB0_869:
	s_or_b64 exec, exec, s[0:1]
	ds_read_u16 v238, v18 offset:8976
	ds_read_b32 v239, v16 offset:132
	ds_read_b32 v254, v15 offset:132
	s_waitcnt lgkmcnt(10)
	v_mul_f32_dpp v53, v240, v2 quad_perm:[0,0,0,0] row_mask:0xf bank_mask:0xf
	v_mul_f32_dpp v70, v240, v3 quad_perm:[1,1,1,1] row_mask:0xf bank_mask:0xf
	v_mul_f32_dpp v71, v240, v4 quad_perm:[2,2,2,2] row_mask:0xf bank_mask:0xf
	v_mul_f32_dpp v72, v240, v5 quad_perm:[3,3,3,3] row_mask:0xf bank_mask:0xf
	s_waitcnt lgkmcnt(9)
	v_fmac_f32_dpp v53, v241, v6 quad_perm:[0,0,0,0] row_mask:0xf bank_mask:0xf
	v_fmac_f32_dpp v70, v241, v7 quad_perm:[1,1,1,1] row_mask:0xf bank_mask:0xf
	v_fmac_f32_dpp v71, v241, v8 quad_perm:[2,2,2,2] row_mask:0xf bank_mask:0xf
	v_fmac_f32_dpp v72, v241, v9 quad_perm:[3,3,3,3] row_mask:0xf bank_mask:0xf
	s_waitcnt lgkmcnt(8)
	v_fmac_f32_dpp v53, v242, v10 quad_perm:[0,0,0,0] row_mask:0xf bank_mask:0xf
	v_fmac_f32_dpp v70, v242, v12 quad_perm:[1,1,1,1] row_mask:0xf bank_mask:0xf
	v_fmac_f32_dpp v71, v242, v13 quad_perm:[2,2,2,2] row_mask:0xf bank_mask:0xf
	v_fmac_f32_dpp v72, v242, v14 quad_perm:[3,3,3,3] row_mask:0xf bank_mask:0xf
	s_waitcnt lgkmcnt(7)
	v_fmac_f32_dpp v53, v243, v17 quad_perm:[0,0,0,0] row_mask:0xf bank_mask:0xf
	v_fmac_f32_dpp v70, v243, v19 quad_perm:[1,1,1,1] row_mask:0xf bank_mask:0xf
	v_fmac_f32_dpp v71, v243, v28 quad_perm:[2,2,2,2] row_mask:0xf bank_mask:0xf
	v_fmac_f32_dpp v72, v243, v35 quad_perm:[3,3,3,3] row_mask:0xf bank_mask:0xf
	s_waitcnt lgkmcnt(6)
	v_fmac_f32_dpp v53, v244, v36 quad_perm:[0,0,0,0] row_mask:0xf bank_mask:0xf
	v_fmac_f32_dpp v70, v244, v37 quad_perm:[1,1,1,1] row_mask:0xf bank_mask:0xf
	v_fmac_f32_dpp v71, v244, v38 quad_perm:[2,2,2,2] row_mask:0xf bank_mask:0xf
	v_fmac_f32_dpp v72, v244, v39 quad_perm:[3,3,3,3] row_mask:0xf bank_mask:0xf
	s_waitcnt lgkmcnt(5)
	v_fmac_f32_dpp v53, v245, v40 quad_perm:[0,0,0,0] row_mask:0xf bank_mask:0xf
	v_fmac_f32_dpp v70, v245, v41 quad_perm:[1,1,1,1] row_mask:0xf bank_mask:0xf
	v_fmac_f32_dpp v71, v245, v42 quad_perm:[2,2,2,2] row_mask:0xf bank_mask:0xf
	v_fmac_f32_dpp v72, v245, v43 quad_perm:[3,3,3,3] row_mask:0xf bank_mask:0xf
	s_waitcnt lgkmcnt(4)
	v_fmac_f32_dpp v53, v246, v44 quad_perm:[0,0,0,0] row_mask:0xf bank_mask:0xf
	v_fmac_f32_dpp v70, v246, v45 quad_perm:[1,1,1,1] row_mask:0xf bank_mask:0xf
	v_fmac_f32_dpp v71, v246, v46 quad_perm:[2,2,2,2] row_mask:0xf bank_mask:0xf
	v_fmac_f32_dpp v72, v246, v47 quad_perm:[3,3,3,3] row_mask:0xf bank_mask:0xf
	s_waitcnt lgkmcnt(3)
	v_fmac_f32_dpp v53, v247, v48 quad_perm:[0,0,0,0] row_mask:0xf bank_mask:0xf
	v_fmac_f32_dpp v70, v247, v49 quad_perm:[1,1,1,1] row_mask:0xf bank_mask:0xf
	v_fmac_f32_dpp v71, v247, v50 quad_perm:[2,2,2,2] row_mask:0xf bank_mask:0xf
	v_fmac_f32_dpp v72, v247, v51 quad_perm:[3,3,3,3] row_mask:0xf bank_mask:0xf
	ds_read_b32 v240, v255 offset:8448
	ds_read_b32 v241, v255 offset:8464
	ds_read_b32 v242, v255 offset:8480
	ds_read_b32 v243, v255 offset:8496
	ds_read_b32 v244, v255 offset:8512
	ds_read_b32 v245, v255 offset:8528
	ds_read_b32 v246, v255 offset:8544
	ds_read_b32 v247, v255 offset:8560
	ds_read_b32 v248, v255 offset:8576
	v_add_f32_e32 v53, v53, v70
	v_add_f32_e32 v54, v71, v72
	v_add_f32_e32 v53, v53, v54
	v_sub_f32_e32 v52, v52, v53
	s_waitcnt lgkmcnt(9)
	v_lshlrev_b32_e32 v53, 16, v238
	v_mul_f32_e32 v53, v239, v53
	s_and_saveexec_b64 s[0:1], s[16:17]
	s_cbranch_execz .LBB0_871
	v_mul_f32_e32 v53, v53, v254
.LBB0_871:
	s_or_b64 exec, exec, s[0:1]
	ds_read_u16 v238, v18 offset:9248
	ds_read_b32 v239, v16 offset:136
	ds_read_b32 v254, v15 offset:136
	s_waitcnt lgkmcnt(11)
	v_mul_f32_dpp v70, v240, v2 quad_perm:[0,0,0,0] row_mask:0xf bank_mask:0xf
	v_mul_f32_dpp v71, v240, v3 quad_perm:[1,1,1,1] row_mask:0xf bank_mask:0xf
	v_mul_f32_dpp v72, v240, v4 quad_perm:[2,2,2,2] row_mask:0xf bank_mask:0xf
	v_mul_f32_dpp v73, v240, v5 quad_perm:[3,3,3,3] row_mask:0xf bank_mask:0xf
	s_waitcnt lgkmcnt(10)
	v_fmac_f32_dpp v70, v241, v6 quad_perm:[0,0,0,0] row_mask:0xf bank_mask:0xf
	v_fmac_f32_dpp v71, v241, v7 quad_perm:[1,1,1,1] row_mask:0xf bank_mask:0xf
	v_fmac_f32_dpp v72, v241, v8 quad_perm:[2,2,2,2] row_mask:0xf bank_mask:0xf
	v_fmac_f32_dpp v73, v241, v9 quad_perm:[3,3,3,3] row_mask:0xf bank_mask:0xf
	s_waitcnt lgkmcnt(9)
	v_fmac_f32_dpp v70, v242, v10 quad_perm:[0,0,0,0] row_mask:0xf bank_mask:0xf
	v_fmac_f32_dpp v71, v242, v12 quad_perm:[1,1,1,1] row_mask:0xf bank_mask:0xf
	v_fmac_f32_dpp v72, v242, v13 quad_perm:[2,2,2,2] row_mask:0xf bank_mask:0xf
	v_fmac_f32_dpp v73, v242, v14 quad_perm:[3,3,3,3] row_mask:0xf bank_mask:0xf
	s_waitcnt lgkmcnt(8)
	v_fmac_f32_dpp v70, v243, v17 quad_perm:[0,0,0,0] row_mask:0xf bank_mask:0xf
	v_fmac_f32_dpp v71, v243, v19 quad_perm:[1,1,1,1] row_mask:0xf bank_mask:0xf
	v_fmac_f32_dpp v72, v243, v28 quad_perm:[2,2,2,2] row_mask:0xf bank_mask:0xf
	v_fmac_f32_dpp v73, v243, v35 quad_perm:[3,3,3,3] row_mask:0xf bank_mask:0xf
	s_waitcnt lgkmcnt(7)
	v_fmac_f32_dpp v70, v244, v36 quad_perm:[0,0,0,0] row_mask:0xf bank_mask:0xf
	v_fmac_f32_dpp v71, v244, v37 quad_perm:[1,1,1,1] row_mask:0xf bank_mask:0xf
	v_fmac_f32_dpp v72, v244, v38 quad_perm:[2,2,2,2] row_mask:0xf bank_mask:0xf
	v_fmac_f32_dpp v73, v244, v39 quad_perm:[3,3,3,3] row_mask:0xf bank_mask:0xf
	s_waitcnt lgkmcnt(6)
	v_fmac_f32_dpp v70, v245, v40 quad_perm:[0,0,0,0] row_mask:0xf bank_mask:0xf
	v_fmac_f32_dpp v71, v245, v41 quad_perm:[1,1,1,1] row_mask:0xf bank_mask:0xf
	v_fmac_f32_dpp v72, v245, v42 quad_perm:[2,2,2,2] row_mask:0xf bank_mask:0xf
	v_fmac_f32_dpp v73, v245, v43 quad_perm:[3,3,3,3] row_mask:0xf bank_mask:0xf
	s_waitcnt lgkmcnt(5)
	v_fmac_f32_dpp v70, v246, v44 quad_perm:[0,0,0,0] row_mask:0xf bank_mask:0xf
	v_fmac_f32_dpp v71, v246, v45 quad_perm:[1,1,1,1] row_mask:0xf bank_mask:0xf
	v_fmac_f32_dpp v72, v246, v46 quad_perm:[2,2,2,2] row_mask:0xf bank_mask:0xf
	v_fmac_f32_dpp v73, v246, v47 quad_perm:[3,3,3,3] row_mask:0xf bank_mask:0xf
	s_waitcnt lgkmcnt(4)
	v_fmac_f32_dpp v70, v247, v48 quad_perm:[0,0,0,0] row_mask:0xf bank_mask:0xf
	v_fmac_f32_dpp v71, v247, v49 quad_perm:[1,1,1,1] row_mask:0xf bank_mask:0xf
	v_fmac_f32_dpp v72, v247, v50 quad_perm:[2,2,2,2] row_mask:0xf bank_mask:0xf
	v_fmac_f32_dpp v73, v247, v51 quad_perm:[3,3,3,3] row_mask:0xf bank_mask:0xf
	s_waitcnt lgkmcnt(3)
	v_fmac_f32_dpp v70, v248, v52 quad_perm:[0,0,0,0] row_mask:0xf bank_mask:0xf
	ds_read_b32 v240, v255 offset:8704
	ds_read_b32 v241, v255 offset:8720
	ds_read_b32 v242, v255 offset:8736
	ds_read_b32 v243, v255 offset:8752
	ds_read_b32 v244, v255 offset:8768
	ds_read_b32 v245, v255 offset:8784
	ds_read_b32 v246, v255 offset:8800
	ds_read_b32 v247, v255 offset:8816
	ds_read_b32 v248, v255 offset:8832
	v_add_f32_e32 v54, v71, v70
	v_add_f32_e32 v55, v72, v73
	v_add_f32_e32 v54, v55, v54
	v_sub_f32_e32 v53, v53, v54
	s_waitcnt lgkmcnt(9)
	v_lshlrev_b32_e32 v54, 16, v238
	v_mul_f32_e32 v54, v239, v54
	s_and_saveexec_b64 s[0:1], s[16:17]
	s_cbranch_execz .LBB0_873
	v_mul_f32_e32 v54, v54, v254
.LBB0_873:
	s_or_b64 exec, exec, s[0:1]
	ds_read_u16 v238, v18 offset:9520
	ds_read_b32 v239, v16 offset:140
	ds_read_b32 v254, v15 offset:140
	s_waitcnt lgkmcnt(11)
	v_mul_f32_dpp v55, v240, v2 quad_perm:[0,0,0,0] row_mask:0xf bank_mask:0xf
	v_mul_f32_dpp v72, v240, v3 quad_perm:[1,1,1,1] row_mask:0xf bank_mask:0xf
	v_mul_f32_dpp v73, v240, v4 quad_perm:[2,2,2,2] row_mask:0xf bank_mask:0xf
	v_mul_f32_dpp v74, v240, v5 quad_perm:[3,3,3,3] row_mask:0xf bank_mask:0xf
	s_waitcnt lgkmcnt(10)
	v_fmac_f32_dpp v55, v241, v6 quad_perm:[0,0,0,0] row_mask:0xf bank_mask:0xf
	v_fmac_f32_dpp v72, v241, v7 quad_perm:[1,1,1,1] row_mask:0xf bank_mask:0xf
	v_fmac_f32_dpp v73, v241, v8 quad_perm:[2,2,2,2] row_mask:0xf bank_mask:0xf
	v_fmac_f32_dpp v74, v241, v9 quad_perm:[3,3,3,3] row_mask:0xf bank_mask:0xf
	s_waitcnt lgkmcnt(9)
	v_fmac_f32_dpp v55, v242, v10 quad_perm:[0,0,0,0] row_mask:0xf bank_mask:0xf
	v_fmac_f32_dpp v72, v242, v12 quad_perm:[1,1,1,1] row_mask:0xf bank_mask:0xf
	v_fmac_f32_dpp v73, v242, v13 quad_perm:[2,2,2,2] row_mask:0xf bank_mask:0xf
	v_fmac_f32_dpp v74, v242, v14 quad_perm:[3,3,3,3] row_mask:0xf bank_mask:0xf
	s_waitcnt lgkmcnt(8)
	v_fmac_f32_dpp v55, v243, v17 quad_perm:[0,0,0,0] row_mask:0xf bank_mask:0xf
	v_fmac_f32_dpp v72, v243, v19 quad_perm:[1,1,1,1] row_mask:0xf bank_mask:0xf
	v_fmac_f32_dpp v73, v243, v28 quad_perm:[2,2,2,2] row_mask:0xf bank_mask:0xf
	v_fmac_f32_dpp v74, v243, v35 quad_perm:[3,3,3,3] row_mask:0xf bank_mask:0xf
	s_waitcnt lgkmcnt(7)
	v_fmac_f32_dpp v55, v244, v36 quad_perm:[0,0,0,0] row_mask:0xf bank_mask:0xf
	v_fmac_f32_dpp v72, v244, v37 quad_perm:[1,1,1,1] row_mask:0xf bank_mask:0xf
	v_fmac_f32_dpp v73, v244, v38 quad_perm:[2,2,2,2] row_mask:0xf bank_mask:0xf
	v_fmac_f32_dpp v74, v244, v39 quad_perm:[3,3,3,3] row_mask:0xf bank_mask:0xf
	s_waitcnt lgkmcnt(6)
	v_fmac_f32_dpp v55, v245, v40 quad_perm:[0,0,0,0] row_mask:0xf bank_mask:0xf
	v_fmac_f32_dpp v72, v245, v41 quad_perm:[1,1,1,1] row_mask:0xf bank_mask:0xf
	v_fmac_f32_dpp v73, v245, v42 quad_perm:[2,2,2,2] row_mask:0xf bank_mask:0xf
	v_fmac_f32_dpp v74, v245, v43 quad_perm:[3,3,3,3] row_mask:0xf bank_mask:0xf
	s_waitcnt lgkmcnt(5)
	v_fmac_f32_dpp v55, v246, v44 quad_perm:[0,0,0,0] row_mask:0xf bank_mask:0xf
	v_fmac_f32_dpp v72, v246, v45 quad_perm:[1,1,1,1] row_mask:0xf bank_mask:0xf
	v_fmac_f32_dpp v73, v246, v46 quad_perm:[2,2,2,2] row_mask:0xf bank_mask:0xf
	v_fmac_f32_dpp v74, v246, v47 quad_perm:[3,3,3,3] row_mask:0xf bank_mask:0xf
	s_waitcnt lgkmcnt(4)
	v_fmac_f32_dpp v55, v247, v48 quad_perm:[0,0,0,0] row_mask:0xf bank_mask:0xf
	v_fmac_f32_dpp v72, v247, v49 quad_perm:[1,1,1,1] row_mask:0xf bank_mask:0xf
	v_fmac_f32_dpp v73, v247, v50 quad_perm:[2,2,2,2] row_mask:0xf bank_mask:0xf
	v_fmac_f32_dpp v74, v247, v51 quad_perm:[3,3,3,3] row_mask:0xf bank_mask:0xf
	s_waitcnt lgkmcnt(3)
	v_fmac_f32_dpp v55, v248, v52 quad_perm:[0,0,0,0] row_mask:0xf bank_mask:0xf
	v_fmac_f32_dpp v72, v248, v53 quad_perm:[1,1,1,1] row_mask:0xf bank_mask:0xf
	ds_read_b32 v240, v255 offset:8960
	ds_read_b32 v241, v255 offset:8976
	ds_read_b32 v242, v255 offset:8992
	ds_read_b32 v243, v255 offset:9008
	ds_read_b32 v244, v255 offset:9024
	ds_read_b32 v245, v255 offset:9040
	ds_read_b32 v246, v255 offset:9056
	ds_read_b32 v247, v255 offset:9072
	ds_read_b32 v248, v255 offset:9088
	v_add_f32_e32 v55, v55, v72
	v_add_f32_e32 v56, v73, v74
	v_add_f32_e32 v55, v56, v55
	v_sub_f32_e32 v54, v54, v55
	s_waitcnt lgkmcnt(9)
	v_lshlrev_b32_e32 v55, 16, v238
	v_mul_f32_e32 v55, v239, v55
	s_and_saveexec_b64 s[0:1], s[16:17]
	s_cbranch_execz .LBB0_875
	v_mul_f32_e32 v55, v55, v254
.LBB0_875:
	s_or_b64 exec, exec, s[0:1]
	ds_read_u16 v238, v18 offset:9792
	ds_read_b32 v239, v16 offset:144
	ds_read_b32 v254, v15 offset:144
	s_waitcnt lgkmcnt(11)
	v_mul_f32_dpp v72, v240, v2 quad_perm:[0,0,0,0] row_mask:0xf bank_mask:0xf
	v_mul_f32_dpp v73, v240, v3 quad_perm:[1,1,1,1] row_mask:0xf bank_mask:0xf
	v_mul_f32_dpp v74, v240, v4 quad_perm:[2,2,2,2] row_mask:0xf bank_mask:0xf
	v_mul_f32_dpp v75, v240, v5 quad_perm:[3,3,3,3] row_mask:0xf bank_mask:0xf
	s_waitcnt lgkmcnt(10)
	v_fmac_f32_dpp v72, v241, v6 quad_perm:[0,0,0,0] row_mask:0xf bank_mask:0xf
	v_fmac_f32_dpp v73, v241, v7 quad_perm:[1,1,1,1] row_mask:0xf bank_mask:0xf
	v_fmac_f32_dpp v74, v241, v8 quad_perm:[2,2,2,2] row_mask:0xf bank_mask:0xf
	v_fmac_f32_dpp v75, v241, v9 quad_perm:[3,3,3,3] row_mask:0xf bank_mask:0xf
	s_waitcnt lgkmcnt(9)
	v_fmac_f32_dpp v72, v242, v10 quad_perm:[0,0,0,0] row_mask:0xf bank_mask:0xf
	v_fmac_f32_dpp v73, v242, v12 quad_perm:[1,1,1,1] row_mask:0xf bank_mask:0xf
	v_fmac_f32_dpp v74, v242, v13 quad_perm:[2,2,2,2] row_mask:0xf bank_mask:0xf
	v_fmac_f32_dpp v75, v242, v14 quad_perm:[3,3,3,3] row_mask:0xf bank_mask:0xf
	s_waitcnt lgkmcnt(8)
	v_fmac_f32_dpp v72, v243, v17 quad_perm:[0,0,0,0] row_mask:0xf bank_mask:0xf
	v_fmac_f32_dpp v73, v243, v19 quad_perm:[1,1,1,1] row_mask:0xf bank_mask:0xf
	v_fmac_f32_dpp v74, v243, v28 quad_perm:[2,2,2,2] row_mask:0xf bank_mask:0xf
	v_fmac_f32_dpp v75, v243, v35 quad_perm:[3,3,3,3] row_mask:0xf bank_mask:0xf
	s_waitcnt lgkmcnt(7)
	v_fmac_f32_dpp v72, v244, v36 quad_perm:[0,0,0,0] row_mask:0xf bank_mask:0xf
	v_fmac_f32_dpp v73, v244, v37 quad_perm:[1,1,1,1] row_mask:0xf bank_mask:0xf
	v_fmac_f32_dpp v74, v244, v38 quad_perm:[2,2,2,2] row_mask:0xf bank_mask:0xf
	v_fmac_f32_dpp v75, v244, v39 quad_perm:[3,3,3,3] row_mask:0xf bank_mask:0xf
	s_waitcnt lgkmcnt(6)
	v_fmac_f32_dpp v72, v245, v40 quad_perm:[0,0,0,0] row_mask:0xf bank_mask:0xf
	v_fmac_f32_dpp v73, v245, v41 quad_perm:[1,1,1,1] row_mask:0xf bank_mask:0xf
	v_fmac_f32_dpp v74, v245, v42 quad_perm:[2,2,2,2] row_mask:0xf bank_mask:0xf
	v_fmac_f32_dpp v75, v245, v43 quad_perm:[3,3,3,3] row_mask:0xf bank_mask:0xf
	s_waitcnt lgkmcnt(5)
	v_fmac_f32_dpp v72, v246, v44 quad_perm:[0,0,0,0] row_mask:0xf bank_mask:0xf
	v_fmac_f32_dpp v73, v246, v45 quad_perm:[1,1,1,1] row_mask:0xf bank_mask:0xf
	v_fmac_f32_dpp v74, v246, v46 quad_perm:[2,2,2,2] row_mask:0xf bank_mask:0xf
	v_fmac_f32_dpp v75, v246, v47 quad_perm:[3,3,3,3] row_mask:0xf bank_mask:0xf
	s_waitcnt lgkmcnt(4)
	v_fmac_f32_dpp v72, v247, v48 quad_perm:[0,0,0,0] row_mask:0xf bank_mask:0xf
	v_fmac_f32_dpp v73, v247, v49 quad_perm:[1,1,1,1] row_mask:0xf bank_mask:0xf
	v_fmac_f32_dpp v74, v247, v50 quad_perm:[2,2,2,2] row_mask:0xf bank_mask:0xf
	v_fmac_f32_dpp v75, v247, v51 quad_perm:[3,3,3,3] row_mask:0xf bank_mask:0xf
	s_waitcnt lgkmcnt(3)
	v_fmac_f32_dpp v72, v248, v52 quad_perm:[0,0,0,0] row_mask:0xf bank_mask:0xf
	v_fmac_f32_dpp v73, v248, v53 quad_perm:[1,1,1,1] row_mask:0xf bank_mask:0xf
	v_fmac_f32_dpp v74, v248, v54 quad_perm:[2,2,2,2] row_mask:0xf bank_mask:0xf
	ds_read_b32 v240, v255 offset:9216
	ds_read_b32 v241, v255 offset:9232
	ds_read_b32 v242, v255 offset:9248
	ds_read_b32 v243, v255 offset:9264
	ds_read_b32 v244, v255 offset:9280
	ds_read_b32 v245, v255 offset:9296
	ds_read_b32 v246, v255 offset:9312
	ds_read_b32 v247, v255 offset:9328
	ds_read_b32 v248, v255 offset:9344
	v_add_f32_e32 v56, v72, v73
	v_add_f32_e32 v57, v75, v74
	v_add_f32_e32 v56, v56, v57
	v_sub_f32_e32 v55, v55, v56
	s_waitcnt lgkmcnt(9)
	v_lshlrev_b32_e32 v56, 16, v238
	v_mul_f32_e32 v56, v239, v56
	s_and_saveexec_b64 s[0:1], s[16:17]
	s_cbranch_execz .LBB0_877
	v_mul_f32_e32 v56, v56, v254
.LBB0_877:
	s_or_b64 exec, exec, s[0:1]
	ds_read_u16 v238, v18 offset:10064
	ds_read_b32 v239, v16 offset:148
	ds_read_b32 v254, v15 offset:148
	s_waitcnt lgkmcnt(11)
	v_mul_f32_dpp v57, v240, v2 quad_perm:[0,0,0,0] row_mask:0xf bank_mask:0xf
	v_mul_f32_dpp v74, v240, v3 quad_perm:[1,1,1,1] row_mask:0xf bank_mask:0xf
	v_mul_f32_dpp v75, v240, v4 quad_perm:[2,2,2,2] row_mask:0xf bank_mask:0xf
	v_mul_f32_dpp v76, v240, v5 quad_perm:[3,3,3,3] row_mask:0xf bank_mask:0xf
	s_waitcnt lgkmcnt(10)
	v_fmac_f32_dpp v57, v241, v6 quad_perm:[0,0,0,0] row_mask:0xf bank_mask:0xf
	v_fmac_f32_dpp v74, v241, v7 quad_perm:[1,1,1,1] row_mask:0xf bank_mask:0xf
	v_fmac_f32_dpp v75, v241, v8 quad_perm:[2,2,2,2] row_mask:0xf bank_mask:0xf
	v_fmac_f32_dpp v76, v241, v9 quad_perm:[3,3,3,3] row_mask:0xf bank_mask:0xf
	s_waitcnt lgkmcnt(9)
	v_fmac_f32_dpp v57, v242, v10 quad_perm:[0,0,0,0] row_mask:0xf bank_mask:0xf
	v_fmac_f32_dpp v74, v242, v12 quad_perm:[1,1,1,1] row_mask:0xf bank_mask:0xf
	v_fmac_f32_dpp v75, v242, v13 quad_perm:[2,2,2,2] row_mask:0xf bank_mask:0xf
	v_fmac_f32_dpp v76, v242, v14 quad_perm:[3,3,3,3] row_mask:0xf bank_mask:0xf
	s_waitcnt lgkmcnt(8)
	v_fmac_f32_dpp v57, v243, v17 quad_perm:[0,0,0,0] row_mask:0xf bank_mask:0xf
	v_fmac_f32_dpp v74, v243, v19 quad_perm:[1,1,1,1] row_mask:0xf bank_mask:0xf
	v_fmac_f32_dpp v75, v243, v28 quad_perm:[2,2,2,2] row_mask:0xf bank_mask:0xf
	v_fmac_f32_dpp v76, v243, v35 quad_perm:[3,3,3,3] row_mask:0xf bank_mask:0xf
	s_waitcnt lgkmcnt(7)
	v_fmac_f32_dpp v57, v244, v36 quad_perm:[0,0,0,0] row_mask:0xf bank_mask:0xf
	v_fmac_f32_dpp v74, v244, v37 quad_perm:[1,1,1,1] row_mask:0xf bank_mask:0xf
	v_fmac_f32_dpp v75, v244, v38 quad_perm:[2,2,2,2] row_mask:0xf bank_mask:0xf
	v_fmac_f32_dpp v76, v244, v39 quad_perm:[3,3,3,3] row_mask:0xf bank_mask:0xf
	s_waitcnt lgkmcnt(6)
	v_fmac_f32_dpp v57, v245, v40 quad_perm:[0,0,0,0] row_mask:0xf bank_mask:0xf
	v_fmac_f32_dpp v74, v245, v41 quad_perm:[1,1,1,1] row_mask:0xf bank_mask:0xf
	v_fmac_f32_dpp v75, v245, v42 quad_perm:[2,2,2,2] row_mask:0xf bank_mask:0xf
	v_fmac_f32_dpp v76, v245, v43 quad_perm:[3,3,3,3] row_mask:0xf bank_mask:0xf
	s_waitcnt lgkmcnt(5)
	v_fmac_f32_dpp v57, v246, v44 quad_perm:[0,0,0,0] row_mask:0xf bank_mask:0xf
	v_fmac_f32_dpp v74, v246, v45 quad_perm:[1,1,1,1] row_mask:0xf bank_mask:0xf
	v_fmac_f32_dpp v75, v246, v46 quad_perm:[2,2,2,2] row_mask:0xf bank_mask:0xf
	v_fmac_f32_dpp v76, v246, v47 quad_perm:[3,3,3,3] row_mask:0xf bank_mask:0xf
	s_waitcnt lgkmcnt(4)
	v_fmac_f32_dpp v57, v247, v48 quad_perm:[0,0,0,0] row_mask:0xf bank_mask:0xf
	v_fmac_f32_dpp v74, v247, v49 quad_perm:[1,1,1,1] row_mask:0xf bank_mask:0xf
	v_fmac_f32_dpp v75, v247, v50 quad_perm:[2,2,2,2] row_mask:0xf bank_mask:0xf
	v_fmac_f32_dpp v76, v247, v51 quad_perm:[3,3,3,3] row_mask:0xf bank_mask:0xf
	s_waitcnt lgkmcnt(3)
	v_fmac_f32_dpp v57, v248, v52 quad_perm:[0,0,0,0] row_mask:0xf bank_mask:0xf
	v_fmac_f32_dpp v74, v248, v53 quad_perm:[1,1,1,1] row_mask:0xf bank_mask:0xf
	v_fmac_f32_dpp v75, v248, v54 quad_perm:[2,2,2,2] row_mask:0xf bank_mask:0xf
	v_fmac_f32_dpp v76, v248, v55 quad_perm:[3,3,3,3] row_mask:0xf bank_mask:0xf
	ds_read_b32 v240, v255 offset:9472
	ds_read_b32 v241, v255 offset:9488
	ds_read_b32 v242, v255 offset:9504
	ds_read_b32 v243, v255 offset:9520
	ds_read_b32 v244, v255 offset:9536
	ds_read_b32 v245, v255 offset:9552
	ds_read_b32 v246, v255 offset:9568
	ds_read_b32 v247, v255 offset:9584
	ds_read_b32 v248, v255 offset:9600
	ds_read_b32 v249, v255 offset:9616
	v_add_f32_e32 v57, v57, v74
	v_add_f32_e32 v58, v75, v76
	v_add_f32_e32 v57, v57, v58
	v_sub_f32_e32 v56, v56, v57
	s_waitcnt lgkmcnt(10)
	v_lshlrev_b32_e32 v57, 16, v238
	v_mul_f32_e32 v57, v239, v57
	s_and_saveexec_b64 s[0:1], s[16:17]
	s_cbranch_execz .LBB0_879
	v_mul_f32_e32 v57, v57, v254
.LBB0_879:
	s_or_b64 exec, exec, s[0:1]
	ds_read_u16 v238, v18 offset:10336
	ds_read_b32 v239, v16 offset:152
	ds_read_b32 v254, v15 offset:152
	s_waitcnt lgkmcnt(12)
	v_mul_f32_dpp v74, v240, v2 quad_perm:[0,0,0,0] row_mask:0xf bank_mask:0xf
	v_mul_f32_dpp v75, v240, v3 quad_perm:[1,1,1,1] row_mask:0xf bank_mask:0xf
	v_mul_f32_dpp v76, v240, v4 quad_perm:[2,2,2,2] row_mask:0xf bank_mask:0xf
	v_mul_f32_dpp v77, v240, v5 quad_perm:[3,3,3,3] row_mask:0xf bank_mask:0xf
	s_waitcnt lgkmcnt(11)
	v_fmac_f32_dpp v74, v241, v6 quad_perm:[0,0,0,0] row_mask:0xf bank_mask:0xf
	v_fmac_f32_dpp v75, v241, v7 quad_perm:[1,1,1,1] row_mask:0xf bank_mask:0xf
	v_fmac_f32_dpp v76, v241, v8 quad_perm:[2,2,2,2] row_mask:0xf bank_mask:0xf
	v_fmac_f32_dpp v77, v241, v9 quad_perm:[3,3,3,3] row_mask:0xf bank_mask:0xf
	s_waitcnt lgkmcnt(10)
	v_fmac_f32_dpp v74, v242, v10 quad_perm:[0,0,0,0] row_mask:0xf bank_mask:0xf
	v_fmac_f32_dpp v75, v242, v12 quad_perm:[1,1,1,1] row_mask:0xf bank_mask:0xf
	v_fmac_f32_dpp v76, v242, v13 quad_perm:[2,2,2,2] row_mask:0xf bank_mask:0xf
	v_fmac_f32_dpp v77, v242, v14 quad_perm:[3,3,3,3] row_mask:0xf bank_mask:0xf
	s_waitcnt lgkmcnt(9)
	v_fmac_f32_dpp v74, v243, v17 quad_perm:[0,0,0,0] row_mask:0xf bank_mask:0xf
	v_fmac_f32_dpp v75, v243, v19 quad_perm:[1,1,1,1] row_mask:0xf bank_mask:0xf
	v_fmac_f32_dpp v76, v243, v28 quad_perm:[2,2,2,2] row_mask:0xf bank_mask:0xf
	v_fmac_f32_dpp v77, v243, v35 quad_perm:[3,3,3,3] row_mask:0xf bank_mask:0xf
	s_waitcnt lgkmcnt(8)
	v_fmac_f32_dpp v74, v244, v36 quad_perm:[0,0,0,0] row_mask:0xf bank_mask:0xf
	v_fmac_f32_dpp v75, v244, v37 quad_perm:[1,1,1,1] row_mask:0xf bank_mask:0xf
	v_fmac_f32_dpp v76, v244, v38 quad_perm:[2,2,2,2] row_mask:0xf bank_mask:0xf
	v_fmac_f32_dpp v77, v244, v39 quad_perm:[3,3,3,3] row_mask:0xf bank_mask:0xf
	s_waitcnt lgkmcnt(7)
	v_fmac_f32_dpp v74, v245, v40 quad_perm:[0,0,0,0] row_mask:0xf bank_mask:0xf
	v_fmac_f32_dpp v75, v245, v41 quad_perm:[1,1,1,1] row_mask:0xf bank_mask:0xf
	v_fmac_f32_dpp v76, v245, v42 quad_perm:[2,2,2,2] row_mask:0xf bank_mask:0xf
	v_fmac_f32_dpp v77, v245, v43 quad_perm:[3,3,3,3] row_mask:0xf bank_mask:0xf
	s_waitcnt lgkmcnt(6)
	v_fmac_f32_dpp v74, v246, v44 quad_perm:[0,0,0,0] row_mask:0xf bank_mask:0xf
	v_fmac_f32_dpp v75, v246, v45 quad_perm:[1,1,1,1] row_mask:0xf bank_mask:0xf
	v_fmac_f32_dpp v76, v246, v46 quad_perm:[2,2,2,2] row_mask:0xf bank_mask:0xf
	v_fmac_f32_dpp v77, v246, v47 quad_perm:[3,3,3,3] row_mask:0xf bank_mask:0xf
	s_waitcnt lgkmcnt(5)
	v_fmac_f32_dpp v74, v247, v48 quad_perm:[0,0,0,0] row_mask:0xf bank_mask:0xf
	v_fmac_f32_dpp v75, v247, v49 quad_perm:[1,1,1,1] row_mask:0xf bank_mask:0xf
	v_fmac_f32_dpp v76, v247, v50 quad_perm:[2,2,2,2] row_mask:0xf bank_mask:0xf
	v_fmac_f32_dpp v77, v247, v51 quad_perm:[3,3,3,3] row_mask:0xf bank_mask:0xf
	s_waitcnt lgkmcnt(4)
	v_fmac_f32_dpp v74, v248, v52 quad_perm:[0,0,0,0] row_mask:0xf bank_mask:0xf
	v_fmac_f32_dpp v75, v248, v53 quad_perm:[1,1,1,1] row_mask:0xf bank_mask:0xf
	v_fmac_f32_dpp v76, v248, v54 quad_perm:[2,2,2,2] row_mask:0xf bank_mask:0xf
	v_fmac_f32_dpp v77, v248, v55 quad_perm:[3,3,3,3] row_mask:0xf bank_mask:0xf
	s_waitcnt lgkmcnt(3)
	v_fmac_f32_dpp v74, v249, v56 quad_perm:[0,0,0,0] row_mask:0xf bank_mask:0xf
	ds_read_b32 v240, v255 offset:9728
	ds_read_b32 v241, v255 offset:9744
	ds_read_b32 v242, v255 offset:9760
	ds_read_b32 v243, v255 offset:9776
	ds_read_b32 v244, v255 offset:9792
	ds_read_b32 v245, v255 offset:9808
	ds_read_b32 v246, v255 offset:9824
	ds_read_b32 v247, v255 offset:9840
	ds_read_b32 v248, v255 offset:9856
	ds_read_b32 v249, v255 offset:9872
	v_add_f32_e32 v58, v75, v74
	v_add_f32_e32 v59, v76, v77
	v_add_f32_e32 v58, v59, v58
	v_sub_f32_e32 v57, v57, v58
	s_waitcnt lgkmcnt(10)
	v_lshlrev_b32_e32 v58, 16, v238
	v_mul_f32_e32 v58, v239, v58
	s_and_saveexec_b64 s[0:1], s[16:17]
	s_cbranch_execz .LBB0_881
	v_mul_f32_e32 v58, v58, v254
.LBB0_881:
	s_or_b64 exec, exec, s[0:1]
	ds_read_u16 v238, v18 offset:10608
	ds_read_b32 v239, v16 offset:156
	ds_read_b32 v254, v15 offset:156
	s_waitcnt lgkmcnt(12)
	v_mul_f32_dpp v59, v240, v2 quad_perm:[0,0,0,0] row_mask:0xf bank_mask:0xf
	v_mul_f32_dpp v76, v240, v3 quad_perm:[1,1,1,1] row_mask:0xf bank_mask:0xf
	v_mul_f32_dpp v77, v240, v4 quad_perm:[2,2,2,2] row_mask:0xf bank_mask:0xf
	v_mul_f32_dpp v78, v240, v5 quad_perm:[3,3,3,3] row_mask:0xf bank_mask:0xf
	s_waitcnt lgkmcnt(11)
	v_fmac_f32_dpp v59, v241, v6 quad_perm:[0,0,0,0] row_mask:0xf bank_mask:0xf
	v_fmac_f32_dpp v76, v241, v7 quad_perm:[1,1,1,1] row_mask:0xf bank_mask:0xf
	v_fmac_f32_dpp v77, v241, v8 quad_perm:[2,2,2,2] row_mask:0xf bank_mask:0xf
	v_fmac_f32_dpp v78, v241, v9 quad_perm:[3,3,3,3] row_mask:0xf bank_mask:0xf
	s_waitcnt lgkmcnt(10)
	v_fmac_f32_dpp v59, v242, v10 quad_perm:[0,0,0,0] row_mask:0xf bank_mask:0xf
	v_fmac_f32_dpp v76, v242, v12 quad_perm:[1,1,1,1] row_mask:0xf bank_mask:0xf
	v_fmac_f32_dpp v77, v242, v13 quad_perm:[2,2,2,2] row_mask:0xf bank_mask:0xf
	v_fmac_f32_dpp v78, v242, v14 quad_perm:[3,3,3,3] row_mask:0xf bank_mask:0xf
	s_waitcnt lgkmcnt(9)
	v_fmac_f32_dpp v59, v243, v17 quad_perm:[0,0,0,0] row_mask:0xf bank_mask:0xf
	v_fmac_f32_dpp v76, v243, v19 quad_perm:[1,1,1,1] row_mask:0xf bank_mask:0xf
	v_fmac_f32_dpp v77, v243, v28 quad_perm:[2,2,2,2] row_mask:0xf bank_mask:0xf
	v_fmac_f32_dpp v78, v243, v35 quad_perm:[3,3,3,3] row_mask:0xf bank_mask:0xf
	s_waitcnt lgkmcnt(8)
	v_fmac_f32_dpp v59, v244, v36 quad_perm:[0,0,0,0] row_mask:0xf bank_mask:0xf
	v_fmac_f32_dpp v76, v244, v37 quad_perm:[1,1,1,1] row_mask:0xf bank_mask:0xf
	v_fmac_f32_dpp v77, v244, v38 quad_perm:[2,2,2,2] row_mask:0xf bank_mask:0xf
	v_fmac_f32_dpp v78, v244, v39 quad_perm:[3,3,3,3] row_mask:0xf bank_mask:0xf
	s_waitcnt lgkmcnt(7)
	v_fmac_f32_dpp v59, v245, v40 quad_perm:[0,0,0,0] row_mask:0xf bank_mask:0xf
	v_fmac_f32_dpp v76, v245, v41 quad_perm:[1,1,1,1] row_mask:0xf bank_mask:0xf
	v_fmac_f32_dpp v77, v245, v42 quad_perm:[2,2,2,2] row_mask:0xf bank_mask:0xf
	v_fmac_f32_dpp v78, v245, v43 quad_perm:[3,3,3,3] row_mask:0xf bank_mask:0xf
	s_waitcnt lgkmcnt(6)
	v_fmac_f32_dpp v59, v246, v44 quad_perm:[0,0,0,0] row_mask:0xf bank_mask:0xf
	v_fmac_f32_dpp v76, v246, v45 quad_perm:[1,1,1,1] row_mask:0xf bank_mask:0xf
	v_fmac_f32_dpp v77, v246, v46 quad_perm:[2,2,2,2] row_mask:0xf bank_mask:0xf
	v_fmac_f32_dpp v78, v246, v47 quad_perm:[3,3,3,3] row_mask:0xf bank_mask:0xf
	s_waitcnt lgkmcnt(5)
	v_fmac_f32_dpp v59, v247, v48 quad_perm:[0,0,0,0] row_mask:0xf bank_mask:0xf
	v_fmac_f32_dpp v76, v247, v49 quad_perm:[1,1,1,1] row_mask:0xf bank_mask:0xf
	v_fmac_f32_dpp v77, v247, v50 quad_perm:[2,2,2,2] row_mask:0xf bank_mask:0xf
	v_fmac_f32_dpp v78, v247, v51 quad_perm:[3,3,3,3] row_mask:0xf bank_mask:0xf
	s_waitcnt lgkmcnt(4)
	v_fmac_f32_dpp v59, v248, v52 quad_perm:[0,0,0,0] row_mask:0xf bank_mask:0xf
	v_fmac_f32_dpp v76, v248, v53 quad_perm:[1,1,1,1] row_mask:0xf bank_mask:0xf
	v_fmac_f32_dpp v77, v248, v54 quad_perm:[2,2,2,2] row_mask:0xf bank_mask:0xf
	v_fmac_f32_dpp v78, v248, v55 quad_perm:[3,3,3,3] row_mask:0xf bank_mask:0xf
	s_waitcnt lgkmcnt(3)
	v_fmac_f32_dpp v59, v249, v56 quad_perm:[0,0,0,0] row_mask:0xf bank_mask:0xf
	v_fmac_f32_dpp v76, v249, v57 quad_perm:[1,1,1,1] row_mask:0xf bank_mask:0xf
	ds_read_b32 v240, v255 offset:9984
	ds_read_b32 v241, v255 offset:10000
	ds_read_b32 v242, v255 offset:10016
	ds_read_b32 v243, v255 offset:10032
	ds_read_b32 v244, v255 offset:10048
	ds_read_b32 v245, v255 offset:10064
	ds_read_b32 v246, v255 offset:10080
	ds_read_b32 v247, v255 offset:10096
	ds_read_b32 v248, v255 offset:10112
	ds_read_b32 v249, v255 offset:10128
	v_add_f32_e32 v59, v59, v76
	v_add_f32_e32 v60, v77, v78
	v_add_f32_e32 v59, v60, v59
	v_sub_f32_e32 v58, v58, v59
	s_waitcnt lgkmcnt(10)
	v_lshlrev_b32_e32 v59, 16, v238
	v_mul_f32_e32 v59, v239, v59
	s_and_saveexec_b64 s[0:1], s[16:17]
	s_cbranch_execz .LBB0_883
	v_mul_f32_e32 v59, v59, v254
.LBB0_883:
	s_or_b64 exec, exec, s[0:1]
	ds_read_u16 v238, v18 offset:10880
	ds_read_b32 v239, v16 offset:160
	ds_read_b32 v254, v15 offset:160
	s_waitcnt lgkmcnt(12)
	v_mul_f32_dpp v76, v240, v2 quad_perm:[0,0,0,0] row_mask:0xf bank_mask:0xf
	v_mul_f32_dpp v77, v240, v3 quad_perm:[1,1,1,1] row_mask:0xf bank_mask:0xf
	v_mul_f32_dpp v78, v240, v4 quad_perm:[2,2,2,2] row_mask:0xf bank_mask:0xf
	v_mul_f32_dpp v79, v240, v5 quad_perm:[3,3,3,3] row_mask:0xf bank_mask:0xf
	s_waitcnt lgkmcnt(11)
	v_fmac_f32_dpp v76, v241, v6 quad_perm:[0,0,0,0] row_mask:0xf bank_mask:0xf
	v_fmac_f32_dpp v77, v241, v7 quad_perm:[1,1,1,1] row_mask:0xf bank_mask:0xf
	v_fmac_f32_dpp v78, v241, v8 quad_perm:[2,2,2,2] row_mask:0xf bank_mask:0xf
	v_fmac_f32_dpp v79, v241, v9 quad_perm:[3,3,3,3] row_mask:0xf bank_mask:0xf
	s_waitcnt lgkmcnt(10)
	v_fmac_f32_dpp v76, v242, v10 quad_perm:[0,0,0,0] row_mask:0xf bank_mask:0xf
	v_fmac_f32_dpp v77, v242, v12 quad_perm:[1,1,1,1] row_mask:0xf bank_mask:0xf
	v_fmac_f32_dpp v78, v242, v13 quad_perm:[2,2,2,2] row_mask:0xf bank_mask:0xf
	v_fmac_f32_dpp v79, v242, v14 quad_perm:[3,3,3,3] row_mask:0xf bank_mask:0xf
	s_waitcnt lgkmcnt(9)
	v_fmac_f32_dpp v76, v243, v17 quad_perm:[0,0,0,0] row_mask:0xf bank_mask:0xf
	v_fmac_f32_dpp v77, v243, v19 quad_perm:[1,1,1,1] row_mask:0xf bank_mask:0xf
	v_fmac_f32_dpp v78, v243, v28 quad_perm:[2,2,2,2] row_mask:0xf bank_mask:0xf
	v_fmac_f32_dpp v79, v243, v35 quad_perm:[3,3,3,3] row_mask:0xf bank_mask:0xf
	s_waitcnt lgkmcnt(8)
	v_fmac_f32_dpp v76, v244, v36 quad_perm:[0,0,0,0] row_mask:0xf bank_mask:0xf
	v_fmac_f32_dpp v77, v244, v37 quad_perm:[1,1,1,1] row_mask:0xf bank_mask:0xf
	v_fmac_f32_dpp v78, v244, v38 quad_perm:[2,2,2,2] row_mask:0xf bank_mask:0xf
	v_fmac_f32_dpp v79, v244, v39 quad_perm:[3,3,3,3] row_mask:0xf bank_mask:0xf
	s_waitcnt lgkmcnt(7)
	v_fmac_f32_dpp v76, v245, v40 quad_perm:[0,0,0,0] row_mask:0xf bank_mask:0xf
	v_fmac_f32_dpp v77, v245, v41 quad_perm:[1,1,1,1] row_mask:0xf bank_mask:0xf
	v_fmac_f32_dpp v78, v245, v42 quad_perm:[2,2,2,2] row_mask:0xf bank_mask:0xf
	v_fmac_f32_dpp v79, v245, v43 quad_perm:[3,3,3,3] row_mask:0xf bank_mask:0xf
	s_waitcnt lgkmcnt(6)
	v_fmac_f32_dpp v76, v246, v44 quad_perm:[0,0,0,0] row_mask:0xf bank_mask:0xf
	v_fmac_f32_dpp v77, v246, v45 quad_perm:[1,1,1,1] row_mask:0xf bank_mask:0xf
	v_fmac_f32_dpp v78, v246, v46 quad_perm:[2,2,2,2] row_mask:0xf bank_mask:0xf
	v_fmac_f32_dpp v79, v246, v47 quad_perm:[3,3,3,3] row_mask:0xf bank_mask:0xf
	s_waitcnt lgkmcnt(5)
	v_fmac_f32_dpp v76, v247, v48 quad_perm:[0,0,0,0] row_mask:0xf bank_mask:0xf
	v_fmac_f32_dpp v77, v247, v49 quad_perm:[1,1,1,1] row_mask:0xf bank_mask:0xf
	v_fmac_f32_dpp v78, v247, v50 quad_perm:[2,2,2,2] row_mask:0xf bank_mask:0xf
	v_fmac_f32_dpp v79, v247, v51 quad_perm:[3,3,3,3] row_mask:0xf bank_mask:0xf
	s_waitcnt lgkmcnt(4)
	v_fmac_f32_dpp v76, v248, v52 quad_perm:[0,0,0,0] row_mask:0xf bank_mask:0xf
	v_fmac_f32_dpp v77, v248, v53 quad_perm:[1,1,1,1] row_mask:0xf bank_mask:0xf
	v_fmac_f32_dpp v78, v248, v54 quad_perm:[2,2,2,2] row_mask:0xf bank_mask:0xf
	v_fmac_f32_dpp v79, v248, v55 quad_perm:[3,3,3,3] row_mask:0xf bank_mask:0xf
	s_waitcnt lgkmcnt(3)
	v_fmac_f32_dpp v76, v249, v56 quad_perm:[0,0,0,0] row_mask:0xf bank_mask:0xf
	v_fmac_f32_dpp v77, v249, v57 quad_perm:[1,1,1,1] row_mask:0xf bank_mask:0xf
	v_fmac_f32_dpp v78, v249, v58 quad_perm:[2,2,2,2] row_mask:0xf bank_mask:0xf
	ds_read_b32 v240, v255 offset:10240
	ds_read_b32 v241, v255 offset:10256
	ds_read_b32 v242, v255 offset:10272
	ds_read_b32 v243, v255 offset:10288
	ds_read_b32 v244, v255 offset:10304
	ds_read_b32 v245, v255 offset:10320
	ds_read_b32 v246, v255 offset:10336
	ds_read_b32 v247, v255 offset:10352
	ds_read_b32 v248, v255 offset:10368
	ds_read_b32 v249, v255 offset:10384
	v_add_f32_e32 v60, v76, v77
	v_add_f32_e32 v61, v79, v78
	v_add_f32_e32 v60, v60, v61
	v_sub_f32_e32 v59, v59, v60
	s_waitcnt lgkmcnt(10)
	v_lshlrev_b32_e32 v60, 16, v238
	v_mul_f32_e32 v60, v239, v60
	s_and_saveexec_b64 s[0:1], s[16:17]
	s_cbranch_execz .LBB0_885
	v_mul_f32_e32 v60, v60, v254
.LBB0_885:
	s_or_b64 exec, exec, s[0:1]
	ds_read_u16 v238, v18 offset:11152
	ds_read_b32 v239, v16 offset:164
	ds_read_b32 v254, v15 offset:164
	s_waitcnt lgkmcnt(12)
	v_mul_f32_dpp v61, v240, v2 quad_perm:[0,0,0,0] row_mask:0xf bank_mask:0xf
	v_mul_f32_dpp v78, v240, v3 quad_perm:[1,1,1,1] row_mask:0xf bank_mask:0xf
	v_mul_f32_dpp v79, v240, v4 quad_perm:[2,2,2,2] row_mask:0xf bank_mask:0xf
	v_mul_f32_dpp v80, v240, v5 quad_perm:[3,3,3,3] row_mask:0xf bank_mask:0xf
	s_waitcnt lgkmcnt(11)
	v_fmac_f32_dpp v61, v241, v6 quad_perm:[0,0,0,0] row_mask:0xf bank_mask:0xf
	v_fmac_f32_dpp v78, v241, v7 quad_perm:[1,1,1,1] row_mask:0xf bank_mask:0xf
	v_fmac_f32_dpp v79, v241, v8 quad_perm:[2,2,2,2] row_mask:0xf bank_mask:0xf
	v_fmac_f32_dpp v80, v241, v9 quad_perm:[3,3,3,3] row_mask:0xf bank_mask:0xf
	s_waitcnt lgkmcnt(10)
	v_fmac_f32_dpp v61, v242, v10 quad_perm:[0,0,0,0] row_mask:0xf bank_mask:0xf
	v_fmac_f32_dpp v78, v242, v12 quad_perm:[1,1,1,1] row_mask:0xf bank_mask:0xf
	v_fmac_f32_dpp v79, v242, v13 quad_perm:[2,2,2,2] row_mask:0xf bank_mask:0xf
	v_fmac_f32_dpp v80, v242, v14 quad_perm:[3,3,3,3] row_mask:0xf bank_mask:0xf
	s_waitcnt lgkmcnt(9)
	v_fmac_f32_dpp v61, v243, v17 quad_perm:[0,0,0,0] row_mask:0xf bank_mask:0xf
	v_fmac_f32_dpp v78, v243, v19 quad_perm:[1,1,1,1] row_mask:0xf bank_mask:0xf
	v_fmac_f32_dpp v79, v243, v28 quad_perm:[2,2,2,2] row_mask:0xf bank_mask:0xf
	v_fmac_f32_dpp v80, v243, v35 quad_perm:[3,3,3,3] row_mask:0xf bank_mask:0xf
	s_waitcnt lgkmcnt(8)
	v_fmac_f32_dpp v61, v244, v36 quad_perm:[0,0,0,0] row_mask:0xf bank_mask:0xf
	v_fmac_f32_dpp v78, v244, v37 quad_perm:[1,1,1,1] row_mask:0xf bank_mask:0xf
	v_fmac_f32_dpp v79, v244, v38 quad_perm:[2,2,2,2] row_mask:0xf bank_mask:0xf
	v_fmac_f32_dpp v80, v244, v39 quad_perm:[3,3,3,3] row_mask:0xf bank_mask:0xf
	s_waitcnt lgkmcnt(7)
	v_fmac_f32_dpp v61, v245, v40 quad_perm:[0,0,0,0] row_mask:0xf bank_mask:0xf
	v_fmac_f32_dpp v78, v245, v41 quad_perm:[1,1,1,1] row_mask:0xf bank_mask:0xf
	v_fmac_f32_dpp v79, v245, v42 quad_perm:[2,2,2,2] row_mask:0xf bank_mask:0xf
	v_fmac_f32_dpp v80, v245, v43 quad_perm:[3,3,3,3] row_mask:0xf bank_mask:0xf
	s_waitcnt lgkmcnt(6)
	v_fmac_f32_dpp v61, v246, v44 quad_perm:[0,0,0,0] row_mask:0xf bank_mask:0xf
	v_fmac_f32_dpp v78, v246, v45 quad_perm:[1,1,1,1] row_mask:0xf bank_mask:0xf
	v_fmac_f32_dpp v79, v246, v46 quad_perm:[2,2,2,2] row_mask:0xf bank_mask:0xf
	v_fmac_f32_dpp v80, v246, v47 quad_perm:[3,3,3,3] row_mask:0xf bank_mask:0xf
	s_waitcnt lgkmcnt(5)
	v_fmac_f32_dpp v61, v247, v48 quad_perm:[0,0,0,0] row_mask:0xf bank_mask:0xf
	v_fmac_f32_dpp v78, v247, v49 quad_perm:[1,1,1,1] row_mask:0xf bank_mask:0xf
	v_fmac_f32_dpp v79, v247, v50 quad_perm:[2,2,2,2] row_mask:0xf bank_mask:0xf
	v_fmac_f32_dpp v80, v247, v51 quad_perm:[3,3,3,3] row_mask:0xf bank_mask:0xf
	s_waitcnt lgkmcnt(4)
	v_fmac_f32_dpp v61, v248, v52 quad_perm:[0,0,0,0] row_mask:0xf bank_mask:0xf
	v_fmac_f32_dpp v78, v248, v53 quad_perm:[1,1,1,1] row_mask:0xf bank_mask:0xf
	v_fmac_f32_dpp v79, v248, v54 quad_perm:[2,2,2,2] row_mask:0xf bank_mask:0xf
	v_fmac_f32_dpp v80, v248, v55 quad_perm:[3,3,3,3] row_mask:0xf bank_mask:0xf
	s_waitcnt lgkmcnt(3)
	v_fmac_f32_dpp v61, v249, v56 quad_perm:[0,0,0,0] row_mask:0xf bank_mask:0xf
	v_fmac_f32_dpp v78, v249, v57 quad_perm:[1,1,1,1] row_mask:0xf bank_mask:0xf
	v_fmac_f32_dpp v79, v249, v58 quad_perm:[2,2,2,2] row_mask:0xf bank_mask:0xf
	v_fmac_f32_dpp v80, v249, v59 quad_perm:[3,3,3,3] row_mask:0xf bank_mask:0xf
	ds_read_b32 v240, v255 offset:10496
	ds_read_b32 v241, v255 offset:10512
	ds_read_b32 v242, v255 offset:10528
	ds_read_b32 v243, v255 offset:10544
	ds_read_b32 v244, v255 offset:10560
	ds_read_b32 v245, v255 offset:10576
	ds_read_b32 v246, v255 offset:10592
	ds_read_b32 v247, v255 offset:10608
	ds_read_b32 v248, v255 offset:10624
	ds_read_b32 v249, v255 offset:10640
	ds_read_b32 v250, v255 offset:10656
	v_add_f32_e32 v61, v61, v78
	v_add_f32_e32 v62, v79, v80
	v_add_f32_e32 v61, v61, v62
	v_sub_f32_e32 v60, v60, v61
	s_waitcnt lgkmcnt(11)
	v_lshlrev_b32_e32 v61, 16, v238
	v_mul_f32_e32 v61, v239, v61
	s_and_saveexec_b64 s[0:1], s[16:17]
	s_cbranch_execz .LBB0_887
	v_mul_f32_e32 v61, v61, v254
.LBB0_887:
	s_or_b64 exec, exec, s[0:1]
	ds_read_u16 v238, v18 offset:11424
	ds_read_b32 v239, v16 offset:168
	ds_read_b32 v254, v15 offset:168
	s_waitcnt lgkmcnt(13)
	v_mul_f32_dpp v78, v240, v2 quad_perm:[0,0,0,0] row_mask:0xf bank_mask:0xf
	v_mul_f32_dpp v79, v240, v3 quad_perm:[1,1,1,1] row_mask:0xf bank_mask:0xf
	v_mul_f32_dpp v80, v240, v4 quad_perm:[2,2,2,2] row_mask:0xf bank_mask:0xf
	v_mul_f32_dpp v81, v240, v5 quad_perm:[3,3,3,3] row_mask:0xf bank_mask:0xf
	s_waitcnt lgkmcnt(12)
	v_fmac_f32_dpp v78, v241, v6 quad_perm:[0,0,0,0] row_mask:0xf bank_mask:0xf
	v_fmac_f32_dpp v79, v241, v7 quad_perm:[1,1,1,1] row_mask:0xf bank_mask:0xf
	v_fmac_f32_dpp v80, v241, v8 quad_perm:[2,2,2,2] row_mask:0xf bank_mask:0xf
	v_fmac_f32_dpp v81, v241, v9 quad_perm:[3,3,3,3] row_mask:0xf bank_mask:0xf
	s_waitcnt lgkmcnt(11)
	v_fmac_f32_dpp v78, v242, v10 quad_perm:[0,0,0,0] row_mask:0xf bank_mask:0xf
	v_fmac_f32_dpp v79, v242, v12 quad_perm:[1,1,1,1] row_mask:0xf bank_mask:0xf
	v_fmac_f32_dpp v80, v242, v13 quad_perm:[2,2,2,2] row_mask:0xf bank_mask:0xf
	v_fmac_f32_dpp v81, v242, v14 quad_perm:[3,3,3,3] row_mask:0xf bank_mask:0xf
	s_waitcnt lgkmcnt(10)
	v_fmac_f32_dpp v78, v243, v17 quad_perm:[0,0,0,0] row_mask:0xf bank_mask:0xf
	v_fmac_f32_dpp v79, v243, v19 quad_perm:[1,1,1,1] row_mask:0xf bank_mask:0xf
	v_fmac_f32_dpp v80, v243, v28 quad_perm:[2,2,2,2] row_mask:0xf bank_mask:0xf
	v_fmac_f32_dpp v81, v243, v35 quad_perm:[3,3,3,3] row_mask:0xf bank_mask:0xf
	s_waitcnt lgkmcnt(9)
	v_fmac_f32_dpp v78, v244, v36 quad_perm:[0,0,0,0] row_mask:0xf bank_mask:0xf
	v_fmac_f32_dpp v79, v244, v37 quad_perm:[1,1,1,1] row_mask:0xf bank_mask:0xf
	v_fmac_f32_dpp v80, v244, v38 quad_perm:[2,2,2,2] row_mask:0xf bank_mask:0xf
	v_fmac_f32_dpp v81, v244, v39 quad_perm:[3,3,3,3] row_mask:0xf bank_mask:0xf
	s_waitcnt lgkmcnt(8)
	v_fmac_f32_dpp v78, v245, v40 quad_perm:[0,0,0,0] row_mask:0xf bank_mask:0xf
	v_fmac_f32_dpp v79, v245, v41 quad_perm:[1,1,1,1] row_mask:0xf bank_mask:0xf
	v_fmac_f32_dpp v80, v245, v42 quad_perm:[2,2,2,2] row_mask:0xf bank_mask:0xf
	v_fmac_f32_dpp v81, v245, v43 quad_perm:[3,3,3,3] row_mask:0xf bank_mask:0xf
	s_waitcnt lgkmcnt(7)
	v_fmac_f32_dpp v78, v246, v44 quad_perm:[0,0,0,0] row_mask:0xf bank_mask:0xf
	v_fmac_f32_dpp v79, v246, v45 quad_perm:[1,1,1,1] row_mask:0xf bank_mask:0xf
	v_fmac_f32_dpp v80, v246, v46 quad_perm:[2,2,2,2] row_mask:0xf bank_mask:0xf
	v_fmac_f32_dpp v81, v246, v47 quad_perm:[3,3,3,3] row_mask:0xf bank_mask:0xf
	s_waitcnt lgkmcnt(6)
	v_fmac_f32_dpp v78, v247, v48 quad_perm:[0,0,0,0] row_mask:0xf bank_mask:0xf
	v_fmac_f32_dpp v79, v247, v49 quad_perm:[1,1,1,1] row_mask:0xf bank_mask:0xf
	v_fmac_f32_dpp v80, v247, v50 quad_perm:[2,2,2,2] row_mask:0xf bank_mask:0xf
	v_fmac_f32_dpp v81, v247, v51 quad_perm:[3,3,3,3] row_mask:0xf bank_mask:0xf
	s_waitcnt lgkmcnt(5)
	v_fmac_f32_dpp v78, v248, v52 quad_perm:[0,0,0,0] row_mask:0xf bank_mask:0xf
	v_fmac_f32_dpp v79, v248, v53 quad_perm:[1,1,1,1] row_mask:0xf bank_mask:0xf
	v_fmac_f32_dpp v80, v248, v54 quad_perm:[2,2,2,2] row_mask:0xf bank_mask:0xf
	v_fmac_f32_dpp v81, v248, v55 quad_perm:[3,3,3,3] row_mask:0xf bank_mask:0xf
	s_waitcnt lgkmcnt(4)
	v_fmac_f32_dpp v78, v249, v56 quad_perm:[0,0,0,0] row_mask:0xf bank_mask:0xf
	v_fmac_f32_dpp v79, v249, v57 quad_perm:[1,1,1,1] row_mask:0xf bank_mask:0xf
	v_fmac_f32_dpp v80, v249, v58 quad_perm:[2,2,2,2] row_mask:0xf bank_mask:0xf
	v_fmac_f32_dpp v81, v249, v59 quad_perm:[3,3,3,3] row_mask:0xf bank_mask:0xf
	s_waitcnt lgkmcnt(3)
	v_fmac_f32_dpp v78, v250, v60 quad_perm:[0,0,0,0] row_mask:0xf bank_mask:0xf
	ds_read_b32 v240, v255 offset:10752
	ds_read_b32 v241, v255 offset:10768
	ds_read_b32 v242, v255 offset:10784
	ds_read_b32 v243, v255 offset:10800
	ds_read_b32 v244, v255 offset:10816
	ds_read_b32 v245, v255 offset:10832
	ds_read_b32 v246, v255 offset:10848
	ds_read_b32 v247, v255 offset:10864
	ds_read_b32 v248, v255 offset:10880
	ds_read_b32 v249, v255 offset:10896
	ds_read_b32 v250, v255 offset:10912
	v_add_f32_e32 v62, v79, v78
	v_add_f32_e32 v63, v80, v81
	v_add_f32_e32 v62, v63, v62
	v_sub_f32_e32 v61, v61, v62
	s_waitcnt lgkmcnt(11)
	v_lshlrev_b32_e32 v62, 16, v238
	v_mul_f32_e32 v62, v239, v62
	s_and_saveexec_b64 s[0:1], s[16:17]
	s_cbranch_execz .LBB0_889
	v_mul_f32_e32 v62, v62, v254
.LBB0_889:
	s_or_b64 exec, exec, s[0:1]
	ds_read_u16 v238, v18 offset:11696
	ds_read_b32 v239, v16 offset:172
	ds_read_b32 v254, v15 offset:172
	s_waitcnt lgkmcnt(13)
	v_mul_f32_dpp v63, v240, v2 quad_perm:[0,0,0,0] row_mask:0xf bank_mask:0xf
	v_mul_f32_dpp v80, v240, v3 quad_perm:[1,1,1,1] row_mask:0xf bank_mask:0xf
	v_mul_f32_dpp v81, v240, v4 quad_perm:[2,2,2,2] row_mask:0xf bank_mask:0xf
	v_mul_f32_dpp v82, v240, v5 quad_perm:[3,3,3,3] row_mask:0xf bank_mask:0xf
	s_waitcnt lgkmcnt(12)
	v_fmac_f32_dpp v63, v241, v6 quad_perm:[0,0,0,0] row_mask:0xf bank_mask:0xf
	v_fmac_f32_dpp v80, v241, v7 quad_perm:[1,1,1,1] row_mask:0xf bank_mask:0xf
	v_fmac_f32_dpp v81, v241, v8 quad_perm:[2,2,2,2] row_mask:0xf bank_mask:0xf
	v_fmac_f32_dpp v82, v241, v9 quad_perm:[3,3,3,3] row_mask:0xf bank_mask:0xf
	s_waitcnt lgkmcnt(11)
	v_fmac_f32_dpp v63, v242, v10 quad_perm:[0,0,0,0] row_mask:0xf bank_mask:0xf
	v_fmac_f32_dpp v80, v242, v12 quad_perm:[1,1,1,1] row_mask:0xf bank_mask:0xf
	v_fmac_f32_dpp v81, v242, v13 quad_perm:[2,2,2,2] row_mask:0xf bank_mask:0xf
	v_fmac_f32_dpp v82, v242, v14 quad_perm:[3,3,3,3] row_mask:0xf bank_mask:0xf
	s_waitcnt lgkmcnt(10)
	v_fmac_f32_dpp v63, v243, v17 quad_perm:[0,0,0,0] row_mask:0xf bank_mask:0xf
	v_fmac_f32_dpp v80, v243, v19 quad_perm:[1,1,1,1] row_mask:0xf bank_mask:0xf
	v_fmac_f32_dpp v81, v243, v28 quad_perm:[2,2,2,2] row_mask:0xf bank_mask:0xf
	v_fmac_f32_dpp v82, v243, v35 quad_perm:[3,3,3,3] row_mask:0xf bank_mask:0xf
	s_waitcnt lgkmcnt(9)
	v_fmac_f32_dpp v63, v244, v36 quad_perm:[0,0,0,0] row_mask:0xf bank_mask:0xf
	v_fmac_f32_dpp v80, v244, v37 quad_perm:[1,1,1,1] row_mask:0xf bank_mask:0xf
	v_fmac_f32_dpp v81, v244, v38 quad_perm:[2,2,2,2] row_mask:0xf bank_mask:0xf
	v_fmac_f32_dpp v82, v244, v39 quad_perm:[3,3,3,3] row_mask:0xf bank_mask:0xf
	s_waitcnt lgkmcnt(8)
	v_fmac_f32_dpp v63, v245, v40 quad_perm:[0,0,0,0] row_mask:0xf bank_mask:0xf
	v_fmac_f32_dpp v80, v245, v41 quad_perm:[1,1,1,1] row_mask:0xf bank_mask:0xf
	v_fmac_f32_dpp v81, v245, v42 quad_perm:[2,2,2,2] row_mask:0xf bank_mask:0xf
	v_fmac_f32_dpp v82, v245, v43 quad_perm:[3,3,3,3] row_mask:0xf bank_mask:0xf
	s_waitcnt lgkmcnt(7)
	v_fmac_f32_dpp v63, v246, v44 quad_perm:[0,0,0,0] row_mask:0xf bank_mask:0xf
	v_fmac_f32_dpp v80, v246, v45 quad_perm:[1,1,1,1] row_mask:0xf bank_mask:0xf
	v_fmac_f32_dpp v81, v246, v46 quad_perm:[2,2,2,2] row_mask:0xf bank_mask:0xf
	v_fmac_f32_dpp v82, v246, v47 quad_perm:[3,3,3,3] row_mask:0xf bank_mask:0xf
	s_waitcnt lgkmcnt(6)
	v_fmac_f32_dpp v63, v247, v48 quad_perm:[0,0,0,0] row_mask:0xf bank_mask:0xf
	v_fmac_f32_dpp v80, v247, v49 quad_perm:[1,1,1,1] row_mask:0xf bank_mask:0xf
	v_fmac_f32_dpp v81, v247, v50 quad_perm:[2,2,2,2] row_mask:0xf bank_mask:0xf
	v_fmac_f32_dpp v82, v247, v51 quad_perm:[3,3,3,3] row_mask:0xf bank_mask:0xf
	s_waitcnt lgkmcnt(5)
	v_fmac_f32_dpp v63, v248, v52 quad_perm:[0,0,0,0] row_mask:0xf bank_mask:0xf
	v_fmac_f32_dpp v80, v248, v53 quad_perm:[1,1,1,1] row_mask:0xf bank_mask:0xf
	v_fmac_f32_dpp v81, v248, v54 quad_perm:[2,2,2,2] row_mask:0xf bank_mask:0xf
	v_fmac_f32_dpp v82, v248, v55 quad_perm:[3,3,3,3] row_mask:0xf bank_mask:0xf
	s_waitcnt lgkmcnt(4)
	v_fmac_f32_dpp v63, v249, v56 quad_perm:[0,0,0,0] row_mask:0xf bank_mask:0xf
	v_fmac_f32_dpp v80, v249, v57 quad_perm:[1,1,1,1] row_mask:0xf bank_mask:0xf
	v_fmac_f32_dpp v81, v249, v58 quad_perm:[2,2,2,2] row_mask:0xf bank_mask:0xf
	v_fmac_f32_dpp v82, v249, v59 quad_perm:[3,3,3,3] row_mask:0xf bank_mask:0xf
	s_waitcnt lgkmcnt(3)
	v_fmac_f32_dpp v63, v250, v60 quad_perm:[0,0,0,0] row_mask:0xf bank_mask:0xf
	v_fmac_f32_dpp v80, v250, v61 quad_perm:[1,1,1,1] row_mask:0xf bank_mask:0xf
	ds_read_b32 v240, v255 offset:11008
	ds_read_b32 v241, v255 offset:11024
	ds_read_b32 v242, v255 offset:11040
	ds_read_b32 v243, v255 offset:11056
	ds_read_b32 v244, v255 offset:11072
	ds_read_b32 v245, v255 offset:11088
	ds_read_b32 v246, v255 offset:11104
	ds_read_b32 v247, v255 offset:11120
	ds_read_b32 v248, v255 offset:11136
	ds_read_b32 v249, v255 offset:11152
	ds_read_b32 v250, v255 offset:11168
	v_add_f32_e32 v63, v63, v80
	v_add_f32_e32 v64, v81, v82
	v_add_f32_e32 v63, v64, v63
	v_sub_f32_e32 v62, v62, v63
	s_waitcnt lgkmcnt(11)
	v_lshlrev_b32_e32 v63, 16, v238
	v_mul_f32_e32 v63, v239, v63
	s_and_saveexec_b64 s[0:1], s[16:17]
	s_cbranch_execz .LBB0_891
	v_mul_f32_e32 v63, v63, v254
.LBB0_891:
	s_or_b64 exec, exec, s[0:1]
	ds_read_u16 v238, v18 offset:11968
	ds_read_b32 v239, v16 offset:176
	ds_read_b32 v254, v15 offset:176
	s_waitcnt lgkmcnt(13)
	v_mul_f32_dpp v80, v240, v2 quad_perm:[0,0,0,0] row_mask:0xf bank_mask:0xf
	v_mul_f32_dpp v81, v240, v3 quad_perm:[1,1,1,1] row_mask:0xf bank_mask:0xf
	v_mul_f32_dpp v82, v240, v4 quad_perm:[2,2,2,2] row_mask:0xf bank_mask:0xf
	v_mul_f32_dpp v83, v240, v5 quad_perm:[3,3,3,3] row_mask:0xf bank_mask:0xf
	s_waitcnt lgkmcnt(12)
	v_fmac_f32_dpp v80, v241, v6 quad_perm:[0,0,0,0] row_mask:0xf bank_mask:0xf
	v_fmac_f32_dpp v81, v241, v7 quad_perm:[1,1,1,1] row_mask:0xf bank_mask:0xf
	v_fmac_f32_dpp v82, v241, v8 quad_perm:[2,2,2,2] row_mask:0xf bank_mask:0xf
	v_fmac_f32_dpp v83, v241, v9 quad_perm:[3,3,3,3] row_mask:0xf bank_mask:0xf
	s_waitcnt lgkmcnt(11)
	v_fmac_f32_dpp v80, v242, v10 quad_perm:[0,0,0,0] row_mask:0xf bank_mask:0xf
	v_fmac_f32_dpp v81, v242, v12 quad_perm:[1,1,1,1] row_mask:0xf bank_mask:0xf
	v_fmac_f32_dpp v82, v242, v13 quad_perm:[2,2,2,2] row_mask:0xf bank_mask:0xf
	v_fmac_f32_dpp v83, v242, v14 quad_perm:[3,3,3,3] row_mask:0xf bank_mask:0xf
	s_waitcnt lgkmcnt(10)
	v_fmac_f32_dpp v80, v243, v17 quad_perm:[0,0,0,0] row_mask:0xf bank_mask:0xf
	v_fmac_f32_dpp v81, v243, v19 quad_perm:[1,1,1,1] row_mask:0xf bank_mask:0xf
	v_fmac_f32_dpp v82, v243, v28 quad_perm:[2,2,2,2] row_mask:0xf bank_mask:0xf
	v_fmac_f32_dpp v83, v243, v35 quad_perm:[3,3,3,3] row_mask:0xf bank_mask:0xf
	s_waitcnt lgkmcnt(9)
	v_fmac_f32_dpp v80, v244, v36 quad_perm:[0,0,0,0] row_mask:0xf bank_mask:0xf
	v_fmac_f32_dpp v81, v244, v37 quad_perm:[1,1,1,1] row_mask:0xf bank_mask:0xf
	v_fmac_f32_dpp v82, v244, v38 quad_perm:[2,2,2,2] row_mask:0xf bank_mask:0xf
	v_fmac_f32_dpp v83, v244, v39 quad_perm:[3,3,3,3] row_mask:0xf bank_mask:0xf
	s_waitcnt lgkmcnt(8)
	v_fmac_f32_dpp v80, v245, v40 quad_perm:[0,0,0,0] row_mask:0xf bank_mask:0xf
	v_fmac_f32_dpp v81, v245, v41 quad_perm:[1,1,1,1] row_mask:0xf bank_mask:0xf
	v_fmac_f32_dpp v82, v245, v42 quad_perm:[2,2,2,2] row_mask:0xf bank_mask:0xf
	v_fmac_f32_dpp v83, v245, v43 quad_perm:[3,3,3,3] row_mask:0xf bank_mask:0xf
	s_waitcnt lgkmcnt(7)
	v_fmac_f32_dpp v80, v246, v44 quad_perm:[0,0,0,0] row_mask:0xf bank_mask:0xf
	v_fmac_f32_dpp v81, v246, v45 quad_perm:[1,1,1,1] row_mask:0xf bank_mask:0xf
	v_fmac_f32_dpp v82, v246, v46 quad_perm:[2,2,2,2] row_mask:0xf bank_mask:0xf
	v_fmac_f32_dpp v83, v246, v47 quad_perm:[3,3,3,3] row_mask:0xf bank_mask:0xf
	s_waitcnt lgkmcnt(6)
	v_fmac_f32_dpp v80, v247, v48 quad_perm:[0,0,0,0] row_mask:0xf bank_mask:0xf
	v_fmac_f32_dpp v81, v247, v49 quad_perm:[1,1,1,1] row_mask:0xf bank_mask:0xf
	v_fmac_f32_dpp v82, v247, v50 quad_perm:[2,2,2,2] row_mask:0xf bank_mask:0xf
	v_fmac_f32_dpp v83, v247, v51 quad_perm:[3,3,3,3] row_mask:0xf bank_mask:0xf
	s_waitcnt lgkmcnt(5)
	v_fmac_f32_dpp v80, v248, v52 quad_perm:[0,0,0,0] row_mask:0xf bank_mask:0xf
	v_fmac_f32_dpp v81, v248, v53 quad_perm:[1,1,1,1] row_mask:0xf bank_mask:0xf
	v_fmac_f32_dpp v82, v248, v54 quad_perm:[2,2,2,2] row_mask:0xf bank_mask:0xf
	v_fmac_f32_dpp v83, v248, v55 quad_perm:[3,3,3,3] row_mask:0xf bank_mask:0xf
	s_waitcnt lgkmcnt(4)
	v_fmac_f32_dpp v80, v249, v56 quad_perm:[0,0,0,0] row_mask:0xf bank_mask:0xf
	v_fmac_f32_dpp v81, v249, v57 quad_perm:[1,1,1,1] row_mask:0xf bank_mask:0xf
	v_fmac_f32_dpp v82, v249, v58 quad_perm:[2,2,2,2] row_mask:0xf bank_mask:0xf
	v_fmac_f32_dpp v83, v249, v59 quad_perm:[3,3,3,3] row_mask:0xf bank_mask:0xf
	s_waitcnt lgkmcnt(3)
	v_fmac_f32_dpp v80, v250, v60 quad_perm:[0,0,0,0] row_mask:0xf bank_mask:0xf
	v_fmac_f32_dpp v81, v250, v61 quad_perm:[1,1,1,1] row_mask:0xf bank_mask:0xf
	v_fmac_f32_dpp v82, v250, v62 quad_perm:[2,2,2,2] row_mask:0xf bank_mask:0xf
	ds_read_b32 v240, v255 offset:11264
	ds_read_b32 v241, v255 offset:11280
	ds_read_b32 v242, v255 offset:11296
	ds_read_b32 v243, v255 offset:11312
	ds_read_b32 v244, v255 offset:11328
	ds_read_b32 v245, v255 offset:11344
	ds_read_b32 v246, v255 offset:11360
	ds_read_b32 v247, v255 offset:11376
	ds_read_b32 v248, v255 offset:11392
	ds_read_b32 v249, v255 offset:11408
	ds_read_b32 v250, v255 offset:11424
	v_add_f32_e32 v64, v80, v81
	v_add_f32_e32 v65, v83, v82
	v_add_f32_e32 v64, v64, v65
	v_sub_f32_e32 v63, v63, v64
	s_waitcnt lgkmcnt(11)
	v_lshlrev_b32_e32 v64, 16, v238
	v_mul_f32_e32 v64, v239, v64
	s_and_saveexec_b64 s[0:1], s[16:17]
	s_cbranch_execz .LBB0_893
	v_mul_f32_e32 v64, v64, v254
.LBB0_893:
	s_or_b64 exec, exec, s[0:1]
	ds_read_u16 v238, v18 offset:12240
	ds_read_b32 v239, v16 offset:180
	ds_read_b32 v254, v15 offset:180
	s_waitcnt lgkmcnt(13)
	v_mul_f32_dpp v65, v240, v2 quad_perm:[0,0,0,0] row_mask:0xf bank_mask:0xf
	v_mul_f32_dpp v82, v240, v3 quad_perm:[1,1,1,1] row_mask:0xf bank_mask:0xf
	v_mul_f32_dpp v83, v240, v4 quad_perm:[2,2,2,2] row_mask:0xf bank_mask:0xf
	v_mul_f32_dpp v84, v240, v5 quad_perm:[3,3,3,3] row_mask:0xf bank_mask:0xf
	s_waitcnt lgkmcnt(12)
	v_fmac_f32_dpp v65, v241, v6 quad_perm:[0,0,0,0] row_mask:0xf bank_mask:0xf
	v_fmac_f32_dpp v82, v241, v7 quad_perm:[1,1,1,1] row_mask:0xf bank_mask:0xf
	v_fmac_f32_dpp v83, v241, v8 quad_perm:[2,2,2,2] row_mask:0xf bank_mask:0xf
	v_fmac_f32_dpp v84, v241, v9 quad_perm:[3,3,3,3] row_mask:0xf bank_mask:0xf
	s_waitcnt lgkmcnt(11)
	v_fmac_f32_dpp v65, v242, v10 quad_perm:[0,0,0,0] row_mask:0xf bank_mask:0xf
	v_fmac_f32_dpp v82, v242, v12 quad_perm:[1,1,1,1] row_mask:0xf bank_mask:0xf
	v_fmac_f32_dpp v83, v242, v13 quad_perm:[2,2,2,2] row_mask:0xf bank_mask:0xf
	v_fmac_f32_dpp v84, v242, v14 quad_perm:[3,3,3,3] row_mask:0xf bank_mask:0xf
	s_waitcnt lgkmcnt(10)
	v_fmac_f32_dpp v65, v243, v17 quad_perm:[0,0,0,0] row_mask:0xf bank_mask:0xf
	v_fmac_f32_dpp v82, v243, v19 quad_perm:[1,1,1,1] row_mask:0xf bank_mask:0xf
	v_fmac_f32_dpp v83, v243, v28 quad_perm:[2,2,2,2] row_mask:0xf bank_mask:0xf
	v_fmac_f32_dpp v84, v243, v35 quad_perm:[3,3,3,3] row_mask:0xf bank_mask:0xf
	s_waitcnt lgkmcnt(9)
	v_fmac_f32_dpp v65, v244, v36 quad_perm:[0,0,0,0] row_mask:0xf bank_mask:0xf
	v_fmac_f32_dpp v82, v244, v37 quad_perm:[1,1,1,1] row_mask:0xf bank_mask:0xf
	v_fmac_f32_dpp v83, v244, v38 quad_perm:[2,2,2,2] row_mask:0xf bank_mask:0xf
	v_fmac_f32_dpp v84, v244, v39 quad_perm:[3,3,3,3] row_mask:0xf bank_mask:0xf
	s_waitcnt lgkmcnt(8)
	v_fmac_f32_dpp v65, v245, v40 quad_perm:[0,0,0,0] row_mask:0xf bank_mask:0xf
	v_fmac_f32_dpp v82, v245, v41 quad_perm:[1,1,1,1] row_mask:0xf bank_mask:0xf
	v_fmac_f32_dpp v83, v245, v42 quad_perm:[2,2,2,2] row_mask:0xf bank_mask:0xf
	v_fmac_f32_dpp v84, v245, v43 quad_perm:[3,3,3,3] row_mask:0xf bank_mask:0xf
	s_waitcnt lgkmcnt(7)
	v_fmac_f32_dpp v65, v246, v44 quad_perm:[0,0,0,0] row_mask:0xf bank_mask:0xf
	v_fmac_f32_dpp v82, v246, v45 quad_perm:[1,1,1,1] row_mask:0xf bank_mask:0xf
	v_fmac_f32_dpp v83, v246, v46 quad_perm:[2,2,2,2] row_mask:0xf bank_mask:0xf
	v_fmac_f32_dpp v84, v246, v47 quad_perm:[3,3,3,3] row_mask:0xf bank_mask:0xf
	s_waitcnt lgkmcnt(6)
	v_fmac_f32_dpp v65, v247, v48 quad_perm:[0,0,0,0] row_mask:0xf bank_mask:0xf
	v_fmac_f32_dpp v82, v247, v49 quad_perm:[1,1,1,1] row_mask:0xf bank_mask:0xf
	v_fmac_f32_dpp v83, v247, v50 quad_perm:[2,2,2,2] row_mask:0xf bank_mask:0xf
	v_fmac_f32_dpp v84, v247, v51 quad_perm:[3,3,3,3] row_mask:0xf bank_mask:0xf
	s_waitcnt lgkmcnt(5)
	v_fmac_f32_dpp v65, v248, v52 quad_perm:[0,0,0,0] row_mask:0xf bank_mask:0xf
	v_fmac_f32_dpp v82, v248, v53 quad_perm:[1,1,1,1] row_mask:0xf bank_mask:0xf
	v_fmac_f32_dpp v83, v248, v54 quad_perm:[2,2,2,2] row_mask:0xf bank_mask:0xf
	v_fmac_f32_dpp v84, v248, v55 quad_perm:[3,3,3,3] row_mask:0xf bank_mask:0xf
	s_waitcnt lgkmcnt(4)
	v_fmac_f32_dpp v65, v249, v56 quad_perm:[0,0,0,0] row_mask:0xf bank_mask:0xf
	v_fmac_f32_dpp v82, v249, v57 quad_perm:[1,1,1,1] row_mask:0xf bank_mask:0xf
	v_fmac_f32_dpp v83, v249, v58 quad_perm:[2,2,2,2] row_mask:0xf bank_mask:0xf
	v_fmac_f32_dpp v84, v249, v59 quad_perm:[3,3,3,3] row_mask:0xf bank_mask:0xf
	s_waitcnt lgkmcnt(3)
	v_fmac_f32_dpp v65, v250, v60 quad_perm:[0,0,0,0] row_mask:0xf bank_mask:0xf
	v_fmac_f32_dpp v82, v250, v61 quad_perm:[1,1,1,1] row_mask:0xf bank_mask:0xf
	v_fmac_f32_dpp v83, v250, v62 quad_perm:[2,2,2,2] row_mask:0xf bank_mask:0xf
	v_fmac_f32_dpp v84, v250, v63 quad_perm:[3,3,3,3] row_mask:0xf bank_mask:0xf
	ds_read_b32 v240, v255 offset:11520
	ds_read_b32 v241, v255 offset:11536
	ds_read_b32 v242, v255 offset:11552
	ds_read_b32 v243, v255 offset:11568
	ds_read_b32 v244, v255 offset:11584
	ds_read_b32 v245, v255 offset:11600
	ds_read_b32 v246, v255 offset:11616
	ds_read_b32 v247, v255 offset:11632
	ds_read_b32 v248, v255 offset:11648
	ds_read_b32 v249, v255 offset:11664
	ds_read_b32 v250, v255 offset:11680
	ds_read_b32 v251, v255 offset:11696
	v_add_f32_e32 v65, v65, v82
	v_add_f32_e32 v66, v83, v84
	v_add_f32_e32 v65, v65, v66
	v_sub_f32_e32 v64, v64, v65
	s_waitcnt lgkmcnt(12)
	v_lshlrev_b32_e32 v65, 16, v238
	v_mul_f32_e32 v65, v239, v65
	s_and_saveexec_b64 s[0:1], s[16:17]
	s_cbranch_execz .LBB0_895
	v_mul_f32_e32 v65, v65, v254
.LBB0_895:
	s_or_b64 exec, exec, s[0:1]
	ds_read_u16 v238, v18 offset:12512
	ds_read_b32 v239, v16 offset:184
	ds_read_b32 v254, v15 offset:184
	s_waitcnt lgkmcnt(14)
	v_mul_f32_dpp v82, v240, v2 quad_perm:[0,0,0,0] row_mask:0xf bank_mask:0xf
	v_mul_f32_dpp v83, v240, v3 quad_perm:[1,1,1,1] row_mask:0xf bank_mask:0xf
	v_mul_f32_dpp v84, v240, v4 quad_perm:[2,2,2,2] row_mask:0xf bank_mask:0xf
	v_mul_f32_dpp v85, v240, v5 quad_perm:[3,3,3,3] row_mask:0xf bank_mask:0xf
	s_waitcnt lgkmcnt(13)
	v_fmac_f32_dpp v82, v241, v6 quad_perm:[0,0,0,0] row_mask:0xf bank_mask:0xf
	v_fmac_f32_dpp v83, v241, v7 quad_perm:[1,1,1,1] row_mask:0xf bank_mask:0xf
	v_fmac_f32_dpp v84, v241, v8 quad_perm:[2,2,2,2] row_mask:0xf bank_mask:0xf
	v_fmac_f32_dpp v85, v241, v9 quad_perm:[3,3,3,3] row_mask:0xf bank_mask:0xf
	s_waitcnt lgkmcnt(12)
	v_fmac_f32_dpp v82, v242, v10 quad_perm:[0,0,0,0] row_mask:0xf bank_mask:0xf
	v_fmac_f32_dpp v83, v242, v12 quad_perm:[1,1,1,1] row_mask:0xf bank_mask:0xf
	v_fmac_f32_dpp v84, v242, v13 quad_perm:[2,2,2,2] row_mask:0xf bank_mask:0xf
	v_fmac_f32_dpp v85, v242, v14 quad_perm:[3,3,3,3] row_mask:0xf bank_mask:0xf
	s_waitcnt lgkmcnt(11)
	v_fmac_f32_dpp v82, v243, v17 quad_perm:[0,0,0,0] row_mask:0xf bank_mask:0xf
	v_fmac_f32_dpp v83, v243, v19 quad_perm:[1,1,1,1] row_mask:0xf bank_mask:0xf
	v_fmac_f32_dpp v84, v243, v28 quad_perm:[2,2,2,2] row_mask:0xf bank_mask:0xf
	v_fmac_f32_dpp v85, v243, v35 quad_perm:[3,3,3,3] row_mask:0xf bank_mask:0xf
	s_waitcnt lgkmcnt(10)
	v_fmac_f32_dpp v82, v244, v36 quad_perm:[0,0,0,0] row_mask:0xf bank_mask:0xf
	v_fmac_f32_dpp v83, v244, v37 quad_perm:[1,1,1,1] row_mask:0xf bank_mask:0xf
	v_fmac_f32_dpp v84, v244, v38 quad_perm:[2,2,2,2] row_mask:0xf bank_mask:0xf
	v_fmac_f32_dpp v85, v244, v39 quad_perm:[3,3,3,3] row_mask:0xf bank_mask:0xf
	s_waitcnt lgkmcnt(9)
	v_fmac_f32_dpp v82, v245, v40 quad_perm:[0,0,0,0] row_mask:0xf bank_mask:0xf
	v_fmac_f32_dpp v83, v245, v41 quad_perm:[1,1,1,1] row_mask:0xf bank_mask:0xf
	v_fmac_f32_dpp v84, v245, v42 quad_perm:[2,2,2,2] row_mask:0xf bank_mask:0xf
	v_fmac_f32_dpp v85, v245, v43 quad_perm:[3,3,3,3] row_mask:0xf bank_mask:0xf
	s_waitcnt lgkmcnt(8)
	v_fmac_f32_dpp v82, v246, v44 quad_perm:[0,0,0,0] row_mask:0xf bank_mask:0xf
	v_fmac_f32_dpp v83, v246, v45 quad_perm:[1,1,1,1] row_mask:0xf bank_mask:0xf
	v_fmac_f32_dpp v84, v246, v46 quad_perm:[2,2,2,2] row_mask:0xf bank_mask:0xf
	v_fmac_f32_dpp v85, v246, v47 quad_perm:[3,3,3,3] row_mask:0xf bank_mask:0xf
	s_waitcnt lgkmcnt(7)
	v_fmac_f32_dpp v82, v247, v48 quad_perm:[0,0,0,0] row_mask:0xf bank_mask:0xf
	v_fmac_f32_dpp v83, v247, v49 quad_perm:[1,1,1,1] row_mask:0xf bank_mask:0xf
	v_fmac_f32_dpp v84, v247, v50 quad_perm:[2,2,2,2] row_mask:0xf bank_mask:0xf
	v_fmac_f32_dpp v85, v247, v51 quad_perm:[3,3,3,3] row_mask:0xf bank_mask:0xf
	s_waitcnt lgkmcnt(6)
	v_fmac_f32_dpp v82, v248, v52 quad_perm:[0,0,0,0] row_mask:0xf bank_mask:0xf
	v_fmac_f32_dpp v83, v248, v53 quad_perm:[1,1,1,1] row_mask:0xf bank_mask:0xf
	v_fmac_f32_dpp v84, v248, v54 quad_perm:[2,2,2,2] row_mask:0xf bank_mask:0xf
	v_fmac_f32_dpp v85, v248, v55 quad_perm:[3,3,3,3] row_mask:0xf bank_mask:0xf
	s_waitcnt lgkmcnt(5)
	v_fmac_f32_dpp v82, v249, v56 quad_perm:[0,0,0,0] row_mask:0xf bank_mask:0xf
	v_fmac_f32_dpp v83, v249, v57 quad_perm:[1,1,1,1] row_mask:0xf bank_mask:0xf
	v_fmac_f32_dpp v84, v249, v58 quad_perm:[2,2,2,2] row_mask:0xf bank_mask:0xf
	v_fmac_f32_dpp v85, v249, v59 quad_perm:[3,3,3,3] row_mask:0xf bank_mask:0xf
	s_waitcnt lgkmcnt(4)
	v_fmac_f32_dpp v82, v250, v60 quad_perm:[0,0,0,0] row_mask:0xf bank_mask:0xf
	v_fmac_f32_dpp v83, v250, v61 quad_perm:[1,1,1,1] row_mask:0xf bank_mask:0xf
	v_fmac_f32_dpp v84, v250, v62 quad_perm:[2,2,2,2] row_mask:0xf bank_mask:0xf
	v_fmac_f32_dpp v85, v250, v63 quad_perm:[3,3,3,3] row_mask:0xf bank_mask:0xf
	s_waitcnt lgkmcnt(3)
	v_fmac_f32_dpp v82, v251, v64 quad_perm:[0,0,0,0] row_mask:0xf bank_mask:0xf
	ds_read_b32 v240, v255 offset:11776
	ds_read_b32 v241, v255 offset:11792
	ds_read_b32 v242, v255 offset:11808
	ds_read_b32 v243, v255 offset:11824
	ds_read_b32 v244, v255 offset:11840
	ds_read_b32 v245, v255 offset:11856
	ds_read_b32 v246, v255 offset:11872
	ds_read_b32 v247, v255 offset:11888
	ds_read_b32 v248, v255 offset:11904
	ds_read_b32 v249, v255 offset:11920
	ds_read_b32 v250, v255 offset:11936
	ds_read_b32 v251, v255 offset:11952
	v_add_f32_e32 v66, v83, v82
	v_add_f32_e32 v67, v84, v85
	v_add_f32_e32 v66, v67, v66
	v_sub_f32_e32 v65, v65, v66
	s_waitcnt lgkmcnt(12)
	v_lshlrev_b32_e32 v66, 16, v238
	v_mul_f32_e32 v66, v239, v66
	s_and_saveexec_b64 s[0:1], s[16:17]
	s_cbranch_execz .LBB0_897
	v_mul_f32_e32 v66, v66, v254
.LBB0_897:
	s_or_b64 exec, exec, s[0:1]
	ds_read_u16 v238, v18 offset:12784
	ds_read_b32 v239, v16 offset:188
	ds_read_b32 v254, v15 offset:188
	s_waitcnt lgkmcnt(14)
	v_mul_f32_dpp v67, v240, v2 quad_perm:[0,0,0,0] row_mask:0xf bank_mask:0xf
	v_mul_f32_dpp v84, v240, v3 quad_perm:[1,1,1,1] row_mask:0xf bank_mask:0xf
	v_mul_f32_dpp v85, v240, v4 quad_perm:[2,2,2,2] row_mask:0xf bank_mask:0xf
	v_mul_f32_dpp v86, v240, v5 quad_perm:[3,3,3,3] row_mask:0xf bank_mask:0xf
	s_waitcnt lgkmcnt(13)
	v_fmac_f32_dpp v67, v241, v6 quad_perm:[0,0,0,0] row_mask:0xf bank_mask:0xf
	v_fmac_f32_dpp v84, v241, v7 quad_perm:[1,1,1,1] row_mask:0xf bank_mask:0xf
	v_fmac_f32_dpp v85, v241, v8 quad_perm:[2,2,2,2] row_mask:0xf bank_mask:0xf
	v_fmac_f32_dpp v86, v241, v9 quad_perm:[3,3,3,3] row_mask:0xf bank_mask:0xf
	s_waitcnt lgkmcnt(12)
	v_fmac_f32_dpp v67, v242, v10 quad_perm:[0,0,0,0] row_mask:0xf bank_mask:0xf
	v_fmac_f32_dpp v84, v242, v12 quad_perm:[1,1,1,1] row_mask:0xf bank_mask:0xf
	v_fmac_f32_dpp v85, v242, v13 quad_perm:[2,2,2,2] row_mask:0xf bank_mask:0xf
	v_fmac_f32_dpp v86, v242, v14 quad_perm:[3,3,3,3] row_mask:0xf bank_mask:0xf
	s_waitcnt lgkmcnt(11)
	v_fmac_f32_dpp v67, v243, v17 quad_perm:[0,0,0,0] row_mask:0xf bank_mask:0xf
	v_fmac_f32_dpp v84, v243, v19 quad_perm:[1,1,1,1] row_mask:0xf bank_mask:0xf
	v_fmac_f32_dpp v85, v243, v28 quad_perm:[2,2,2,2] row_mask:0xf bank_mask:0xf
	v_fmac_f32_dpp v86, v243, v35 quad_perm:[3,3,3,3] row_mask:0xf bank_mask:0xf
	s_waitcnt lgkmcnt(10)
	v_fmac_f32_dpp v67, v244, v36 quad_perm:[0,0,0,0] row_mask:0xf bank_mask:0xf
	v_fmac_f32_dpp v84, v244, v37 quad_perm:[1,1,1,1] row_mask:0xf bank_mask:0xf
	v_fmac_f32_dpp v85, v244, v38 quad_perm:[2,2,2,2] row_mask:0xf bank_mask:0xf
	v_fmac_f32_dpp v86, v244, v39 quad_perm:[3,3,3,3] row_mask:0xf bank_mask:0xf
	s_waitcnt lgkmcnt(9)
	v_fmac_f32_dpp v67, v245, v40 quad_perm:[0,0,0,0] row_mask:0xf bank_mask:0xf
	v_fmac_f32_dpp v84, v245, v41 quad_perm:[1,1,1,1] row_mask:0xf bank_mask:0xf
	v_fmac_f32_dpp v85, v245, v42 quad_perm:[2,2,2,2] row_mask:0xf bank_mask:0xf
	v_fmac_f32_dpp v86, v245, v43 quad_perm:[3,3,3,3] row_mask:0xf bank_mask:0xf
	s_waitcnt lgkmcnt(8)
	v_fmac_f32_dpp v67, v246, v44 quad_perm:[0,0,0,0] row_mask:0xf bank_mask:0xf
	v_fmac_f32_dpp v84, v246, v45 quad_perm:[1,1,1,1] row_mask:0xf bank_mask:0xf
	v_fmac_f32_dpp v85, v246, v46 quad_perm:[2,2,2,2] row_mask:0xf bank_mask:0xf
	v_fmac_f32_dpp v86, v246, v47 quad_perm:[3,3,3,3] row_mask:0xf bank_mask:0xf
	s_waitcnt lgkmcnt(7)
	v_fmac_f32_dpp v67, v247, v48 quad_perm:[0,0,0,0] row_mask:0xf bank_mask:0xf
	v_fmac_f32_dpp v84, v247, v49 quad_perm:[1,1,1,1] row_mask:0xf bank_mask:0xf
	v_fmac_f32_dpp v85, v247, v50 quad_perm:[2,2,2,2] row_mask:0xf bank_mask:0xf
	v_fmac_f32_dpp v86, v247, v51 quad_perm:[3,3,3,3] row_mask:0xf bank_mask:0xf
	s_waitcnt lgkmcnt(6)
	v_fmac_f32_dpp v67, v248, v52 quad_perm:[0,0,0,0] row_mask:0xf bank_mask:0xf
	v_fmac_f32_dpp v84, v248, v53 quad_perm:[1,1,1,1] row_mask:0xf bank_mask:0xf
	v_fmac_f32_dpp v85, v248, v54 quad_perm:[2,2,2,2] row_mask:0xf bank_mask:0xf
	v_fmac_f32_dpp v86, v248, v55 quad_perm:[3,3,3,3] row_mask:0xf bank_mask:0xf
	s_waitcnt lgkmcnt(5)
	v_fmac_f32_dpp v67, v249, v56 quad_perm:[0,0,0,0] row_mask:0xf bank_mask:0xf
	v_fmac_f32_dpp v84, v249, v57 quad_perm:[1,1,1,1] row_mask:0xf bank_mask:0xf
	v_fmac_f32_dpp v85, v249, v58 quad_perm:[2,2,2,2] row_mask:0xf bank_mask:0xf
	v_fmac_f32_dpp v86, v249, v59 quad_perm:[3,3,3,3] row_mask:0xf bank_mask:0xf
	s_waitcnt lgkmcnt(4)
	v_fmac_f32_dpp v67, v250, v60 quad_perm:[0,0,0,0] row_mask:0xf bank_mask:0xf
	v_fmac_f32_dpp v84, v250, v61 quad_perm:[1,1,1,1] row_mask:0xf bank_mask:0xf
	v_fmac_f32_dpp v85, v250, v62 quad_perm:[2,2,2,2] row_mask:0xf bank_mask:0xf
	v_fmac_f32_dpp v86, v250, v63 quad_perm:[3,3,3,3] row_mask:0xf bank_mask:0xf
	s_waitcnt lgkmcnt(3)
	v_fmac_f32_dpp v67, v251, v64 quad_perm:[0,0,0,0] row_mask:0xf bank_mask:0xf
	v_fmac_f32_dpp v84, v251, v65 quad_perm:[1,1,1,1] row_mask:0xf bank_mask:0xf
	ds_read_b32 v240, v255 offset:12032
	ds_read_b32 v241, v255 offset:12048
	ds_read_b32 v242, v255 offset:12064
	ds_read_b32 v243, v255 offset:12080
	ds_read_b32 v244, v255 offset:12096
	ds_read_b32 v245, v255 offset:12112
	ds_read_b32 v246, v255 offset:12128
	ds_read_b32 v247, v255 offset:12144
	ds_read_b32 v248, v255 offset:12160
	ds_read_b32 v249, v255 offset:12176
	ds_read_b32 v250, v255 offset:12192
	ds_read_b32 v251, v255 offset:12208
	v_add_f32_e32 v67, v67, v84
	v_add_f32_e32 v68, v85, v86
	v_add_f32_e32 v67, v68, v67
	v_sub_f32_e32 v66, v66, v67
	s_waitcnt lgkmcnt(12)
	v_lshlrev_b32_e32 v67, 16, v238
	v_mul_f32_e32 v67, v239, v67
	s_and_saveexec_b64 s[0:1], s[16:17]
	s_cbranch_execz .LBB0_899
	v_mul_f32_e32 v67, v67, v254
.LBB0_899:
	s_or_b64 exec, exec, s[0:1]
	ds_read_u16 v238, v18 offset:13056
	ds_read_b32 v239, v16 offset:192
	ds_read_b32 v254, v15 offset:192
	s_waitcnt lgkmcnt(14)
	v_mul_f32_dpp v84, v240, v2 quad_perm:[0,0,0,0] row_mask:0xf bank_mask:0xf
	v_mul_f32_dpp v85, v240, v3 quad_perm:[1,1,1,1] row_mask:0xf bank_mask:0xf
	v_mul_f32_dpp v86, v240, v4 quad_perm:[2,2,2,2] row_mask:0xf bank_mask:0xf
	v_mul_f32_dpp v87, v240, v5 quad_perm:[3,3,3,3] row_mask:0xf bank_mask:0xf
	s_waitcnt lgkmcnt(13)
	v_fmac_f32_dpp v84, v241, v6 quad_perm:[0,0,0,0] row_mask:0xf bank_mask:0xf
	v_fmac_f32_dpp v85, v241, v7 quad_perm:[1,1,1,1] row_mask:0xf bank_mask:0xf
	v_fmac_f32_dpp v86, v241, v8 quad_perm:[2,2,2,2] row_mask:0xf bank_mask:0xf
	v_fmac_f32_dpp v87, v241, v9 quad_perm:[3,3,3,3] row_mask:0xf bank_mask:0xf
	s_waitcnt lgkmcnt(12)
	v_fmac_f32_dpp v84, v242, v10 quad_perm:[0,0,0,0] row_mask:0xf bank_mask:0xf
	v_fmac_f32_dpp v85, v242, v12 quad_perm:[1,1,1,1] row_mask:0xf bank_mask:0xf
	v_fmac_f32_dpp v86, v242, v13 quad_perm:[2,2,2,2] row_mask:0xf bank_mask:0xf
	v_fmac_f32_dpp v87, v242, v14 quad_perm:[3,3,3,3] row_mask:0xf bank_mask:0xf
	s_waitcnt lgkmcnt(11)
	v_fmac_f32_dpp v84, v243, v17 quad_perm:[0,0,0,0] row_mask:0xf bank_mask:0xf
	v_fmac_f32_dpp v85, v243, v19 quad_perm:[1,1,1,1] row_mask:0xf bank_mask:0xf
	v_fmac_f32_dpp v86, v243, v28 quad_perm:[2,2,2,2] row_mask:0xf bank_mask:0xf
	v_fmac_f32_dpp v87, v243, v35 quad_perm:[3,3,3,3] row_mask:0xf bank_mask:0xf
	s_waitcnt lgkmcnt(10)
	v_fmac_f32_dpp v84, v244, v36 quad_perm:[0,0,0,0] row_mask:0xf bank_mask:0xf
	v_fmac_f32_dpp v85, v244, v37 quad_perm:[1,1,1,1] row_mask:0xf bank_mask:0xf
	v_fmac_f32_dpp v86, v244, v38 quad_perm:[2,2,2,2] row_mask:0xf bank_mask:0xf
	v_fmac_f32_dpp v87, v244, v39 quad_perm:[3,3,3,3] row_mask:0xf bank_mask:0xf
	s_waitcnt lgkmcnt(9)
	v_fmac_f32_dpp v84, v245, v40 quad_perm:[0,0,0,0] row_mask:0xf bank_mask:0xf
	v_fmac_f32_dpp v85, v245, v41 quad_perm:[1,1,1,1] row_mask:0xf bank_mask:0xf
	v_fmac_f32_dpp v86, v245, v42 quad_perm:[2,2,2,2] row_mask:0xf bank_mask:0xf
	v_fmac_f32_dpp v87, v245, v43 quad_perm:[3,3,3,3] row_mask:0xf bank_mask:0xf
	s_waitcnt lgkmcnt(8)
	v_fmac_f32_dpp v84, v246, v44 quad_perm:[0,0,0,0] row_mask:0xf bank_mask:0xf
	v_fmac_f32_dpp v85, v246, v45 quad_perm:[1,1,1,1] row_mask:0xf bank_mask:0xf
	v_fmac_f32_dpp v86, v246, v46 quad_perm:[2,2,2,2] row_mask:0xf bank_mask:0xf
	v_fmac_f32_dpp v87, v246, v47 quad_perm:[3,3,3,3] row_mask:0xf bank_mask:0xf
	s_waitcnt lgkmcnt(7)
	v_fmac_f32_dpp v84, v247, v48 quad_perm:[0,0,0,0] row_mask:0xf bank_mask:0xf
	v_fmac_f32_dpp v85, v247, v49 quad_perm:[1,1,1,1] row_mask:0xf bank_mask:0xf
	v_fmac_f32_dpp v86, v247, v50 quad_perm:[2,2,2,2] row_mask:0xf bank_mask:0xf
	v_fmac_f32_dpp v87, v247, v51 quad_perm:[3,3,3,3] row_mask:0xf bank_mask:0xf
	s_waitcnt lgkmcnt(6)
	v_fmac_f32_dpp v84, v248, v52 quad_perm:[0,0,0,0] row_mask:0xf bank_mask:0xf
	v_fmac_f32_dpp v85, v248, v53 quad_perm:[1,1,1,1] row_mask:0xf bank_mask:0xf
	v_fmac_f32_dpp v86, v248, v54 quad_perm:[2,2,2,2] row_mask:0xf bank_mask:0xf
	v_fmac_f32_dpp v87, v248, v55 quad_perm:[3,3,3,3] row_mask:0xf bank_mask:0xf
	s_waitcnt lgkmcnt(5)
	v_fmac_f32_dpp v84, v249, v56 quad_perm:[0,0,0,0] row_mask:0xf bank_mask:0xf
	v_fmac_f32_dpp v85, v249, v57 quad_perm:[1,1,1,1] row_mask:0xf bank_mask:0xf
	v_fmac_f32_dpp v86, v249, v58 quad_perm:[2,2,2,2] row_mask:0xf bank_mask:0xf
	v_fmac_f32_dpp v87, v249, v59 quad_perm:[3,3,3,3] row_mask:0xf bank_mask:0xf
	s_waitcnt lgkmcnt(4)
	v_fmac_f32_dpp v84, v250, v60 quad_perm:[0,0,0,0] row_mask:0xf bank_mask:0xf
	v_fmac_f32_dpp v85, v250, v61 quad_perm:[1,1,1,1] row_mask:0xf bank_mask:0xf
	v_fmac_f32_dpp v86, v250, v62 quad_perm:[2,2,2,2] row_mask:0xf bank_mask:0xf
	v_fmac_f32_dpp v87, v250, v63 quad_perm:[3,3,3,3] row_mask:0xf bank_mask:0xf
	s_waitcnt lgkmcnt(3)
	v_fmac_f32_dpp v84, v251, v64 quad_perm:[0,0,0,0] row_mask:0xf bank_mask:0xf
	v_fmac_f32_dpp v85, v251, v65 quad_perm:[1,1,1,1] row_mask:0xf bank_mask:0xf
	v_fmac_f32_dpp v86, v251, v66 quad_perm:[2,2,2,2] row_mask:0xf bank_mask:0xf
	ds_read_b32 v240, v255 offset:12288
	ds_read_b32 v241, v255 offset:12304
	ds_read_b32 v242, v255 offset:12320
	ds_read_b32 v243, v255 offset:12336
	ds_read_b32 v244, v255 offset:12352
	ds_read_b32 v245, v255 offset:12368
	ds_read_b32 v246, v255 offset:12384
	ds_read_b32 v247, v255 offset:12400
	ds_read_b32 v248, v255 offset:12416
	ds_read_b32 v249, v255 offset:12432
	ds_read_b32 v250, v255 offset:12448
	ds_read_b32 v251, v255 offset:12464
	v_add_f32_e32 v68, v84, v85
	v_add_f32_e32 v69, v87, v86
	v_add_f32_e32 v68, v68, v69
	v_sub_f32_e32 v67, v67, v68
	s_waitcnt lgkmcnt(12)
	v_lshlrev_b32_e32 v68, 16, v238
	v_mul_f32_e32 v68, v239, v68
	s_and_saveexec_b64 s[0:1], s[16:17]
	s_cbranch_execz .LBB0_901
	v_mul_f32_e32 v68, v68, v254
.LBB0_901:
	s_or_b64 exec, exec, s[0:1]
	ds_read_u16 v238, v18 offset:13328
	ds_read_b32 v239, v16 offset:196
	ds_read_b32 v254, v15 offset:196
	s_waitcnt lgkmcnt(14)
	v_mul_f32_dpp v69, v240, v2 quad_perm:[0,0,0,0] row_mask:0xf bank_mask:0xf
	v_mul_f32_dpp v86, v240, v3 quad_perm:[1,1,1,1] row_mask:0xf bank_mask:0xf
	v_mul_f32_dpp v87, v240, v4 quad_perm:[2,2,2,2] row_mask:0xf bank_mask:0xf
	v_mul_f32_dpp v88, v240, v5 quad_perm:[3,3,3,3] row_mask:0xf bank_mask:0xf
	s_waitcnt lgkmcnt(13)
	v_fmac_f32_dpp v69, v241, v6 quad_perm:[0,0,0,0] row_mask:0xf bank_mask:0xf
	v_fmac_f32_dpp v86, v241, v7 quad_perm:[1,1,1,1] row_mask:0xf bank_mask:0xf
	v_fmac_f32_dpp v87, v241, v8 quad_perm:[2,2,2,2] row_mask:0xf bank_mask:0xf
	v_fmac_f32_dpp v88, v241, v9 quad_perm:[3,3,3,3] row_mask:0xf bank_mask:0xf
	s_waitcnt lgkmcnt(12)
	v_fmac_f32_dpp v69, v242, v10 quad_perm:[0,0,0,0] row_mask:0xf bank_mask:0xf
	v_fmac_f32_dpp v86, v242, v12 quad_perm:[1,1,1,1] row_mask:0xf bank_mask:0xf
	v_fmac_f32_dpp v87, v242, v13 quad_perm:[2,2,2,2] row_mask:0xf bank_mask:0xf
	v_fmac_f32_dpp v88, v242, v14 quad_perm:[3,3,3,3] row_mask:0xf bank_mask:0xf
	s_waitcnt lgkmcnt(11)
	v_fmac_f32_dpp v69, v243, v17 quad_perm:[0,0,0,0] row_mask:0xf bank_mask:0xf
	v_fmac_f32_dpp v86, v243, v19 quad_perm:[1,1,1,1] row_mask:0xf bank_mask:0xf
	v_fmac_f32_dpp v87, v243, v28 quad_perm:[2,2,2,2] row_mask:0xf bank_mask:0xf
	v_fmac_f32_dpp v88, v243, v35 quad_perm:[3,3,3,3] row_mask:0xf bank_mask:0xf
	s_waitcnt lgkmcnt(10)
	v_fmac_f32_dpp v69, v244, v36 quad_perm:[0,0,0,0] row_mask:0xf bank_mask:0xf
	v_fmac_f32_dpp v86, v244, v37 quad_perm:[1,1,1,1] row_mask:0xf bank_mask:0xf
	v_fmac_f32_dpp v87, v244, v38 quad_perm:[2,2,2,2] row_mask:0xf bank_mask:0xf
	v_fmac_f32_dpp v88, v244, v39 quad_perm:[3,3,3,3] row_mask:0xf bank_mask:0xf
	s_waitcnt lgkmcnt(9)
	v_fmac_f32_dpp v69, v245, v40 quad_perm:[0,0,0,0] row_mask:0xf bank_mask:0xf
	v_fmac_f32_dpp v86, v245, v41 quad_perm:[1,1,1,1] row_mask:0xf bank_mask:0xf
	v_fmac_f32_dpp v87, v245, v42 quad_perm:[2,2,2,2] row_mask:0xf bank_mask:0xf
	v_fmac_f32_dpp v88, v245, v43 quad_perm:[3,3,3,3] row_mask:0xf bank_mask:0xf
	s_waitcnt lgkmcnt(8)
	v_fmac_f32_dpp v69, v246, v44 quad_perm:[0,0,0,0] row_mask:0xf bank_mask:0xf
	v_fmac_f32_dpp v86, v246, v45 quad_perm:[1,1,1,1] row_mask:0xf bank_mask:0xf
	v_fmac_f32_dpp v87, v246, v46 quad_perm:[2,2,2,2] row_mask:0xf bank_mask:0xf
	v_fmac_f32_dpp v88, v246, v47 quad_perm:[3,3,3,3] row_mask:0xf bank_mask:0xf
	s_waitcnt lgkmcnt(7)
	v_fmac_f32_dpp v69, v247, v48 quad_perm:[0,0,0,0] row_mask:0xf bank_mask:0xf
	v_fmac_f32_dpp v86, v247, v49 quad_perm:[1,1,1,1] row_mask:0xf bank_mask:0xf
	v_fmac_f32_dpp v87, v247, v50 quad_perm:[2,2,2,2] row_mask:0xf bank_mask:0xf
	v_fmac_f32_dpp v88, v247, v51 quad_perm:[3,3,3,3] row_mask:0xf bank_mask:0xf
	s_waitcnt lgkmcnt(6)
	v_fmac_f32_dpp v69, v248, v52 quad_perm:[0,0,0,0] row_mask:0xf bank_mask:0xf
	v_fmac_f32_dpp v86, v248, v53 quad_perm:[1,1,1,1] row_mask:0xf bank_mask:0xf
	v_fmac_f32_dpp v87, v248, v54 quad_perm:[2,2,2,2] row_mask:0xf bank_mask:0xf
	v_fmac_f32_dpp v88, v248, v55 quad_perm:[3,3,3,3] row_mask:0xf bank_mask:0xf
	s_waitcnt lgkmcnt(5)
	v_fmac_f32_dpp v69, v249, v56 quad_perm:[0,0,0,0] row_mask:0xf bank_mask:0xf
	v_fmac_f32_dpp v86, v249, v57 quad_perm:[1,1,1,1] row_mask:0xf bank_mask:0xf
	v_fmac_f32_dpp v87, v249, v58 quad_perm:[2,2,2,2] row_mask:0xf bank_mask:0xf
	v_fmac_f32_dpp v88, v249, v59 quad_perm:[3,3,3,3] row_mask:0xf bank_mask:0xf
	s_waitcnt lgkmcnt(4)
	v_fmac_f32_dpp v69, v250, v60 quad_perm:[0,0,0,0] row_mask:0xf bank_mask:0xf
	v_fmac_f32_dpp v86, v250, v61 quad_perm:[1,1,1,1] row_mask:0xf bank_mask:0xf
	v_fmac_f32_dpp v87, v250, v62 quad_perm:[2,2,2,2] row_mask:0xf bank_mask:0xf
	v_fmac_f32_dpp v88, v250, v63 quad_perm:[3,3,3,3] row_mask:0xf bank_mask:0xf
	s_waitcnt lgkmcnt(3)
	v_fmac_f32_dpp v69, v251, v64 quad_perm:[0,0,0,0] row_mask:0xf bank_mask:0xf
	v_fmac_f32_dpp v86, v251, v65 quad_perm:[1,1,1,1] row_mask:0xf bank_mask:0xf
	v_fmac_f32_dpp v87, v251, v66 quad_perm:[2,2,2,2] row_mask:0xf bank_mask:0xf
	v_fmac_f32_dpp v88, v251, v67 quad_perm:[3,3,3,3] row_mask:0xf bank_mask:0xf
	ds_read_b32 v240, v255 offset:12544
	ds_read_b32 v241, v255 offset:12560
	ds_read_b32 v242, v255 offset:12576
	ds_read_b32 v243, v255 offset:12592
	ds_read_b32 v244, v255 offset:12608
	ds_read_b32 v245, v255 offset:12624
	ds_read_b32 v246, v255 offset:12640
	ds_read_b32 v247, v255 offset:12656
	ds_read_b32 v248, v255 offset:12672
	ds_read_b32 v249, v255 offset:12688
	ds_read_b32 v250, v255 offset:12704
	ds_read_b32 v251, v255 offset:12720
	v_add_f32_e32 v69, v69, v86
	v_add_f32_e32 v70, v87, v88
	v_add_f32_e32 v69, v69, v70
	v_sub_f32_e32 v68, v68, v69
	s_waitcnt lgkmcnt(12)
	v_lshlrev_b32_e32 v69, 16, v238
	v_mul_f32_e32 v69, v239, v69
	s_and_saveexec_b64 s[0:1], s[16:17]
	s_cbranch_execz .LBB0_903
	v_mul_f32_e32 v69, v69, v254
.LBB0_903:
	s_or_b64 exec, exec, s[0:1]
	ds_read_u16 v238, v18 offset:13600
	ds_read_b32 v239, v16 offset:200
	ds_read_b32 v254, v15 offset:200
	s_waitcnt lgkmcnt(14)
	v_mul_f32_dpp v86, v240, v2 quad_perm:[0,0,0,0] row_mask:0xf bank_mask:0xf
	v_mul_f32_dpp v87, v240, v3 quad_perm:[1,1,1,1] row_mask:0xf bank_mask:0xf
	v_mul_f32_dpp v88, v240, v4 quad_perm:[2,2,2,2] row_mask:0xf bank_mask:0xf
	v_mul_f32_dpp v89, v240, v5 quad_perm:[3,3,3,3] row_mask:0xf bank_mask:0xf
	ds_read_b32 v240, v255 offset:12736
	s_waitcnt lgkmcnt(14)
	v_fmac_f32_dpp v86, v241, v6 quad_perm:[0,0,0,0] row_mask:0xf bank_mask:0xf
	v_fmac_f32_dpp v87, v241, v7 quad_perm:[1,1,1,1] row_mask:0xf bank_mask:0xf
	v_fmac_f32_dpp v88, v241, v8 quad_perm:[2,2,2,2] row_mask:0xf bank_mask:0xf
	v_fmac_f32_dpp v89, v241, v9 quad_perm:[3,3,3,3] row_mask:0xf bank_mask:0xf
	s_waitcnt lgkmcnt(13)
	v_fmac_f32_dpp v86, v242, v10 quad_perm:[0,0,0,0] row_mask:0xf bank_mask:0xf
	v_fmac_f32_dpp v87, v242, v12 quad_perm:[1,1,1,1] row_mask:0xf bank_mask:0xf
	v_fmac_f32_dpp v88, v242, v13 quad_perm:[2,2,2,2] row_mask:0xf bank_mask:0xf
	v_fmac_f32_dpp v89, v242, v14 quad_perm:[3,3,3,3] row_mask:0xf bank_mask:0xf
	s_waitcnt lgkmcnt(12)
	v_fmac_f32_dpp v86, v243, v17 quad_perm:[0,0,0,0] row_mask:0xf bank_mask:0xf
	v_fmac_f32_dpp v87, v243, v19 quad_perm:[1,1,1,1] row_mask:0xf bank_mask:0xf
	v_fmac_f32_dpp v88, v243, v28 quad_perm:[2,2,2,2] row_mask:0xf bank_mask:0xf
	v_fmac_f32_dpp v89, v243, v35 quad_perm:[3,3,3,3] row_mask:0xf bank_mask:0xf
	s_waitcnt lgkmcnt(11)
	v_fmac_f32_dpp v86, v244, v36 quad_perm:[0,0,0,0] row_mask:0xf bank_mask:0xf
	v_fmac_f32_dpp v87, v244, v37 quad_perm:[1,1,1,1] row_mask:0xf bank_mask:0xf
	v_fmac_f32_dpp v88, v244, v38 quad_perm:[2,2,2,2] row_mask:0xf bank_mask:0xf
	v_fmac_f32_dpp v89, v244, v39 quad_perm:[3,3,3,3] row_mask:0xf bank_mask:0xf
	s_waitcnt lgkmcnt(10)
	v_fmac_f32_dpp v86, v245, v40 quad_perm:[0,0,0,0] row_mask:0xf bank_mask:0xf
	v_fmac_f32_dpp v87, v245, v41 quad_perm:[1,1,1,1] row_mask:0xf bank_mask:0xf
	v_fmac_f32_dpp v88, v245, v42 quad_perm:[2,2,2,2] row_mask:0xf bank_mask:0xf
	v_fmac_f32_dpp v89, v245, v43 quad_perm:[3,3,3,3] row_mask:0xf bank_mask:0xf
	s_waitcnt lgkmcnt(9)
	v_fmac_f32_dpp v86, v246, v44 quad_perm:[0,0,0,0] row_mask:0xf bank_mask:0xf
	v_fmac_f32_dpp v87, v246, v45 quad_perm:[1,1,1,1] row_mask:0xf bank_mask:0xf
	v_fmac_f32_dpp v88, v246, v46 quad_perm:[2,2,2,2] row_mask:0xf bank_mask:0xf
	v_fmac_f32_dpp v89, v246, v47 quad_perm:[3,3,3,3] row_mask:0xf bank_mask:0xf
	s_waitcnt lgkmcnt(8)
	v_fmac_f32_dpp v86, v247, v48 quad_perm:[0,0,0,0] row_mask:0xf bank_mask:0xf
	v_fmac_f32_dpp v87, v247, v49 quad_perm:[1,1,1,1] row_mask:0xf bank_mask:0xf
	v_fmac_f32_dpp v88, v247, v50 quad_perm:[2,2,2,2] row_mask:0xf bank_mask:0xf
	v_fmac_f32_dpp v89, v247, v51 quad_perm:[3,3,3,3] row_mask:0xf bank_mask:0xf
	s_waitcnt lgkmcnt(7)
	v_fmac_f32_dpp v86, v248, v52 quad_perm:[0,0,0,0] row_mask:0xf bank_mask:0xf
	v_fmac_f32_dpp v87, v248, v53 quad_perm:[1,1,1,1] row_mask:0xf bank_mask:0xf
	v_fmac_f32_dpp v88, v248, v54 quad_perm:[2,2,2,2] row_mask:0xf bank_mask:0xf
	v_fmac_f32_dpp v89, v248, v55 quad_perm:[3,3,3,3] row_mask:0xf bank_mask:0xf
	s_waitcnt lgkmcnt(6)
	v_fmac_f32_dpp v86, v249, v56 quad_perm:[0,0,0,0] row_mask:0xf bank_mask:0xf
	v_fmac_f32_dpp v87, v249, v57 quad_perm:[1,1,1,1] row_mask:0xf bank_mask:0xf
	v_fmac_f32_dpp v88, v249, v58 quad_perm:[2,2,2,2] row_mask:0xf bank_mask:0xf
	v_fmac_f32_dpp v89, v249, v59 quad_perm:[3,3,3,3] row_mask:0xf bank_mask:0xf
	s_waitcnt lgkmcnt(5)
	v_fmac_f32_dpp v86, v250, v60 quad_perm:[0,0,0,0] row_mask:0xf bank_mask:0xf
	v_fmac_f32_dpp v87, v250, v61 quad_perm:[1,1,1,1] row_mask:0xf bank_mask:0xf
	v_fmac_f32_dpp v88, v250, v62 quad_perm:[2,2,2,2] row_mask:0xf bank_mask:0xf
	v_fmac_f32_dpp v89, v250, v63 quad_perm:[3,3,3,3] row_mask:0xf bank_mask:0xf
	s_waitcnt lgkmcnt(4)
	v_fmac_f32_dpp v86, v251, v64 quad_perm:[0,0,0,0] row_mask:0xf bank_mask:0xf
	v_fmac_f32_dpp v87, v251, v65 quad_perm:[1,1,1,1] row_mask:0xf bank_mask:0xf
	v_fmac_f32_dpp v88, v251, v66 quad_perm:[2,2,2,2] row_mask:0xf bank_mask:0xf
	v_fmac_f32_dpp v89, v251, v67 quad_perm:[3,3,3,3] row_mask:0xf bank_mask:0xf
	s_waitcnt lgkmcnt(0)
	v_fmac_f32_dpp v86, v240, v68 quad_perm:[0,0,0,0] row_mask:0xf bank_mask:0xf
	ds_read_b32 v240, v255 offset:12800
	ds_read_b32 v241, v255 offset:12816
	ds_read_b32 v242, v255 offset:12832
	ds_read_b32 v243, v255 offset:12848
	ds_read_b32 v244, v255 offset:12864
	ds_read_b32 v245, v255 offset:12880
	ds_read_b32 v246, v255 offset:12896
	ds_read_b32 v247, v255 offset:12912
	ds_read_b32 v248, v255 offset:12928
	ds_read_b32 v249, v255 offset:12944
	ds_read_b32 v250, v255 offset:12960
	ds_read_b32 v251, v255 offset:12976
	v_add_f32_e32 v70, v87, v86
	v_add_f32_e32 v71, v88, v89
	v_add_f32_e32 v70, v71, v70
	v_sub_f32_e32 v69, v69, v70
	v_lshlrev_b32_e32 v70, 16, v238
	v_mul_f32_e32 v70, v239, v70
	s_and_saveexec_b64 s[0:1], s[16:17]
	s_cbranch_execz .LBB0_905
	v_mul_f32_e32 v70, v70, v254
.LBB0_905:
	s_or_b64 exec, exec, s[0:1]
	ds_read_u16 v238, v18 offset:13872
	ds_read_b32 v239, v16 offset:204
	ds_read_b32 v254, v15 offset:204
	s_waitcnt lgkmcnt(14)
	v_mul_f32_dpp v71, v240, v2 quad_perm:[0,0,0,0] row_mask:0xf bank_mask:0xf
	v_mul_f32_dpp v88, v240, v3 quad_perm:[1,1,1,1] row_mask:0xf bank_mask:0xf
	v_mul_f32_dpp v89, v240, v4 quad_perm:[2,2,2,2] row_mask:0xf bank_mask:0xf
	v_mul_f32_dpp v90, v240, v5 quad_perm:[3,3,3,3] row_mask:0xf bank_mask:0xf
	ds_read_b32 v240, v255 offset:12992
	s_waitcnt lgkmcnt(14)
	v_fmac_f32_dpp v71, v241, v6 quad_perm:[0,0,0,0] row_mask:0xf bank_mask:0xf
	v_fmac_f32_dpp v88, v241, v7 quad_perm:[1,1,1,1] row_mask:0xf bank_mask:0xf
	v_fmac_f32_dpp v89, v241, v8 quad_perm:[2,2,2,2] row_mask:0xf bank_mask:0xf
	v_fmac_f32_dpp v90, v241, v9 quad_perm:[3,3,3,3] row_mask:0xf bank_mask:0xf
	s_waitcnt lgkmcnt(13)
	v_fmac_f32_dpp v71, v242, v10 quad_perm:[0,0,0,0] row_mask:0xf bank_mask:0xf
	v_fmac_f32_dpp v88, v242, v12 quad_perm:[1,1,1,1] row_mask:0xf bank_mask:0xf
	v_fmac_f32_dpp v89, v242, v13 quad_perm:[2,2,2,2] row_mask:0xf bank_mask:0xf
	v_fmac_f32_dpp v90, v242, v14 quad_perm:[3,3,3,3] row_mask:0xf bank_mask:0xf
	s_waitcnt lgkmcnt(12)
	v_fmac_f32_dpp v71, v243, v17 quad_perm:[0,0,0,0] row_mask:0xf bank_mask:0xf
	v_fmac_f32_dpp v88, v243, v19 quad_perm:[1,1,1,1] row_mask:0xf bank_mask:0xf
	v_fmac_f32_dpp v89, v243, v28 quad_perm:[2,2,2,2] row_mask:0xf bank_mask:0xf
	v_fmac_f32_dpp v90, v243, v35 quad_perm:[3,3,3,3] row_mask:0xf bank_mask:0xf
	s_waitcnt lgkmcnt(11)
	v_fmac_f32_dpp v71, v244, v36 quad_perm:[0,0,0,0] row_mask:0xf bank_mask:0xf
	v_fmac_f32_dpp v88, v244, v37 quad_perm:[1,1,1,1] row_mask:0xf bank_mask:0xf
	v_fmac_f32_dpp v89, v244, v38 quad_perm:[2,2,2,2] row_mask:0xf bank_mask:0xf
	v_fmac_f32_dpp v90, v244, v39 quad_perm:[3,3,3,3] row_mask:0xf bank_mask:0xf
	s_waitcnt lgkmcnt(10)
	v_fmac_f32_dpp v71, v245, v40 quad_perm:[0,0,0,0] row_mask:0xf bank_mask:0xf
	v_fmac_f32_dpp v88, v245, v41 quad_perm:[1,1,1,1] row_mask:0xf bank_mask:0xf
	v_fmac_f32_dpp v89, v245, v42 quad_perm:[2,2,2,2] row_mask:0xf bank_mask:0xf
	v_fmac_f32_dpp v90, v245, v43 quad_perm:[3,3,3,3] row_mask:0xf bank_mask:0xf
	s_waitcnt lgkmcnt(9)
	v_fmac_f32_dpp v71, v246, v44 quad_perm:[0,0,0,0] row_mask:0xf bank_mask:0xf
	v_fmac_f32_dpp v88, v246, v45 quad_perm:[1,1,1,1] row_mask:0xf bank_mask:0xf
	v_fmac_f32_dpp v89, v246, v46 quad_perm:[2,2,2,2] row_mask:0xf bank_mask:0xf
	v_fmac_f32_dpp v90, v246, v47 quad_perm:[3,3,3,3] row_mask:0xf bank_mask:0xf
	s_waitcnt lgkmcnt(8)
	v_fmac_f32_dpp v71, v247, v48 quad_perm:[0,0,0,0] row_mask:0xf bank_mask:0xf
	v_fmac_f32_dpp v88, v247, v49 quad_perm:[1,1,1,1] row_mask:0xf bank_mask:0xf
	v_fmac_f32_dpp v89, v247, v50 quad_perm:[2,2,2,2] row_mask:0xf bank_mask:0xf
	v_fmac_f32_dpp v90, v247, v51 quad_perm:[3,3,3,3] row_mask:0xf bank_mask:0xf
	s_waitcnt lgkmcnt(7)
	v_fmac_f32_dpp v71, v248, v52 quad_perm:[0,0,0,0] row_mask:0xf bank_mask:0xf
	v_fmac_f32_dpp v88, v248, v53 quad_perm:[1,1,1,1] row_mask:0xf bank_mask:0xf
	v_fmac_f32_dpp v89, v248, v54 quad_perm:[2,2,2,2] row_mask:0xf bank_mask:0xf
	v_fmac_f32_dpp v90, v248, v55 quad_perm:[3,3,3,3] row_mask:0xf bank_mask:0xf
	s_waitcnt lgkmcnt(6)
	v_fmac_f32_dpp v71, v249, v56 quad_perm:[0,0,0,0] row_mask:0xf bank_mask:0xf
	v_fmac_f32_dpp v88, v249, v57 quad_perm:[1,1,1,1] row_mask:0xf bank_mask:0xf
	v_fmac_f32_dpp v89, v249, v58 quad_perm:[2,2,2,2] row_mask:0xf bank_mask:0xf
	v_fmac_f32_dpp v90, v249, v59 quad_perm:[3,3,3,3] row_mask:0xf bank_mask:0xf
	s_waitcnt lgkmcnt(5)
	v_fmac_f32_dpp v71, v250, v60 quad_perm:[0,0,0,0] row_mask:0xf bank_mask:0xf
	v_fmac_f32_dpp v88, v250, v61 quad_perm:[1,1,1,1] row_mask:0xf bank_mask:0xf
	v_fmac_f32_dpp v89, v250, v62 quad_perm:[2,2,2,2] row_mask:0xf bank_mask:0xf
	v_fmac_f32_dpp v90, v250, v63 quad_perm:[3,3,3,3] row_mask:0xf bank_mask:0xf
	s_waitcnt lgkmcnt(4)
	v_fmac_f32_dpp v71, v251, v64 quad_perm:[0,0,0,0] row_mask:0xf bank_mask:0xf
	v_fmac_f32_dpp v88, v251, v65 quad_perm:[1,1,1,1] row_mask:0xf bank_mask:0xf
	v_fmac_f32_dpp v89, v251, v66 quad_perm:[2,2,2,2] row_mask:0xf bank_mask:0xf
	v_fmac_f32_dpp v90, v251, v67 quad_perm:[3,3,3,3] row_mask:0xf bank_mask:0xf
	s_waitcnt lgkmcnt(0)
	v_fmac_f32_dpp v71, v240, v68 quad_perm:[0,0,0,0] row_mask:0xf bank_mask:0xf
	v_fmac_f32_dpp v88, v240, v69 quad_perm:[1,1,1,1] row_mask:0xf bank_mask:0xf
	ds_read_b32 v240, v255 offset:13056
	ds_read_b32 v241, v255 offset:13072
	ds_read_b32 v242, v255 offset:13088
	ds_read_b32 v243, v255 offset:13104
	ds_read_b32 v244, v255 offset:13120
	ds_read_b32 v245, v255 offset:13136
	ds_read_b32 v246, v255 offset:13152
	ds_read_b32 v247, v255 offset:13168
	ds_read_b32 v248, v255 offset:13184
	ds_read_b32 v249, v255 offset:13200
	ds_read_b32 v250, v255 offset:13216
	ds_read_b32 v251, v255 offset:13232
	v_add_f32_e32 v71, v71, v88
	v_add_f32_e32 v72, v89, v90
	v_add_f32_e32 v71, v72, v71
	v_sub_f32_e32 v70, v70, v71
	v_lshlrev_b32_e32 v71, 16, v238
	v_mul_f32_e32 v71, v239, v71
	s_and_saveexec_b64 s[0:1], s[16:17]
	s_cbranch_execz .LBB0_907
	v_mul_f32_e32 v71, v71, v254
.LBB0_907:
	s_or_b64 exec, exec, s[0:1]
	ds_read_u16 v238, v18 offset:14144
	ds_read_b32 v239, v16 offset:208
	ds_read_b32 v254, v15 offset:208
	s_waitcnt lgkmcnt(14)
	v_mul_f32_dpp v88, v240, v2 quad_perm:[0,0,0,0] row_mask:0xf bank_mask:0xf
	v_mul_f32_dpp v89, v240, v3 quad_perm:[1,1,1,1] row_mask:0xf bank_mask:0xf
	v_mul_f32_dpp v90, v240, v4 quad_perm:[2,2,2,2] row_mask:0xf bank_mask:0xf
	v_mul_f32_dpp v91, v240, v5 quad_perm:[3,3,3,3] row_mask:0xf bank_mask:0xf
	ds_read_b32 v240, v255 offset:13248
	s_waitcnt lgkmcnt(14)
	v_fmac_f32_dpp v88, v241, v6 quad_perm:[0,0,0,0] row_mask:0xf bank_mask:0xf
	v_fmac_f32_dpp v89, v241, v7 quad_perm:[1,1,1,1] row_mask:0xf bank_mask:0xf
	v_fmac_f32_dpp v90, v241, v8 quad_perm:[2,2,2,2] row_mask:0xf bank_mask:0xf
	v_fmac_f32_dpp v91, v241, v9 quad_perm:[3,3,3,3] row_mask:0xf bank_mask:0xf
	s_waitcnt lgkmcnt(13)
	v_fmac_f32_dpp v88, v242, v10 quad_perm:[0,0,0,0] row_mask:0xf bank_mask:0xf
	v_fmac_f32_dpp v89, v242, v12 quad_perm:[1,1,1,1] row_mask:0xf bank_mask:0xf
	v_fmac_f32_dpp v90, v242, v13 quad_perm:[2,2,2,2] row_mask:0xf bank_mask:0xf
	v_fmac_f32_dpp v91, v242, v14 quad_perm:[3,3,3,3] row_mask:0xf bank_mask:0xf
	s_waitcnt lgkmcnt(12)
	v_fmac_f32_dpp v88, v243, v17 quad_perm:[0,0,0,0] row_mask:0xf bank_mask:0xf
	v_fmac_f32_dpp v89, v243, v19 quad_perm:[1,1,1,1] row_mask:0xf bank_mask:0xf
	v_fmac_f32_dpp v90, v243, v28 quad_perm:[2,2,2,2] row_mask:0xf bank_mask:0xf
	v_fmac_f32_dpp v91, v243, v35 quad_perm:[3,3,3,3] row_mask:0xf bank_mask:0xf
	s_waitcnt lgkmcnt(11)
	v_fmac_f32_dpp v88, v244, v36 quad_perm:[0,0,0,0] row_mask:0xf bank_mask:0xf
	v_fmac_f32_dpp v89, v244, v37 quad_perm:[1,1,1,1] row_mask:0xf bank_mask:0xf
	v_fmac_f32_dpp v90, v244, v38 quad_perm:[2,2,2,2] row_mask:0xf bank_mask:0xf
	v_fmac_f32_dpp v91, v244, v39 quad_perm:[3,3,3,3] row_mask:0xf bank_mask:0xf
	s_waitcnt lgkmcnt(10)
	v_fmac_f32_dpp v88, v245, v40 quad_perm:[0,0,0,0] row_mask:0xf bank_mask:0xf
	v_fmac_f32_dpp v89, v245, v41 quad_perm:[1,1,1,1] row_mask:0xf bank_mask:0xf
	v_fmac_f32_dpp v90, v245, v42 quad_perm:[2,2,2,2] row_mask:0xf bank_mask:0xf
	v_fmac_f32_dpp v91, v245, v43 quad_perm:[3,3,3,3] row_mask:0xf bank_mask:0xf
	s_waitcnt lgkmcnt(9)
	v_fmac_f32_dpp v88, v246, v44 quad_perm:[0,0,0,0] row_mask:0xf bank_mask:0xf
	v_fmac_f32_dpp v89, v246, v45 quad_perm:[1,1,1,1] row_mask:0xf bank_mask:0xf
	v_fmac_f32_dpp v90, v246, v46 quad_perm:[2,2,2,2] row_mask:0xf bank_mask:0xf
	v_fmac_f32_dpp v91, v246, v47 quad_perm:[3,3,3,3] row_mask:0xf bank_mask:0xf
	s_waitcnt lgkmcnt(8)
	v_fmac_f32_dpp v88, v247, v48 quad_perm:[0,0,0,0] row_mask:0xf bank_mask:0xf
	v_fmac_f32_dpp v89, v247, v49 quad_perm:[1,1,1,1] row_mask:0xf bank_mask:0xf
	v_fmac_f32_dpp v90, v247, v50 quad_perm:[2,2,2,2] row_mask:0xf bank_mask:0xf
	v_fmac_f32_dpp v91, v247, v51 quad_perm:[3,3,3,3] row_mask:0xf bank_mask:0xf
	s_waitcnt lgkmcnt(7)
	v_fmac_f32_dpp v88, v248, v52 quad_perm:[0,0,0,0] row_mask:0xf bank_mask:0xf
	v_fmac_f32_dpp v89, v248, v53 quad_perm:[1,1,1,1] row_mask:0xf bank_mask:0xf
	v_fmac_f32_dpp v90, v248, v54 quad_perm:[2,2,2,2] row_mask:0xf bank_mask:0xf
	v_fmac_f32_dpp v91, v248, v55 quad_perm:[3,3,3,3] row_mask:0xf bank_mask:0xf
	s_waitcnt lgkmcnt(6)
	v_fmac_f32_dpp v88, v249, v56 quad_perm:[0,0,0,0] row_mask:0xf bank_mask:0xf
	v_fmac_f32_dpp v89, v249, v57 quad_perm:[1,1,1,1] row_mask:0xf bank_mask:0xf
	v_fmac_f32_dpp v90, v249, v58 quad_perm:[2,2,2,2] row_mask:0xf bank_mask:0xf
	v_fmac_f32_dpp v91, v249, v59 quad_perm:[3,3,3,3] row_mask:0xf bank_mask:0xf
	s_waitcnt lgkmcnt(5)
	v_fmac_f32_dpp v88, v250, v60 quad_perm:[0,0,0,0] row_mask:0xf bank_mask:0xf
	v_fmac_f32_dpp v89, v250, v61 quad_perm:[1,1,1,1] row_mask:0xf bank_mask:0xf
	v_fmac_f32_dpp v90, v250, v62 quad_perm:[2,2,2,2] row_mask:0xf bank_mask:0xf
	v_fmac_f32_dpp v91, v250, v63 quad_perm:[3,3,3,3] row_mask:0xf bank_mask:0xf
	s_waitcnt lgkmcnt(4)
	v_fmac_f32_dpp v88, v251, v64 quad_perm:[0,0,0,0] row_mask:0xf bank_mask:0xf
	v_fmac_f32_dpp v89, v251, v65 quad_perm:[1,1,1,1] row_mask:0xf bank_mask:0xf
	v_fmac_f32_dpp v90, v251, v66 quad_perm:[2,2,2,2] row_mask:0xf bank_mask:0xf
	v_fmac_f32_dpp v91, v251, v67 quad_perm:[3,3,3,3] row_mask:0xf bank_mask:0xf
	s_waitcnt lgkmcnt(0)
	v_fmac_f32_dpp v88, v240, v68 quad_perm:[0,0,0,0] row_mask:0xf bank_mask:0xf
	v_fmac_f32_dpp v89, v240, v69 quad_perm:[1,1,1,1] row_mask:0xf bank_mask:0xf
	v_fmac_f32_dpp v90, v240, v70 quad_perm:[2,2,2,2] row_mask:0xf bank_mask:0xf
	ds_read_b32 v240, v255 offset:13312
	ds_read_b32 v241, v255 offset:13328
	ds_read_b32 v242, v255 offset:13344
	ds_read_b32 v243, v255 offset:13360
	ds_read_b32 v244, v255 offset:13376
	ds_read_b32 v245, v255 offset:13392
	ds_read_b32 v246, v255 offset:13408
	ds_read_b32 v247, v255 offset:13424
	ds_read_b32 v248, v255 offset:13440
	ds_read_b32 v249, v255 offset:13456
	ds_read_b32 v250, v255 offset:13472
	ds_read_b32 v251, v255 offset:13488
	v_add_f32_e32 v72, v88, v89
	v_add_f32_e32 v73, v91, v90
	v_add_f32_e32 v72, v72, v73
	v_sub_f32_e32 v71, v71, v72
	v_lshlrev_b32_e32 v72, 16, v238
	v_mul_f32_e32 v72, v239, v72
	s_and_saveexec_b64 s[0:1], s[16:17]
	s_cbranch_execz .LBB0_909
	v_mul_f32_e32 v72, v72, v254
.LBB0_909:
	s_or_b64 exec, exec, s[0:1]
	ds_read_u16 v238, v18 offset:14416
	ds_read_b32 v239, v16 offset:212
	ds_read_b32 v254, v15 offset:212
	s_waitcnt lgkmcnt(14)
	v_mul_f32_dpp v73, v240, v2 quad_perm:[0,0,0,0] row_mask:0xf bank_mask:0xf
	v_mul_f32_dpp v90, v240, v3 quad_perm:[1,1,1,1] row_mask:0xf bank_mask:0xf
	v_mul_f32_dpp v91, v240, v4 quad_perm:[2,2,2,2] row_mask:0xf bank_mask:0xf
	v_mul_f32_dpp v92, v240, v5 quad_perm:[3,3,3,3] row_mask:0xf bank_mask:0xf
	ds_read_b32 v240, v255 offset:13504
	s_waitcnt lgkmcnt(14)
	v_fmac_f32_dpp v73, v241, v6 quad_perm:[0,0,0,0] row_mask:0xf bank_mask:0xf
	v_fmac_f32_dpp v90, v241, v7 quad_perm:[1,1,1,1] row_mask:0xf bank_mask:0xf
	v_fmac_f32_dpp v91, v241, v8 quad_perm:[2,2,2,2] row_mask:0xf bank_mask:0xf
	v_fmac_f32_dpp v92, v241, v9 quad_perm:[3,3,3,3] row_mask:0xf bank_mask:0xf
	s_waitcnt lgkmcnt(13)
	v_fmac_f32_dpp v73, v242, v10 quad_perm:[0,0,0,0] row_mask:0xf bank_mask:0xf
	v_fmac_f32_dpp v90, v242, v12 quad_perm:[1,1,1,1] row_mask:0xf bank_mask:0xf
	v_fmac_f32_dpp v91, v242, v13 quad_perm:[2,2,2,2] row_mask:0xf bank_mask:0xf
	v_fmac_f32_dpp v92, v242, v14 quad_perm:[3,3,3,3] row_mask:0xf bank_mask:0xf
	s_waitcnt lgkmcnt(12)
	v_fmac_f32_dpp v73, v243, v17 quad_perm:[0,0,0,0] row_mask:0xf bank_mask:0xf
	v_fmac_f32_dpp v90, v243, v19 quad_perm:[1,1,1,1] row_mask:0xf bank_mask:0xf
	v_fmac_f32_dpp v91, v243, v28 quad_perm:[2,2,2,2] row_mask:0xf bank_mask:0xf
	v_fmac_f32_dpp v92, v243, v35 quad_perm:[3,3,3,3] row_mask:0xf bank_mask:0xf
	s_waitcnt lgkmcnt(11)
	v_fmac_f32_dpp v73, v244, v36 quad_perm:[0,0,0,0] row_mask:0xf bank_mask:0xf
	v_fmac_f32_dpp v90, v244, v37 quad_perm:[1,1,1,1] row_mask:0xf bank_mask:0xf
	v_fmac_f32_dpp v91, v244, v38 quad_perm:[2,2,2,2] row_mask:0xf bank_mask:0xf
	v_fmac_f32_dpp v92, v244, v39 quad_perm:[3,3,3,3] row_mask:0xf bank_mask:0xf
	s_waitcnt lgkmcnt(10)
	v_fmac_f32_dpp v73, v245, v40 quad_perm:[0,0,0,0] row_mask:0xf bank_mask:0xf
	v_fmac_f32_dpp v90, v245, v41 quad_perm:[1,1,1,1] row_mask:0xf bank_mask:0xf
	v_fmac_f32_dpp v91, v245, v42 quad_perm:[2,2,2,2] row_mask:0xf bank_mask:0xf
	v_fmac_f32_dpp v92, v245, v43 quad_perm:[3,3,3,3] row_mask:0xf bank_mask:0xf
	s_waitcnt lgkmcnt(9)
	v_fmac_f32_dpp v73, v246, v44 quad_perm:[0,0,0,0] row_mask:0xf bank_mask:0xf
	v_fmac_f32_dpp v90, v246, v45 quad_perm:[1,1,1,1] row_mask:0xf bank_mask:0xf
	v_fmac_f32_dpp v91, v246, v46 quad_perm:[2,2,2,2] row_mask:0xf bank_mask:0xf
	v_fmac_f32_dpp v92, v246, v47 quad_perm:[3,3,3,3] row_mask:0xf bank_mask:0xf
	s_waitcnt lgkmcnt(8)
	v_fmac_f32_dpp v73, v247, v48 quad_perm:[0,0,0,0] row_mask:0xf bank_mask:0xf
	v_fmac_f32_dpp v90, v247, v49 quad_perm:[1,1,1,1] row_mask:0xf bank_mask:0xf
	v_fmac_f32_dpp v91, v247, v50 quad_perm:[2,2,2,2] row_mask:0xf bank_mask:0xf
	v_fmac_f32_dpp v92, v247, v51 quad_perm:[3,3,3,3] row_mask:0xf bank_mask:0xf
	s_waitcnt lgkmcnt(7)
	v_fmac_f32_dpp v73, v248, v52 quad_perm:[0,0,0,0] row_mask:0xf bank_mask:0xf
	v_fmac_f32_dpp v90, v248, v53 quad_perm:[1,1,1,1] row_mask:0xf bank_mask:0xf
	v_fmac_f32_dpp v91, v248, v54 quad_perm:[2,2,2,2] row_mask:0xf bank_mask:0xf
	v_fmac_f32_dpp v92, v248, v55 quad_perm:[3,3,3,3] row_mask:0xf bank_mask:0xf
	s_waitcnt lgkmcnt(6)
	v_fmac_f32_dpp v73, v249, v56 quad_perm:[0,0,0,0] row_mask:0xf bank_mask:0xf
	v_fmac_f32_dpp v90, v249, v57 quad_perm:[1,1,1,1] row_mask:0xf bank_mask:0xf
	v_fmac_f32_dpp v91, v249, v58 quad_perm:[2,2,2,2] row_mask:0xf bank_mask:0xf
	v_fmac_f32_dpp v92, v249, v59 quad_perm:[3,3,3,3] row_mask:0xf bank_mask:0xf
	s_waitcnt lgkmcnt(5)
	v_fmac_f32_dpp v73, v250, v60 quad_perm:[0,0,0,0] row_mask:0xf bank_mask:0xf
	v_fmac_f32_dpp v90, v250, v61 quad_perm:[1,1,1,1] row_mask:0xf bank_mask:0xf
	v_fmac_f32_dpp v91, v250, v62 quad_perm:[2,2,2,2] row_mask:0xf bank_mask:0xf
	v_fmac_f32_dpp v92, v250, v63 quad_perm:[3,3,3,3] row_mask:0xf bank_mask:0xf
	s_waitcnt lgkmcnt(4)
	v_fmac_f32_dpp v73, v251, v64 quad_perm:[0,0,0,0] row_mask:0xf bank_mask:0xf
	v_fmac_f32_dpp v90, v251, v65 quad_perm:[1,1,1,1] row_mask:0xf bank_mask:0xf
	v_fmac_f32_dpp v91, v251, v66 quad_perm:[2,2,2,2] row_mask:0xf bank_mask:0xf
	v_fmac_f32_dpp v92, v251, v67 quad_perm:[3,3,3,3] row_mask:0xf bank_mask:0xf
	s_waitcnt lgkmcnt(0)
	v_fmac_f32_dpp v73, v240, v68 quad_perm:[0,0,0,0] row_mask:0xf bank_mask:0xf
	v_fmac_f32_dpp v90, v240, v69 quad_perm:[1,1,1,1] row_mask:0xf bank_mask:0xf
	v_fmac_f32_dpp v91, v240, v70 quad_perm:[2,2,2,2] row_mask:0xf bank_mask:0xf
	v_fmac_f32_dpp v92, v240, v71 quad_perm:[3,3,3,3] row_mask:0xf bank_mask:0xf
	ds_read_b32 v240, v255 offset:13568
	ds_read_b32 v241, v255 offset:13584
	ds_read_b32 v242, v255 offset:13600
	ds_read_b32 v243, v255 offset:13616
	ds_read_b32 v244, v255 offset:13632
	ds_read_b32 v245, v255 offset:13648
	ds_read_b32 v246, v255 offset:13664
	ds_read_b32 v247, v255 offset:13680
	ds_read_b32 v248, v255 offset:13696
	ds_read_b32 v249, v255 offset:13712
	ds_read_b32 v250, v255 offset:13728
	ds_read_b32 v251, v255 offset:13744
	v_add_f32_e32 v73, v73, v90
	v_add_f32_e32 v74, v91, v92
	v_add_f32_e32 v73, v73, v74
	v_sub_f32_e32 v72, v72, v73
	v_lshlrev_b32_e32 v73, 16, v238
	v_mul_f32_e32 v73, v239, v73
	s_and_saveexec_b64 s[0:1], s[16:17]
	s_cbranch_execz .LBB0_911
	v_mul_f32_e32 v73, v73, v254
.LBB0_911:
	s_or_b64 exec, exec, s[0:1]
	ds_read_u16 v238, v18 offset:14688
	ds_read_b32 v239, v16 offset:216
	ds_read_b32 v254, v15 offset:216
	s_waitcnt lgkmcnt(14)
	v_mul_f32_dpp v90, v240, v2 quad_perm:[0,0,0,0] row_mask:0xf bank_mask:0xf
	v_mul_f32_dpp v91, v240, v3 quad_perm:[1,1,1,1] row_mask:0xf bank_mask:0xf
	v_mul_f32_dpp v92, v240, v4 quad_perm:[2,2,2,2] row_mask:0xf bank_mask:0xf
	v_mul_f32_dpp v93, v240, v5 quad_perm:[3,3,3,3] row_mask:0xf bank_mask:0xf
	ds_read_b32 v240, v255 offset:13760
	s_waitcnt lgkmcnt(14)
	v_fmac_f32_dpp v90, v241, v6 quad_perm:[0,0,0,0] row_mask:0xf bank_mask:0xf
	v_fmac_f32_dpp v91, v241, v7 quad_perm:[1,1,1,1] row_mask:0xf bank_mask:0xf
	v_fmac_f32_dpp v92, v241, v8 quad_perm:[2,2,2,2] row_mask:0xf bank_mask:0xf
	v_fmac_f32_dpp v93, v241, v9 quad_perm:[3,3,3,3] row_mask:0xf bank_mask:0xf
	ds_read_b32 v241, v255 offset:13776
	s_waitcnt lgkmcnt(14)
	v_fmac_f32_dpp v90, v242, v10 quad_perm:[0,0,0,0] row_mask:0xf bank_mask:0xf
	v_fmac_f32_dpp v91, v242, v12 quad_perm:[1,1,1,1] row_mask:0xf bank_mask:0xf
	v_fmac_f32_dpp v92, v242, v13 quad_perm:[2,2,2,2] row_mask:0xf bank_mask:0xf
	v_fmac_f32_dpp v93, v242, v14 quad_perm:[3,3,3,3] row_mask:0xf bank_mask:0xf
	s_waitcnt lgkmcnt(13)
	v_fmac_f32_dpp v90, v243, v17 quad_perm:[0,0,0,0] row_mask:0xf bank_mask:0xf
	v_fmac_f32_dpp v91, v243, v19 quad_perm:[1,1,1,1] row_mask:0xf bank_mask:0xf
	v_fmac_f32_dpp v92, v243, v28 quad_perm:[2,2,2,2] row_mask:0xf bank_mask:0xf
	v_fmac_f32_dpp v93, v243, v35 quad_perm:[3,3,3,3] row_mask:0xf bank_mask:0xf
	s_waitcnt lgkmcnt(12)
	v_fmac_f32_dpp v90, v244, v36 quad_perm:[0,0,0,0] row_mask:0xf bank_mask:0xf
	v_fmac_f32_dpp v91, v244, v37 quad_perm:[1,1,1,1] row_mask:0xf bank_mask:0xf
	v_fmac_f32_dpp v92, v244, v38 quad_perm:[2,2,2,2] row_mask:0xf bank_mask:0xf
	v_fmac_f32_dpp v93, v244, v39 quad_perm:[3,3,3,3] row_mask:0xf bank_mask:0xf
	s_waitcnt lgkmcnt(11)
	v_fmac_f32_dpp v90, v245, v40 quad_perm:[0,0,0,0] row_mask:0xf bank_mask:0xf
	v_fmac_f32_dpp v91, v245, v41 quad_perm:[1,1,1,1] row_mask:0xf bank_mask:0xf
	v_fmac_f32_dpp v92, v245, v42 quad_perm:[2,2,2,2] row_mask:0xf bank_mask:0xf
	v_fmac_f32_dpp v93, v245, v43 quad_perm:[3,3,3,3] row_mask:0xf bank_mask:0xf
	s_waitcnt lgkmcnt(10)
	v_fmac_f32_dpp v90, v246, v44 quad_perm:[0,0,0,0] row_mask:0xf bank_mask:0xf
	v_fmac_f32_dpp v91, v246, v45 quad_perm:[1,1,1,1] row_mask:0xf bank_mask:0xf
	v_fmac_f32_dpp v92, v246, v46 quad_perm:[2,2,2,2] row_mask:0xf bank_mask:0xf
	v_fmac_f32_dpp v93, v246, v47 quad_perm:[3,3,3,3] row_mask:0xf bank_mask:0xf
	s_waitcnt lgkmcnt(9)
	v_fmac_f32_dpp v90, v247, v48 quad_perm:[0,0,0,0] row_mask:0xf bank_mask:0xf
	v_fmac_f32_dpp v91, v247, v49 quad_perm:[1,1,1,1] row_mask:0xf bank_mask:0xf
	v_fmac_f32_dpp v92, v247, v50 quad_perm:[2,2,2,2] row_mask:0xf bank_mask:0xf
	v_fmac_f32_dpp v93, v247, v51 quad_perm:[3,3,3,3] row_mask:0xf bank_mask:0xf
	s_waitcnt lgkmcnt(8)
	v_fmac_f32_dpp v90, v248, v52 quad_perm:[0,0,0,0] row_mask:0xf bank_mask:0xf
	v_fmac_f32_dpp v91, v248, v53 quad_perm:[1,1,1,1] row_mask:0xf bank_mask:0xf
	v_fmac_f32_dpp v92, v248, v54 quad_perm:[2,2,2,2] row_mask:0xf bank_mask:0xf
	v_fmac_f32_dpp v93, v248, v55 quad_perm:[3,3,3,3] row_mask:0xf bank_mask:0xf
	s_waitcnt lgkmcnt(7)
	v_fmac_f32_dpp v90, v249, v56 quad_perm:[0,0,0,0] row_mask:0xf bank_mask:0xf
	v_fmac_f32_dpp v91, v249, v57 quad_perm:[1,1,1,1] row_mask:0xf bank_mask:0xf
	v_fmac_f32_dpp v92, v249, v58 quad_perm:[2,2,2,2] row_mask:0xf bank_mask:0xf
	v_fmac_f32_dpp v93, v249, v59 quad_perm:[3,3,3,3] row_mask:0xf bank_mask:0xf
	s_waitcnt lgkmcnt(6)
	v_fmac_f32_dpp v90, v250, v60 quad_perm:[0,0,0,0] row_mask:0xf bank_mask:0xf
	v_fmac_f32_dpp v91, v250, v61 quad_perm:[1,1,1,1] row_mask:0xf bank_mask:0xf
	v_fmac_f32_dpp v92, v250, v62 quad_perm:[2,2,2,2] row_mask:0xf bank_mask:0xf
	v_fmac_f32_dpp v93, v250, v63 quad_perm:[3,3,3,3] row_mask:0xf bank_mask:0xf
	s_waitcnt lgkmcnt(5)
	v_fmac_f32_dpp v90, v251, v64 quad_perm:[0,0,0,0] row_mask:0xf bank_mask:0xf
	v_fmac_f32_dpp v91, v251, v65 quad_perm:[1,1,1,1] row_mask:0xf bank_mask:0xf
	v_fmac_f32_dpp v92, v251, v66 quad_perm:[2,2,2,2] row_mask:0xf bank_mask:0xf
	v_fmac_f32_dpp v93, v251, v67 quad_perm:[3,3,3,3] row_mask:0xf bank_mask:0xf
	s_waitcnt lgkmcnt(1)
	v_fmac_f32_dpp v90, v240, v68 quad_perm:[0,0,0,0] row_mask:0xf bank_mask:0xf
	v_fmac_f32_dpp v91, v240, v69 quad_perm:[1,1,1,1] row_mask:0xf bank_mask:0xf
	v_fmac_f32_dpp v92, v240, v70 quad_perm:[2,2,2,2] row_mask:0xf bank_mask:0xf
	v_fmac_f32_dpp v93, v240, v71 quad_perm:[3,3,3,3] row_mask:0xf bank_mask:0xf
	s_waitcnt lgkmcnt(0)
	v_fmac_f32_dpp v90, v241, v72 quad_perm:[0,0,0,0] row_mask:0xf bank_mask:0xf
	ds_read_b32 v240, v255 offset:13824
	ds_read_b32 v241, v255 offset:13840
	ds_read_b32 v242, v255 offset:13856
	ds_read_b32 v243, v255 offset:13872
	ds_read_b32 v244, v255 offset:13888
	ds_read_b32 v245, v255 offset:13904
	ds_read_b32 v246, v255 offset:13920
	ds_read_b32 v247, v255 offset:13936
	ds_read_b32 v248, v255 offset:13952
	ds_read_b32 v249, v255 offset:13968
	ds_read_b32 v250, v255 offset:13984
	ds_read_b32 v251, v255 offset:14000
	v_add_f32_e32 v74, v91, v90
	v_add_f32_e32 v75, v92, v93
	v_add_f32_e32 v74, v75, v74
	v_sub_f32_e32 v73, v73, v74
	v_lshlrev_b32_e32 v74, 16, v238
	v_mul_f32_e32 v74, v239, v74
	s_and_saveexec_b64 s[0:1], s[16:17]
	s_cbranch_execz .LBB0_913
	v_mul_f32_e32 v74, v74, v254
.LBB0_913:
	s_or_b64 exec, exec, s[0:1]
	ds_read_u16 v238, v18 offset:14960
	ds_read_b32 v239, v16 offset:220
	ds_read_b32 v254, v15 offset:220
	s_waitcnt lgkmcnt(14)
	v_mul_f32_dpp v75, v240, v2 quad_perm:[0,0,0,0] row_mask:0xf bank_mask:0xf
	v_mul_f32_dpp v92, v240, v3 quad_perm:[1,1,1,1] row_mask:0xf bank_mask:0xf
	v_mul_f32_dpp v93, v240, v4 quad_perm:[2,2,2,2] row_mask:0xf bank_mask:0xf
	v_mul_f32_dpp v94, v240, v5 quad_perm:[3,3,3,3] row_mask:0xf bank_mask:0xf
	ds_read_b32 v240, v255 offset:14016
	s_waitcnt lgkmcnt(14)
	v_fmac_f32_dpp v75, v241, v6 quad_perm:[0,0,0,0] row_mask:0xf bank_mask:0xf
	v_fmac_f32_dpp v92, v241, v7 quad_perm:[1,1,1,1] row_mask:0xf bank_mask:0xf
	v_fmac_f32_dpp v93, v241, v8 quad_perm:[2,2,2,2] row_mask:0xf bank_mask:0xf
	v_fmac_f32_dpp v94, v241, v9 quad_perm:[3,3,3,3] row_mask:0xf bank_mask:0xf
	ds_read_b32 v241, v255 offset:14032
	s_waitcnt lgkmcnt(14)
	v_fmac_f32_dpp v75, v242, v10 quad_perm:[0,0,0,0] row_mask:0xf bank_mask:0xf
	v_fmac_f32_dpp v92, v242, v12 quad_perm:[1,1,1,1] row_mask:0xf bank_mask:0xf
	v_fmac_f32_dpp v93, v242, v13 quad_perm:[2,2,2,2] row_mask:0xf bank_mask:0xf
	v_fmac_f32_dpp v94, v242, v14 quad_perm:[3,3,3,3] row_mask:0xf bank_mask:0xf
	s_waitcnt lgkmcnt(13)
	v_fmac_f32_dpp v75, v243, v17 quad_perm:[0,0,0,0] row_mask:0xf bank_mask:0xf
	v_fmac_f32_dpp v92, v243, v19 quad_perm:[1,1,1,1] row_mask:0xf bank_mask:0xf
	v_fmac_f32_dpp v93, v243, v28 quad_perm:[2,2,2,2] row_mask:0xf bank_mask:0xf
	v_fmac_f32_dpp v94, v243, v35 quad_perm:[3,3,3,3] row_mask:0xf bank_mask:0xf
	s_waitcnt lgkmcnt(12)
	v_fmac_f32_dpp v75, v244, v36 quad_perm:[0,0,0,0] row_mask:0xf bank_mask:0xf
	v_fmac_f32_dpp v92, v244, v37 quad_perm:[1,1,1,1] row_mask:0xf bank_mask:0xf
	v_fmac_f32_dpp v93, v244, v38 quad_perm:[2,2,2,2] row_mask:0xf bank_mask:0xf
	v_fmac_f32_dpp v94, v244, v39 quad_perm:[3,3,3,3] row_mask:0xf bank_mask:0xf
	s_waitcnt lgkmcnt(11)
	v_fmac_f32_dpp v75, v245, v40 quad_perm:[0,0,0,0] row_mask:0xf bank_mask:0xf
	v_fmac_f32_dpp v92, v245, v41 quad_perm:[1,1,1,1] row_mask:0xf bank_mask:0xf
	v_fmac_f32_dpp v93, v245, v42 quad_perm:[2,2,2,2] row_mask:0xf bank_mask:0xf
	v_fmac_f32_dpp v94, v245, v43 quad_perm:[3,3,3,3] row_mask:0xf bank_mask:0xf
	s_waitcnt lgkmcnt(10)
	v_fmac_f32_dpp v75, v246, v44 quad_perm:[0,0,0,0] row_mask:0xf bank_mask:0xf
	v_fmac_f32_dpp v92, v246, v45 quad_perm:[1,1,1,1] row_mask:0xf bank_mask:0xf
	v_fmac_f32_dpp v93, v246, v46 quad_perm:[2,2,2,2] row_mask:0xf bank_mask:0xf
	v_fmac_f32_dpp v94, v246, v47 quad_perm:[3,3,3,3] row_mask:0xf bank_mask:0xf
	s_waitcnt lgkmcnt(9)
	v_fmac_f32_dpp v75, v247, v48 quad_perm:[0,0,0,0] row_mask:0xf bank_mask:0xf
	v_fmac_f32_dpp v92, v247, v49 quad_perm:[1,1,1,1] row_mask:0xf bank_mask:0xf
	v_fmac_f32_dpp v93, v247, v50 quad_perm:[2,2,2,2] row_mask:0xf bank_mask:0xf
	v_fmac_f32_dpp v94, v247, v51 quad_perm:[3,3,3,3] row_mask:0xf bank_mask:0xf
	s_waitcnt lgkmcnt(8)
	v_fmac_f32_dpp v75, v248, v52 quad_perm:[0,0,0,0] row_mask:0xf bank_mask:0xf
	v_fmac_f32_dpp v92, v248, v53 quad_perm:[1,1,1,1] row_mask:0xf bank_mask:0xf
	v_fmac_f32_dpp v93, v248, v54 quad_perm:[2,2,2,2] row_mask:0xf bank_mask:0xf
	v_fmac_f32_dpp v94, v248, v55 quad_perm:[3,3,3,3] row_mask:0xf bank_mask:0xf
	s_waitcnt lgkmcnt(7)
	v_fmac_f32_dpp v75, v249, v56 quad_perm:[0,0,0,0] row_mask:0xf bank_mask:0xf
	v_fmac_f32_dpp v92, v249, v57 quad_perm:[1,1,1,1] row_mask:0xf bank_mask:0xf
	v_fmac_f32_dpp v93, v249, v58 quad_perm:[2,2,2,2] row_mask:0xf bank_mask:0xf
	v_fmac_f32_dpp v94, v249, v59 quad_perm:[3,3,3,3] row_mask:0xf bank_mask:0xf
	s_waitcnt lgkmcnt(6)
	v_fmac_f32_dpp v75, v250, v60 quad_perm:[0,0,0,0] row_mask:0xf bank_mask:0xf
	v_fmac_f32_dpp v92, v250, v61 quad_perm:[1,1,1,1] row_mask:0xf bank_mask:0xf
	v_fmac_f32_dpp v93, v250, v62 quad_perm:[2,2,2,2] row_mask:0xf bank_mask:0xf
	v_fmac_f32_dpp v94, v250, v63 quad_perm:[3,3,3,3] row_mask:0xf bank_mask:0xf
	s_waitcnt lgkmcnt(5)
	v_fmac_f32_dpp v75, v251, v64 quad_perm:[0,0,0,0] row_mask:0xf bank_mask:0xf
	v_fmac_f32_dpp v92, v251, v65 quad_perm:[1,1,1,1] row_mask:0xf bank_mask:0xf
	v_fmac_f32_dpp v93, v251, v66 quad_perm:[2,2,2,2] row_mask:0xf bank_mask:0xf
	v_fmac_f32_dpp v94, v251, v67 quad_perm:[3,3,3,3] row_mask:0xf bank_mask:0xf
	s_waitcnt lgkmcnt(1)
	v_fmac_f32_dpp v75, v240, v68 quad_perm:[0,0,0,0] row_mask:0xf bank_mask:0xf
	v_fmac_f32_dpp v92, v240, v69 quad_perm:[1,1,1,1] row_mask:0xf bank_mask:0xf
	v_fmac_f32_dpp v93, v240, v70 quad_perm:[2,2,2,2] row_mask:0xf bank_mask:0xf
	v_fmac_f32_dpp v94, v240, v71 quad_perm:[3,3,3,3] row_mask:0xf bank_mask:0xf
	s_waitcnt lgkmcnt(0)
	v_fmac_f32_dpp v75, v241, v72 quad_perm:[0,0,0,0] row_mask:0xf bank_mask:0xf
	v_fmac_f32_dpp v92, v241, v73 quad_perm:[1,1,1,1] row_mask:0xf bank_mask:0xf
	ds_read_b32 v240, v255 offset:14080
	ds_read_b32 v241, v255 offset:14096
	ds_read_b32 v242, v255 offset:14112
	ds_read_b32 v243, v255 offset:14128
	ds_read_b32 v244, v255 offset:14144
	ds_read_b32 v245, v255 offset:14160
	ds_read_b32 v246, v255 offset:14176
	ds_read_b32 v247, v255 offset:14192
	ds_read_b32 v248, v255 offset:14208
	ds_read_b32 v249, v255 offset:14224
	ds_read_b32 v250, v255 offset:14240
	ds_read_b32 v251, v255 offset:14256
	v_add_f32_e32 v75, v75, v92
	v_add_f32_e32 v76, v93, v94
	v_add_f32_e32 v75, v76, v75
	v_sub_f32_e32 v74, v74, v75
	v_lshlrev_b32_e32 v75, 16, v238
	v_mul_f32_e32 v75, v239, v75
	s_and_saveexec_b64 s[0:1], s[16:17]
	s_cbranch_execz .LBB0_915
	v_mul_f32_e32 v75, v75, v254
.LBB0_915:
	s_or_b64 exec, exec, s[0:1]
	ds_read_u16 v238, v18 offset:15232
	ds_read_b32 v239, v16 offset:224
	ds_read_b32 v254, v15 offset:224
	s_waitcnt lgkmcnt(14)
	v_mul_f32_dpp v92, v240, v2 quad_perm:[0,0,0,0] row_mask:0xf bank_mask:0xf
	v_mul_f32_dpp v93, v240, v3 quad_perm:[1,1,1,1] row_mask:0xf bank_mask:0xf
	v_mul_f32_dpp v94, v240, v4 quad_perm:[2,2,2,2] row_mask:0xf bank_mask:0xf
	v_mul_f32_dpp v95, v240, v5 quad_perm:[3,3,3,3] row_mask:0xf bank_mask:0xf
	ds_read_b32 v240, v255 offset:14272
	s_waitcnt lgkmcnt(14)
	v_fmac_f32_dpp v92, v241, v6 quad_perm:[0,0,0,0] row_mask:0xf bank_mask:0xf
	v_fmac_f32_dpp v93, v241, v7 quad_perm:[1,1,1,1] row_mask:0xf bank_mask:0xf
	v_fmac_f32_dpp v94, v241, v8 quad_perm:[2,2,2,2] row_mask:0xf bank_mask:0xf
	v_fmac_f32_dpp v95, v241, v9 quad_perm:[3,3,3,3] row_mask:0xf bank_mask:0xf
	ds_read_b32 v241, v255 offset:14288
	s_waitcnt lgkmcnt(14)
	v_fmac_f32_dpp v92, v242, v10 quad_perm:[0,0,0,0] row_mask:0xf bank_mask:0xf
	v_fmac_f32_dpp v93, v242, v12 quad_perm:[1,1,1,1] row_mask:0xf bank_mask:0xf
	v_fmac_f32_dpp v94, v242, v13 quad_perm:[2,2,2,2] row_mask:0xf bank_mask:0xf
	v_fmac_f32_dpp v95, v242, v14 quad_perm:[3,3,3,3] row_mask:0xf bank_mask:0xf
	s_waitcnt lgkmcnt(13)
	v_fmac_f32_dpp v92, v243, v17 quad_perm:[0,0,0,0] row_mask:0xf bank_mask:0xf
	v_fmac_f32_dpp v93, v243, v19 quad_perm:[1,1,1,1] row_mask:0xf bank_mask:0xf
	v_fmac_f32_dpp v94, v243, v28 quad_perm:[2,2,2,2] row_mask:0xf bank_mask:0xf
	v_fmac_f32_dpp v95, v243, v35 quad_perm:[3,3,3,3] row_mask:0xf bank_mask:0xf
	s_waitcnt lgkmcnt(12)
	v_fmac_f32_dpp v92, v244, v36 quad_perm:[0,0,0,0] row_mask:0xf bank_mask:0xf
	v_fmac_f32_dpp v93, v244, v37 quad_perm:[1,1,1,1] row_mask:0xf bank_mask:0xf
	v_fmac_f32_dpp v94, v244, v38 quad_perm:[2,2,2,2] row_mask:0xf bank_mask:0xf
	v_fmac_f32_dpp v95, v244, v39 quad_perm:[3,3,3,3] row_mask:0xf bank_mask:0xf
	s_waitcnt lgkmcnt(11)
	v_fmac_f32_dpp v92, v245, v40 quad_perm:[0,0,0,0] row_mask:0xf bank_mask:0xf
	v_fmac_f32_dpp v93, v245, v41 quad_perm:[1,1,1,1] row_mask:0xf bank_mask:0xf
	v_fmac_f32_dpp v94, v245, v42 quad_perm:[2,2,2,2] row_mask:0xf bank_mask:0xf
	v_fmac_f32_dpp v95, v245, v43 quad_perm:[3,3,3,3] row_mask:0xf bank_mask:0xf
	s_waitcnt lgkmcnt(10)
	v_fmac_f32_dpp v92, v246, v44 quad_perm:[0,0,0,0] row_mask:0xf bank_mask:0xf
	v_fmac_f32_dpp v93, v246, v45 quad_perm:[1,1,1,1] row_mask:0xf bank_mask:0xf
	v_fmac_f32_dpp v94, v246, v46 quad_perm:[2,2,2,2] row_mask:0xf bank_mask:0xf
	v_fmac_f32_dpp v95, v246, v47 quad_perm:[3,3,3,3] row_mask:0xf bank_mask:0xf
	s_waitcnt lgkmcnt(9)
	v_fmac_f32_dpp v92, v247, v48 quad_perm:[0,0,0,0] row_mask:0xf bank_mask:0xf
	v_fmac_f32_dpp v93, v247, v49 quad_perm:[1,1,1,1] row_mask:0xf bank_mask:0xf
	v_fmac_f32_dpp v94, v247, v50 quad_perm:[2,2,2,2] row_mask:0xf bank_mask:0xf
	v_fmac_f32_dpp v95, v247, v51 quad_perm:[3,3,3,3] row_mask:0xf bank_mask:0xf
	s_waitcnt lgkmcnt(8)
	v_fmac_f32_dpp v92, v248, v52 quad_perm:[0,0,0,0] row_mask:0xf bank_mask:0xf
	v_fmac_f32_dpp v93, v248, v53 quad_perm:[1,1,1,1] row_mask:0xf bank_mask:0xf
	v_fmac_f32_dpp v94, v248, v54 quad_perm:[2,2,2,2] row_mask:0xf bank_mask:0xf
	v_fmac_f32_dpp v95, v248, v55 quad_perm:[3,3,3,3] row_mask:0xf bank_mask:0xf
	s_waitcnt lgkmcnt(7)
	v_fmac_f32_dpp v92, v249, v56 quad_perm:[0,0,0,0] row_mask:0xf bank_mask:0xf
	v_fmac_f32_dpp v93, v249, v57 quad_perm:[1,1,1,1] row_mask:0xf bank_mask:0xf
	v_fmac_f32_dpp v94, v249, v58 quad_perm:[2,2,2,2] row_mask:0xf bank_mask:0xf
	v_fmac_f32_dpp v95, v249, v59 quad_perm:[3,3,3,3] row_mask:0xf bank_mask:0xf
	s_waitcnt lgkmcnt(6)
	v_fmac_f32_dpp v92, v250, v60 quad_perm:[0,0,0,0] row_mask:0xf bank_mask:0xf
	v_fmac_f32_dpp v93, v250, v61 quad_perm:[1,1,1,1] row_mask:0xf bank_mask:0xf
	v_fmac_f32_dpp v94, v250, v62 quad_perm:[2,2,2,2] row_mask:0xf bank_mask:0xf
	v_fmac_f32_dpp v95, v250, v63 quad_perm:[3,3,3,3] row_mask:0xf bank_mask:0xf
	s_waitcnt lgkmcnt(5)
	v_fmac_f32_dpp v92, v251, v64 quad_perm:[0,0,0,0] row_mask:0xf bank_mask:0xf
	v_fmac_f32_dpp v93, v251, v65 quad_perm:[1,1,1,1] row_mask:0xf bank_mask:0xf
	v_fmac_f32_dpp v94, v251, v66 quad_perm:[2,2,2,2] row_mask:0xf bank_mask:0xf
	v_fmac_f32_dpp v95, v251, v67 quad_perm:[3,3,3,3] row_mask:0xf bank_mask:0xf
	s_waitcnt lgkmcnt(1)
	v_fmac_f32_dpp v92, v240, v68 quad_perm:[0,0,0,0] row_mask:0xf bank_mask:0xf
	v_fmac_f32_dpp v93, v240, v69 quad_perm:[1,1,1,1] row_mask:0xf bank_mask:0xf
	v_fmac_f32_dpp v94, v240, v70 quad_perm:[2,2,2,2] row_mask:0xf bank_mask:0xf
	v_fmac_f32_dpp v95, v240, v71 quad_perm:[3,3,3,3] row_mask:0xf bank_mask:0xf
	s_waitcnt lgkmcnt(0)
	v_fmac_f32_dpp v92, v241, v72 quad_perm:[0,0,0,0] row_mask:0xf bank_mask:0xf
	v_fmac_f32_dpp v93, v241, v73 quad_perm:[1,1,1,1] row_mask:0xf bank_mask:0xf
	v_fmac_f32_dpp v94, v241, v74 quad_perm:[2,2,2,2] row_mask:0xf bank_mask:0xf
	ds_read_b32 v240, v255 offset:14336
	ds_read_b32 v241, v255 offset:14352
	ds_read_b32 v242, v255 offset:14368
	ds_read_b32 v243, v255 offset:14384
	ds_read_b32 v244, v255 offset:14400
	ds_read_b32 v245, v255 offset:14416
	ds_read_b32 v246, v255 offset:14432
	ds_read_b32 v247, v255 offset:14448
	ds_read_b32 v248, v255 offset:14464
	ds_read_b32 v249, v255 offset:14480
	ds_read_b32 v250, v255 offset:14496
	ds_read_b32 v251, v255 offset:14512
	v_add_f32_e32 v76, v92, v93
	v_add_f32_e32 v77, v95, v94
	v_add_f32_e32 v76, v76, v77
	v_sub_f32_e32 v75, v75, v76
	v_lshlrev_b32_e32 v76, 16, v238
	v_mul_f32_e32 v76, v239, v76
	s_and_saveexec_b64 s[0:1], s[16:17]
	s_cbranch_execz .LBB0_917
	v_mul_f32_e32 v76, v76, v254
.LBB0_917:
	s_or_b64 exec, exec, s[0:1]
	ds_read_u16 v238, v18 offset:15504
	ds_read_b32 v239, v16 offset:228
	ds_read_b32 v254, v15 offset:228
	s_waitcnt lgkmcnt(14)
	v_mul_f32_dpp v77, v240, v2 quad_perm:[0,0,0,0] row_mask:0xf bank_mask:0xf
	v_mul_f32_dpp v94, v240, v3 quad_perm:[1,1,1,1] row_mask:0xf bank_mask:0xf
	v_mul_f32_dpp v95, v240, v4 quad_perm:[2,2,2,2] row_mask:0xf bank_mask:0xf
	v_mul_f32_dpp v96, v240, v5 quad_perm:[3,3,3,3] row_mask:0xf bank_mask:0xf
	ds_read_b32 v240, v255 offset:14528
	s_waitcnt lgkmcnt(14)
	v_fmac_f32_dpp v77, v241, v6 quad_perm:[0,0,0,0] row_mask:0xf bank_mask:0xf
	v_fmac_f32_dpp v94, v241, v7 quad_perm:[1,1,1,1] row_mask:0xf bank_mask:0xf
	v_fmac_f32_dpp v95, v241, v8 quad_perm:[2,2,2,2] row_mask:0xf bank_mask:0xf
	v_fmac_f32_dpp v96, v241, v9 quad_perm:[3,3,3,3] row_mask:0xf bank_mask:0xf
	ds_read_b32 v241, v255 offset:14544
	s_waitcnt lgkmcnt(14)
	v_fmac_f32_dpp v77, v242, v10 quad_perm:[0,0,0,0] row_mask:0xf bank_mask:0xf
	v_fmac_f32_dpp v94, v242, v12 quad_perm:[1,1,1,1] row_mask:0xf bank_mask:0xf
	v_fmac_f32_dpp v95, v242, v13 quad_perm:[2,2,2,2] row_mask:0xf bank_mask:0xf
	v_fmac_f32_dpp v96, v242, v14 quad_perm:[3,3,3,3] row_mask:0xf bank_mask:0xf
	s_waitcnt lgkmcnt(13)
	v_fmac_f32_dpp v77, v243, v17 quad_perm:[0,0,0,0] row_mask:0xf bank_mask:0xf
	v_fmac_f32_dpp v94, v243, v19 quad_perm:[1,1,1,1] row_mask:0xf bank_mask:0xf
	v_fmac_f32_dpp v95, v243, v28 quad_perm:[2,2,2,2] row_mask:0xf bank_mask:0xf
	v_fmac_f32_dpp v96, v243, v35 quad_perm:[3,3,3,3] row_mask:0xf bank_mask:0xf
	s_waitcnt lgkmcnt(12)
	v_fmac_f32_dpp v77, v244, v36 quad_perm:[0,0,0,0] row_mask:0xf bank_mask:0xf
	v_fmac_f32_dpp v94, v244, v37 quad_perm:[1,1,1,1] row_mask:0xf bank_mask:0xf
	v_fmac_f32_dpp v95, v244, v38 quad_perm:[2,2,2,2] row_mask:0xf bank_mask:0xf
	v_fmac_f32_dpp v96, v244, v39 quad_perm:[3,3,3,3] row_mask:0xf bank_mask:0xf
	s_waitcnt lgkmcnt(11)
	v_fmac_f32_dpp v77, v245, v40 quad_perm:[0,0,0,0] row_mask:0xf bank_mask:0xf
	v_fmac_f32_dpp v94, v245, v41 quad_perm:[1,1,1,1] row_mask:0xf bank_mask:0xf
	v_fmac_f32_dpp v95, v245, v42 quad_perm:[2,2,2,2] row_mask:0xf bank_mask:0xf
	v_fmac_f32_dpp v96, v245, v43 quad_perm:[3,3,3,3] row_mask:0xf bank_mask:0xf
	s_waitcnt lgkmcnt(10)
	v_fmac_f32_dpp v77, v246, v44 quad_perm:[0,0,0,0] row_mask:0xf bank_mask:0xf
	v_fmac_f32_dpp v94, v246, v45 quad_perm:[1,1,1,1] row_mask:0xf bank_mask:0xf
	v_fmac_f32_dpp v95, v246, v46 quad_perm:[2,2,2,2] row_mask:0xf bank_mask:0xf
	v_fmac_f32_dpp v96, v246, v47 quad_perm:[3,3,3,3] row_mask:0xf bank_mask:0xf
	s_waitcnt lgkmcnt(9)
	v_fmac_f32_dpp v77, v247, v48 quad_perm:[0,0,0,0] row_mask:0xf bank_mask:0xf
	v_fmac_f32_dpp v94, v247, v49 quad_perm:[1,1,1,1] row_mask:0xf bank_mask:0xf
	v_fmac_f32_dpp v95, v247, v50 quad_perm:[2,2,2,2] row_mask:0xf bank_mask:0xf
	v_fmac_f32_dpp v96, v247, v51 quad_perm:[3,3,3,3] row_mask:0xf bank_mask:0xf
	s_waitcnt lgkmcnt(8)
	v_fmac_f32_dpp v77, v248, v52 quad_perm:[0,0,0,0] row_mask:0xf bank_mask:0xf
	v_fmac_f32_dpp v94, v248, v53 quad_perm:[1,1,1,1] row_mask:0xf bank_mask:0xf
	v_fmac_f32_dpp v95, v248, v54 quad_perm:[2,2,2,2] row_mask:0xf bank_mask:0xf
	v_fmac_f32_dpp v96, v248, v55 quad_perm:[3,3,3,3] row_mask:0xf bank_mask:0xf
	s_waitcnt lgkmcnt(7)
	v_fmac_f32_dpp v77, v249, v56 quad_perm:[0,0,0,0] row_mask:0xf bank_mask:0xf
	v_fmac_f32_dpp v94, v249, v57 quad_perm:[1,1,1,1] row_mask:0xf bank_mask:0xf
	v_fmac_f32_dpp v95, v249, v58 quad_perm:[2,2,2,2] row_mask:0xf bank_mask:0xf
	v_fmac_f32_dpp v96, v249, v59 quad_perm:[3,3,3,3] row_mask:0xf bank_mask:0xf
	s_waitcnt lgkmcnt(6)
	v_fmac_f32_dpp v77, v250, v60 quad_perm:[0,0,0,0] row_mask:0xf bank_mask:0xf
	v_fmac_f32_dpp v94, v250, v61 quad_perm:[1,1,1,1] row_mask:0xf bank_mask:0xf
	v_fmac_f32_dpp v95, v250, v62 quad_perm:[2,2,2,2] row_mask:0xf bank_mask:0xf
	v_fmac_f32_dpp v96, v250, v63 quad_perm:[3,3,3,3] row_mask:0xf bank_mask:0xf
	s_waitcnt lgkmcnt(5)
	v_fmac_f32_dpp v77, v251, v64 quad_perm:[0,0,0,0] row_mask:0xf bank_mask:0xf
	v_fmac_f32_dpp v94, v251, v65 quad_perm:[1,1,1,1] row_mask:0xf bank_mask:0xf
	v_fmac_f32_dpp v95, v251, v66 quad_perm:[2,2,2,2] row_mask:0xf bank_mask:0xf
	v_fmac_f32_dpp v96, v251, v67 quad_perm:[3,3,3,3] row_mask:0xf bank_mask:0xf
	s_waitcnt lgkmcnt(1)
	v_fmac_f32_dpp v77, v240, v68 quad_perm:[0,0,0,0] row_mask:0xf bank_mask:0xf
	v_fmac_f32_dpp v94, v240, v69 quad_perm:[1,1,1,1] row_mask:0xf bank_mask:0xf
	v_fmac_f32_dpp v95, v240, v70 quad_perm:[2,2,2,2] row_mask:0xf bank_mask:0xf
	v_fmac_f32_dpp v96, v240, v71 quad_perm:[3,3,3,3] row_mask:0xf bank_mask:0xf
	s_waitcnt lgkmcnt(0)
	v_fmac_f32_dpp v77, v241, v72 quad_perm:[0,0,0,0] row_mask:0xf bank_mask:0xf
	v_fmac_f32_dpp v94, v241, v73 quad_perm:[1,1,1,1] row_mask:0xf bank_mask:0xf
	v_fmac_f32_dpp v95, v241, v74 quad_perm:[2,2,2,2] row_mask:0xf bank_mask:0xf
	v_fmac_f32_dpp v96, v241, v75 quad_perm:[3,3,3,3] row_mask:0xf bank_mask:0xf
	ds_read_b32 v240, v255 offset:14592
	ds_read_b32 v241, v255 offset:14608
	ds_read_b32 v242, v255 offset:14624
	ds_read_b32 v243, v255 offset:14640
	ds_read_b32 v244, v255 offset:14656
	ds_read_b32 v245, v255 offset:14672
	ds_read_b32 v246, v255 offset:14688
	ds_read_b32 v247, v255 offset:14704
	ds_read_b32 v248, v255 offset:14720
	ds_read_b32 v249, v255 offset:14736
	ds_read_b32 v250, v255 offset:14752
	ds_read_b32 v251, v255 offset:14768
	v_add_f32_e32 v77, v77, v94
	v_add_f32_e32 v78, v95, v96
	v_add_f32_e32 v77, v77, v78
	v_sub_f32_e32 v76, v76, v77
	v_lshlrev_b32_e32 v77, 16, v238
	v_mul_f32_e32 v77, v239, v77
	s_and_saveexec_b64 s[0:1], s[16:17]
	s_cbranch_execz .LBB0_919
	v_mul_f32_e32 v77, v77, v254
.LBB0_919:
	s_or_b64 exec, exec, s[0:1]
	ds_read_u16 v238, v18 offset:15776
	ds_read_b32 v239, v16 offset:232
	ds_read_b32 v254, v15 offset:232
	s_waitcnt lgkmcnt(14)
	v_mul_f32_dpp v94, v240, v2 quad_perm:[0,0,0,0] row_mask:0xf bank_mask:0xf
	v_mul_f32_dpp v95, v240, v3 quad_perm:[1,1,1,1] row_mask:0xf bank_mask:0xf
	v_mul_f32_dpp v96, v240, v4 quad_perm:[2,2,2,2] row_mask:0xf bank_mask:0xf
	v_mul_f32_dpp v97, v240, v5 quad_perm:[3,3,3,3] row_mask:0xf bank_mask:0xf
	ds_read_b32 v240, v255 offset:14784
	s_waitcnt lgkmcnt(14)
	v_fmac_f32_dpp v94, v241, v6 quad_perm:[0,0,0,0] row_mask:0xf bank_mask:0xf
	v_fmac_f32_dpp v95, v241, v7 quad_perm:[1,1,1,1] row_mask:0xf bank_mask:0xf
	v_fmac_f32_dpp v96, v241, v8 quad_perm:[2,2,2,2] row_mask:0xf bank_mask:0xf
	v_fmac_f32_dpp v97, v241, v9 quad_perm:[3,3,3,3] row_mask:0xf bank_mask:0xf
	ds_read_b32 v241, v255 offset:14800
	s_waitcnt lgkmcnt(14)
	v_fmac_f32_dpp v94, v242, v10 quad_perm:[0,0,0,0] row_mask:0xf bank_mask:0xf
	v_fmac_f32_dpp v95, v242, v12 quad_perm:[1,1,1,1] row_mask:0xf bank_mask:0xf
	v_fmac_f32_dpp v96, v242, v13 quad_perm:[2,2,2,2] row_mask:0xf bank_mask:0xf
	v_fmac_f32_dpp v97, v242, v14 quad_perm:[3,3,3,3] row_mask:0xf bank_mask:0xf
	ds_read_b32 v242, v255 offset:14816
	s_waitcnt lgkmcnt(14)
	v_fmac_f32_dpp v94, v243, v17 quad_perm:[0,0,0,0] row_mask:0xf bank_mask:0xf
	v_fmac_f32_dpp v95, v243, v19 quad_perm:[1,1,1,1] row_mask:0xf bank_mask:0xf
	v_fmac_f32_dpp v96, v243, v28 quad_perm:[2,2,2,2] row_mask:0xf bank_mask:0xf
	v_fmac_f32_dpp v97, v243, v35 quad_perm:[3,3,3,3] row_mask:0xf bank_mask:0xf
	s_waitcnt lgkmcnt(13)
	v_fmac_f32_dpp v94, v244, v36 quad_perm:[0,0,0,0] row_mask:0xf bank_mask:0xf
	v_fmac_f32_dpp v95, v244, v37 quad_perm:[1,1,1,1] row_mask:0xf bank_mask:0xf
	v_fmac_f32_dpp v96, v244, v38 quad_perm:[2,2,2,2] row_mask:0xf bank_mask:0xf
	v_fmac_f32_dpp v97, v244, v39 quad_perm:[3,3,3,3] row_mask:0xf bank_mask:0xf
	s_waitcnt lgkmcnt(12)
	v_fmac_f32_dpp v94, v245, v40 quad_perm:[0,0,0,0] row_mask:0xf bank_mask:0xf
	v_fmac_f32_dpp v95, v245, v41 quad_perm:[1,1,1,1] row_mask:0xf bank_mask:0xf
	v_fmac_f32_dpp v96, v245, v42 quad_perm:[2,2,2,2] row_mask:0xf bank_mask:0xf
	v_fmac_f32_dpp v97, v245, v43 quad_perm:[3,3,3,3] row_mask:0xf bank_mask:0xf
	s_waitcnt lgkmcnt(11)
	v_fmac_f32_dpp v94, v246, v44 quad_perm:[0,0,0,0] row_mask:0xf bank_mask:0xf
	v_fmac_f32_dpp v95, v246, v45 quad_perm:[1,1,1,1] row_mask:0xf bank_mask:0xf
	v_fmac_f32_dpp v96, v246, v46 quad_perm:[2,2,2,2] row_mask:0xf bank_mask:0xf
	v_fmac_f32_dpp v97, v246, v47 quad_perm:[3,3,3,3] row_mask:0xf bank_mask:0xf
	s_waitcnt lgkmcnt(10)
	v_fmac_f32_dpp v94, v247, v48 quad_perm:[0,0,0,0] row_mask:0xf bank_mask:0xf
	v_fmac_f32_dpp v95, v247, v49 quad_perm:[1,1,1,1] row_mask:0xf bank_mask:0xf
	v_fmac_f32_dpp v96, v247, v50 quad_perm:[2,2,2,2] row_mask:0xf bank_mask:0xf
	v_fmac_f32_dpp v97, v247, v51 quad_perm:[3,3,3,3] row_mask:0xf bank_mask:0xf
	s_waitcnt lgkmcnt(9)
	v_fmac_f32_dpp v94, v248, v52 quad_perm:[0,0,0,0] row_mask:0xf bank_mask:0xf
	v_fmac_f32_dpp v95, v248, v53 quad_perm:[1,1,1,1] row_mask:0xf bank_mask:0xf
	v_fmac_f32_dpp v96, v248, v54 quad_perm:[2,2,2,2] row_mask:0xf bank_mask:0xf
	v_fmac_f32_dpp v97, v248, v55 quad_perm:[3,3,3,3] row_mask:0xf bank_mask:0xf
	s_waitcnt lgkmcnt(8)
	v_fmac_f32_dpp v94, v249, v56 quad_perm:[0,0,0,0] row_mask:0xf bank_mask:0xf
	v_fmac_f32_dpp v95, v249, v57 quad_perm:[1,1,1,1] row_mask:0xf bank_mask:0xf
	v_fmac_f32_dpp v96, v249, v58 quad_perm:[2,2,2,2] row_mask:0xf bank_mask:0xf
	v_fmac_f32_dpp v97, v249, v59 quad_perm:[3,3,3,3] row_mask:0xf bank_mask:0xf
	s_waitcnt lgkmcnt(7)
	v_fmac_f32_dpp v94, v250, v60 quad_perm:[0,0,0,0] row_mask:0xf bank_mask:0xf
	v_fmac_f32_dpp v95, v250, v61 quad_perm:[1,1,1,1] row_mask:0xf bank_mask:0xf
	v_fmac_f32_dpp v96, v250, v62 quad_perm:[2,2,2,2] row_mask:0xf bank_mask:0xf
	v_fmac_f32_dpp v97, v250, v63 quad_perm:[3,3,3,3] row_mask:0xf bank_mask:0xf
	s_waitcnt lgkmcnt(6)
	v_fmac_f32_dpp v94, v251, v64 quad_perm:[0,0,0,0] row_mask:0xf bank_mask:0xf
	v_fmac_f32_dpp v95, v251, v65 quad_perm:[1,1,1,1] row_mask:0xf bank_mask:0xf
	v_fmac_f32_dpp v96, v251, v66 quad_perm:[2,2,2,2] row_mask:0xf bank_mask:0xf
	v_fmac_f32_dpp v97, v251, v67 quad_perm:[3,3,3,3] row_mask:0xf bank_mask:0xf
	s_waitcnt lgkmcnt(2)
	v_fmac_f32_dpp v94, v240, v68 quad_perm:[0,0,0,0] row_mask:0xf bank_mask:0xf
	v_fmac_f32_dpp v95, v240, v69 quad_perm:[1,1,1,1] row_mask:0xf bank_mask:0xf
	v_fmac_f32_dpp v96, v240, v70 quad_perm:[2,2,2,2] row_mask:0xf bank_mask:0xf
	v_fmac_f32_dpp v97, v240, v71 quad_perm:[3,3,3,3] row_mask:0xf bank_mask:0xf
	s_waitcnt lgkmcnt(1)
	v_fmac_f32_dpp v94, v241, v72 quad_perm:[0,0,0,0] row_mask:0xf bank_mask:0xf
	v_fmac_f32_dpp v95, v241, v73 quad_perm:[1,1,1,1] row_mask:0xf bank_mask:0xf
	v_fmac_f32_dpp v96, v241, v74 quad_perm:[2,2,2,2] row_mask:0xf bank_mask:0xf
	v_fmac_f32_dpp v97, v241, v75 quad_perm:[3,3,3,3] row_mask:0xf bank_mask:0xf
	s_waitcnt lgkmcnt(0)
	v_fmac_f32_dpp v94, v242, v76 quad_perm:[0,0,0,0] row_mask:0xf bank_mask:0xf
	ds_read_b32 v240, v255 offset:14848
	ds_read_b32 v241, v255 offset:14864
	ds_read_b32 v242, v255 offset:14880
	ds_read_b32 v243, v255 offset:14896
	ds_read_b32 v244, v255 offset:14912
	ds_read_b32 v245, v255 offset:14928
	ds_read_b32 v246, v255 offset:14944
	ds_read_b32 v247, v255 offset:14960
	ds_read_b32 v248, v255 offset:14976
	ds_read_b32 v249, v255 offset:14992
	ds_read_b32 v250, v255 offset:15008
	ds_read_b32 v251, v255 offset:15024
	v_add_f32_e32 v78, v95, v94
	v_add_f32_e32 v79, v96, v97
	v_add_f32_e32 v78, v79, v78
	v_sub_f32_e32 v77, v77, v78
	v_lshlrev_b32_e32 v78, 16, v238
	v_mul_f32_e32 v78, v239, v78
	s_and_saveexec_b64 s[0:1], s[16:17]
	s_cbranch_execz .LBB0_921
	v_mul_f32_e32 v78, v78, v254
.LBB0_921:
	s_or_b64 exec, exec, s[0:1]
	ds_read_u16 v238, v18 offset:16048
	ds_read_b32 v239, v16 offset:236
	ds_read_b32 v254, v15 offset:236
	s_waitcnt lgkmcnt(14)
	v_mul_f32_dpp v79, v240, v2 quad_perm:[0,0,0,0] row_mask:0xf bank_mask:0xf
	v_mul_f32_dpp v96, v240, v3 quad_perm:[1,1,1,1] row_mask:0xf bank_mask:0xf
	v_mul_f32_dpp v97, v240, v4 quad_perm:[2,2,2,2] row_mask:0xf bank_mask:0xf
	v_mul_f32_dpp v98, v240, v5 quad_perm:[3,3,3,3] row_mask:0xf bank_mask:0xf
	ds_read_b32 v240, v255 offset:15040
	s_waitcnt lgkmcnt(14)
	v_fmac_f32_dpp v79, v241, v6 quad_perm:[0,0,0,0] row_mask:0xf bank_mask:0xf
	v_fmac_f32_dpp v96, v241, v7 quad_perm:[1,1,1,1] row_mask:0xf bank_mask:0xf
	v_fmac_f32_dpp v97, v241, v8 quad_perm:[2,2,2,2] row_mask:0xf bank_mask:0xf
	v_fmac_f32_dpp v98, v241, v9 quad_perm:[3,3,3,3] row_mask:0xf bank_mask:0xf
	ds_read_b32 v241, v255 offset:15056
	s_waitcnt lgkmcnt(14)
	v_fmac_f32_dpp v79, v242, v10 quad_perm:[0,0,0,0] row_mask:0xf bank_mask:0xf
	v_fmac_f32_dpp v96, v242, v12 quad_perm:[1,1,1,1] row_mask:0xf bank_mask:0xf
	v_fmac_f32_dpp v97, v242, v13 quad_perm:[2,2,2,2] row_mask:0xf bank_mask:0xf
	v_fmac_f32_dpp v98, v242, v14 quad_perm:[3,3,3,3] row_mask:0xf bank_mask:0xf
	ds_read_b32 v242, v255 offset:15072
	s_waitcnt lgkmcnt(14)
	v_fmac_f32_dpp v79, v243, v17 quad_perm:[0,0,0,0] row_mask:0xf bank_mask:0xf
	v_fmac_f32_dpp v96, v243, v19 quad_perm:[1,1,1,1] row_mask:0xf bank_mask:0xf
	v_fmac_f32_dpp v97, v243, v28 quad_perm:[2,2,2,2] row_mask:0xf bank_mask:0xf
	v_fmac_f32_dpp v98, v243, v35 quad_perm:[3,3,3,3] row_mask:0xf bank_mask:0xf
	s_waitcnt lgkmcnt(13)
	v_fmac_f32_dpp v79, v244, v36 quad_perm:[0,0,0,0] row_mask:0xf bank_mask:0xf
	v_fmac_f32_dpp v96, v244, v37 quad_perm:[1,1,1,1] row_mask:0xf bank_mask:0xf
	v_fmac_f32_dpp v97, v244, v38 quad_perm:[2,2,2,2] row_mask:0xf bank_mask:0xf
	v_fmac_f32_dpp v98, v244, v39 quad_perm:[3,3,3,3] row_mask:0xf bank_mask:0xf
	s_waitcnt lgkmcnt(12)
	v_fmac_f32_dpp v79, v245, v40 quad_perm:[0,0,0,0] row_mask:0xf bank_mask:0xf
	v_fmac_f32_dpp v96, v245, v41 quad_perm:[1,1,1,1] row_mask:0xf bank_mask:0xf
	v_fmac_f32_dpp v97, v245, v42 quad_perm:[2,2,2,2] row_mask:0xf bank_mask:0xf
	v_fmac_f32_dpp v98, v245, v43 quad_perm:[3,3,3,3] row_mask:0xf bank_mask:0xf
	s_waitcnt lgkmcnt(11)
	v_fmac_f32_dpp v79, v246, v44 quad_perm:[0,0,0,0] row_mask:0xf bank_mask:0xf
	v_fmac_f32_dpp v96, v246, v45 quad_perm:[1,1,1,1] row_mask:0xf bank_mask:0xf
	v_fmac_f32_dpp v97, v246, v46 quad_perm:[2,2,2,2] row_mask:0xf bank_mask:0xf
	v_fmac_f32_dpp v98, v246, v47 quad_perm:[3,3,3,3] row_mask:0xf bank_mask:0xf
	s_waitcnt lgkmcnt(10)
	v_fmac_f32_dpp v79, v247, v48 quad_perm:[0,0,0,0] row_mask:0xf bank_mask:0xf
	v_fmac_f32_dpp v96, v247, v49 quad_perm:[1,1,1,1] row_mask:0xf bank_mask:0xf
	v_fmac_f32_dpp v97, v247, v50 quad_perm:[2,2,2,2] row_mask:0xf bank_mask:0xf
	v_fmac_f32_dpp v98, v247, v51 quad_perm:[3,3,3,3] row_mask:0xf bank_mask:0xf
	s_waitcnt lgkmcnt(9)
	v_fmac_f32_dpp v79, v248, v52 quad_perm:[0,0,0,0] row_mask:0xf bank_mask:0xf
	v_fmac_f32_dpp v96, v248, v53 quad_perm:[1,1,1,1] row_mask:0xf bank_mask:0xf
	v_fmac_f32_dpp v97, v248, v54 quad_perm:[2,2,2,2] row_mask:0xf bank_mask:0xf
	v_fmac_f32_dpp v98, v248, v55 quad_perm:[3,3,3,3] row_mask:0xf bank_mask:0xf
	s_waitcnt lgkmcnt(8)
	v_fmac_f32_dpp v79, v249, v56 quad_perm:[0,0,0,0] row_mask:0xf bank_mask:0xf
	v_fmac_f32_dpp v96, v249, v57 quad_perm:[1,1,1,1] row_mask:0xf bank_mask:0xf
	v_fmac_f32_dpp v97, v249, v58 quad_perm:[2,2,2,2] row_mask:0xf bank_mask:0xf
	v_fmac_f32_dpp v98, v249, v59 quad_perm:[3,3,3,3] row_mask:0xf bank_mask:0xf
	s_waitcnt lgkmcnt(7)
	v_fmac_f32_dpp v79, v250, v60 quad_perm:[0,0,0,0] row_mask:0xf bank_mask:0xf
	v_fmac_f32_dpp v96, v250, v61 quad_perm:[1,1,1,1] row_mask:0xf bank_mask:0xf
	v_fmac_f32_dpp v97, v250, v62 quad_perm:[2,2,2,2] row_mask:0xf bank_mask:0xf
	v_fmac_f32_dpp v98, v250, v63 quad_perm:[3,3,3,3] row_mask:0xf bank_mask:0xf
	s_waitcnt lgkmcnt(6)
	v_fmac_f32_dpp v79, v251, v64 quad_perm:[0,0,0,0] row_mask:0xf bank_mask:0xf
	v_fmac_f32_dpp v96, v251, v65 quad_perm:[1,1,1,1] row_mask:0xf bank_mask:0xf
	v_fmac_f32_dpp v97, v251, v66 quad_perm:[2,2,2,2] row_mask:0xf bank_mask:0xf
	v_fmac_f32_dpp v98, v251, v67 quad_perm:[3,3,3,3] row_mask:0xf bank_mask:0xf
	s_waitcnt lgkmcnt(2)
	v_fmac_f32_dpp v79, v240, v68 quad_perm:[0,0,0,0] row_mask:0xf bank_mask:0xf
	v_fmac_f32_dpp v96, v240, v69 quad_perm:[1,1,1,1] row_mask:0xf bank_mask:0xf
	v_fmac_f32_dpp v97, v240, v70 quad_perm:[2,2,2,2] row_mask:0xf bank_mask:0xf
	v_fmac_f32_dpp v98, v240, v71 quad_perm:[3,3,3,3] row_mask:0xf bank_mask:0xf
	s_waitcnt lgkmcnt(1)
	v_fmac_f32_dpp v79, v241, v72 quad_perm:[0,0,0,0] row_mask:0xf bank_mask:0xf
	v_fmac_f32_dpp v96, v241, v73 quad_perm:[1,1,1,1] row_mask:0xf bank_mask:0xf
	v_fmac_f32_dpp v97, v241, v74 quad_perm:[2,2,2,2] row_mask:0xf bank_mask:0xf
	v_fmac_f32_dpp v98, v241, v75 quad_perm:[3,3,3,3] row_mask:0xf bank_mask:0xf
	s_waitcnt lgkmcnt(0)
	v_fmac_f32_dpp v79, v242, v76 quad_perm:[0,0,0,0] row_mask:0xf bank_mask:0xf
	v_fmac_f32_dpp v96, v242, v77 quad_perm:[1,1,1,1] row_mask:0xf bank_mask:0xf
	ds_read_b32 v240, v255 offset:15104
	ds_read_b32 v241, v255 offset:15120
	ds_read_b32 v242, v255 offset:15136
	ds_read_b32 v243, v255 offset:15152
	ds_read_b32 v244, v255 offset:15168
	ds_read_b32 v245, v255 offset:15184
	ds_read_b32 v246, v255 offset:15200
	ds_read_b32 v247, v255 offset:15216
	ds_read_b32 v248, v255 offset:15232
	ds_read_b32 v249, v255 offset:15248
	ds_read_b32 v250, v255 offset:15264
	ds_read_b32 v251, v255 offset:15280
	v_add_f32_e32 v79, v79, v96
	v_add_f32_e32 v80, v97, v98
	v_add_f32_e32 v79, v80, v79
	v_sub_f32_e32 v78, v78, v79
	v_lshlrev_b32_e32 v79, 16, v238
	v_mul_f32_e32 v79, v239, v79
	s_and_saveexec_b64 s[0:1], s[16:17]
	s_cbranch_execz .LBB0_923
	v_mul_f32_e32 v79, v79, v254
.LBB0_923:
	s_or_b64 exec, exec, s[0:1]
	ds_read_u16 v238, v18 offset:16320
	ds_read_b32 v239, v16 offset:240
	ds_read_b32 v254, v15 offset:240
	s_waitcnt lgkmcnt(14)
	v_mul_f32_dpp v96, v240, v2 quad_perm:[0,0,0,0] row_mask:0xf bank_mask:0xf
	v_mul_f32_dpp v97, v240, v3 quad_perm:[1,1,1,1] row_mask:0xf bank_mask:0xf
	v_mul_f32_dpp v98, v240, v4 quad_perm:[2,2,2,2] row_mask:0xf bank_mask:0xf
	v_mul_f32_dpp v99, v240, v5 quad_perm:[3,3,3,3] row_mask:0xf bank_mask:0xf
	ds_read_b32 v240, v255 offset:15296
	s_waitcnt lgkmcnt(14)
	v_fmac_f32_dpp v96, v241, v6 quad_perm:[0,0,0,0] row_mask:0xf bank_mask:0xf
	v_fmac_f32_dpp v97, v241, v7 quad_perm:[1,1,1,1] row_mask:0xf bank_mask:0xf
	v_fmac_f32_dpp v98, v241, v8 quad_perm:[2,2,2,2] row_mask:0xf bank_mask:0xf
	v_fmac_f32_dpp v99, v241, v9 quad_perm:[3,3,3,3] row_mask:0xf bank_mask:0xf
	ds_read_b32 v241, v255 offset:15312
	s_waitcnt lgkmcnt(14)
	v_fmac_f32_dpp v96, v242, v10 quad_perm:[0,0,0,0] row_mask:0xf bank_mask:0xf
	v_fmac_f32_dpp v97, v242, v12 quad_perm:[1,1,1,1] row_mask:0xf bank_mask:0xf
	v_fmac_f32_dpp v98, v242, v13 quad_perm:[2,2,2,2] row_mask:0xf bank_mask:0xf
	v_fmac_f32_dpp v99, v242, v14 quad_perm:[3,3,3,3] row_mask:0xf bank_mask:0xf
	ds_read_b32 v242, v255 offset:15328
	s_waitcnt lgkmcnt(14)
	v_fmac_f32_dpp v96, v243, v17 quad_perm:[0,0,0,0] row_mask:0xf bank_mask:0xf
	v_fmac_f32_dpp v97, v243, v19 quad_perm:[1,1,1,1] row_mask:0xf bank_mask:0xf
	v_fmac_f32_dpp v98, v243, v28 quad_perm:[2,2,2,2] row_mask:0xf bank_mask:0xf
	v_fmac_f32_dpp v99, v243, v35 quad_perm:[3,3,3,3] row_mask:0xf bank_mask:0xf
	s_waitcnt lgkmcnt(13)
	v_fmac_f32_dpp v96, v244, v36 quad_perm:[0,0,0,0] row_mask:0xf bank_mask:0xf
	v_fmac_f32_dpp v97, v244, v37 quad_perm:[1,1,1,1] row_mask:0xf bank_mask:0xf
	v_fmac_f32_dpp v98, v244, v38 quad_perm:[2,2,2,2] row_mask:0xf bank_mask:0xf
	v_fmac_f32_dpp v99, v244, v39 quad_perm:[3,3,3,3] row_mask:0xf bank_mask:0xf
	s_waitcnt lgkmcnt(12)
	v_fmac_f32_dpp v96, v245, v40 quad_perm:[0,0,0,0] row_mask:0xf bank_mask:0xf
	v_fmac_f32_dpp v97, v245, v41 quad_perm:[1,1,1,1] row_mask:0xf bank_mask:0xf
	v_fmac_f32_dpp v98, v245, v42 quad_perm:[2,2,2,2] row_mask:0xf bank_mask:0xf
	v_fmac_f32_dpp v99, v245, v43 quad_perm:[3,3,3,3] row_mask:0xf bank_mask:0xf
	s_waitcnt lgkmcnt(11)
	v_fmac_f32_dpp v96, v246, v44 quad_perm:[0,0,0,0] row_mask:0xf bank_mask:0xf
	v_fmac_f32_dpp v97, v246, v45 quad_perm:[1,1,1,1] row_mask:0xf bank_mask:0xf
	v_fmac_f32_dpp v98, v246, v46 quad_perm:[2,2,2,2] row_mask:0xf bank_mask:0xf
	v_fmac_f32_dpp v99, v246, v47 quad_perm:[3,3,3,3] row_mask:0xf bank_mask:0xf
	s_waitcnt lgkmcnt(10)
	v_fmac_f32_dpp v96, v247, v48 quad_perm:[0,0,0,0] row_mask:0xf bank_mask:0xf
	v_fmac_f32_dpp v97, v247, v49 quad_perm:[1,1,1,1] row_mask:0xf bank_mask:0xf
	v_fmac_f32_dpp v98, v247, v50 quad_perm:[2,2,2,2] row_mask:0xf bank_mask:0xf
	v_fmac_f32_dpp v99, v247, v51 quad_perm:[3,3,3,3] row_mask:0xf bank_mask:0xf
	s_waitcnt lgkmcnt(9)
	v_fmac_f32_dpp v96, v248, v52 quad_perm:[0,0,0,0] row_mask:0xf bank_mask:0xf
	v_fmac_f32_dpp v97, v248, v53 quad_perm:[1,1,1,1] row_mask:0xf bank_mask:0xf
	v_fmac_f32_dpp v98, v248, v54 quad_perm:[2,2,2,2] row_mask:0xf bank_mask:0xf
	v_fmac_f32_dpp v99, v248, v55 quad_perm:[3,3,3,3] row_mask:0xf bank_mask:0xf
	s_waitcnt lgkmcnt(8)
	v_fmac_f32_dpp v96, v249, v56 quad_perm:[0,0,0,0] row_mask:0xf bank_mask:0xf
	v_fmac_f32_dpp v97, v249, v57 quad_perm:[1,1,1,1] row_mask:0xf bank_mask:0xf
	v_fmac_f32_dpp v98, v249, v58 quad_perm:[2,2,2,2] row_mask:0xf bank_mask:0xf
	v_fmac_f32_dpp v99, v249, v59 quad_perm:[3,3,3,3] row_mask:0xf bank_mask:0xf
	s_waitcnt lgkmcnt(7)
	v_fmac_f32_dpp v96, v250, v60 quad_perm:[0,0,0,0] row_mask:0xf bank_mask:0xf
	v_fmac_f32_dpp v97, v250, v61 quad_perm:[1,1,1,1] row_mask:0xf bank_mask:0xf
	v_fmac_f32_dpp v98, v250, v62 quad_perm:[2,2,2,2] row_mask:0xf bank_mask:0xf
	v_fmac_f32_dpp v99, v250, v63 quad_perm:[3,3,3,3] row_mask:0xf bank_mask:0xf
	s_waitcnt lgkmcnt(6)
	v_fmac_f32_dpp v96, v251, v64 quad_perm:[0,0,0,0] row_mask:0xf bank_mask:0xf
	v_fmac_f32_dpp v97, v251, v65 quad_perm:[1,1,1,1] row_mask:0xf bank_mask:0xf
	v_fmac_f32_dpp v98, v251, v66 quad_perm:[2,2,2,2] row_mask:0xf bank_mask:0xf
	v_fmac_f32_dpp v99, v251, v67 quad_perm:[3,3,3,3] row_mask:0xf bank_mask:0xf
	s_waitcnt lgkmcnt(2)
	v_fmac_f32_dpp v96, v240, v68 quad_perm:[0,0,0,0] row_mask:0xf bank_mask:0xf
	v_fmac_f32_dpp v97, v240, v69 quad_perm:[1,1,1,1] row_mask:0xf bank_mask:0xf
	v_fmac_f32_dpp v98, v240, v70 quad_perm:[2,2,2,2] row_mask:0xf bank_mask:0xf
	v_fmac_f32_dpp v99, v240, v71 quad_perm:[3,3,3,3] row_mask:0xf bank_mask:0xf
	s_waitcnt lgkmcnt(1)
	v_fmac_f32_dpp v96, v241, v72 quad_perm:[0,0,0,0] row_mask:0xf bank_mask:0xf
	v_fmac_f32_dpp v97, v241, v73 quad_perm:[1,1,1,1] row_mask:0xf bank_mask:0xf
	v_fmac_f32_dpp v98, v241, v74 quad_perm:[2,2,2,2] row_mask:0xf bank_mask:0xf
	v_fmac_f32_dpp v99, v241, v75 quad_perm:[3,3,3,3] row_mask:0xf bank_mask:0xf
	s_waitcnt lgkmcnt(0)
	v_fmac_f32_dpp v96, v242, v76 quad_perm:[0,0,0,0] row_mask:0xf bank_mask:0xf
	v_fmac_f32_dpp v97, v242, v77 quad_perm:[1,1,1,1] row_mask:0xf bank_mask:0xf
	v_fmac_f32_dpp v98, v242, v78 quad_perm:[2,2,2,2] row_mask:0xf bank_mask:0xf
	ds_read_b32 v240, v255 offset:15360
	ds_read_b32 v241, v255 offset:15376
	ds_read_b32 v242, v255 offset:15392
	ds_read_b32 v243, v255 offset:15408
	ds_read_b32 v244, v255 offset:15424
	ds_read_b32 v245, v255 offset:15440
	ds_read_b32 v246, v255 offset:15456
	ds_read_b32 v247, v255 offset:15472
	ds_read_b32 v248, v255 offset:15488
	ds_read_b32 v249, v255 offset:15504
	ds_read_b32 v250, v255 offset:15520
	ds_read_b32 v251, v255 offset:15536
	v_add_f32_e32 v80, v96, v97
	v_add_f32_e32 v81, v99, v98
	v_add_f32_e32 v80, v80, v81
	v_sub_f32_e32 v79, v79, v80
	v_lshlrev_b32_e32 v80, 16, v238
	v_mul_f32_e32 v80, v239, v80
	s_and_saveexec_b64 s[0:1], s[16:17]
	s_cbranch_execz .LBB0_925
	v_mul_f32_e32 v80, v80, v254
.LBB0_925:
	s_or_b64 exec, exec, s[0:1]
	ds_read_u16 v238, v18 offset:16592
	ds_read_b32 v239, v16 offset:244
	ds_read_b32 v254, v15 offset:244
	s_waitcnt lgkmcnt(14)
	v_mul_f32_dpp v81, v240, v2 quad_perm:[0,0,0,0] row_mask:0xf bank_mask:0xf
	v_mul_f32_dpp v98, v240, v3 quad_perm:[1,1,1,1] row_mask:0xf bank_mask:0xf
	v_mul_f32_dpp v99, v240, v4 quad_perm:[2,2,2,2] row_mask:0xf bank_mask:0xf
	v_mul_f32_dpp v100, v240, v5 quad_perm:[3,3,3,3] row_mask:0xf bank_mask:0xf
	ds_read_b32 v240, v255 offset:15552
	s_waitcnt lgkmcnt(14)
	v_fmac_f32_dpp v81, v241, v6 quad_perm:[0,0,0,0] row_mask:0xf bank_mask:0xf
	v_fmac_f32_dpp v98, v241, v7 quad_perm:[1,1,1,1] row_mask:0xf bank_mask:0xf
	v_fmac_f32_dpp v99, v241, v8 quad_perm:[2,2,2,2] row_mask:0xf bank_mask:0xf
	v_fmac_f32_dpp v100, v241, v9 quad_perm:[3,3,3,3] row_mask:0xf bank_mask:0xf
	ds_read_b32 v241, v255 offset:15568
	s_waitcnt lgkmcnt(14)
	v_fmac_f32_dpp v81, v242, v10 quad_perm:[0,0,0,0] row_mask:0xf bank_mask:0xf
	v_fmac_f32_dpp v98, v242, v12 quad_perm:[1,1,1,1] row_mask:0xf bank_mask:0xf
	v_fmac_f32_dpp v99, v242, v13 quad_perm:[2,2,2,2] row_mask:0xf bank_mask:0xf
	v_fmac_f32_dpp v100, v242, v14 quad_perm:[3,3,3,3] row_mask:0xf bank_mask:0xf
	ds_read_b32 v242, v255 offset:15584
	s_waitcnt lgkmcnt(14)
	v_fmac_f32_dpp v81, v243, v17 quad_perm:[0,0,0,0] row_mask:0xf bank_mask:0xf
	v_fmac_f32_dpp v98, v243, v19 quad_perm:[1,1,1,1] row_mask:0xf bank_mask:0xf
	v_fmac_f32_dpp v99, v243, v28 quad_perm:[2,2,2,2] row_mask:0xf bank_mask:0xf
	v_fmac_f32_dpp v100, v243, v35 quad_perm:[3,3,3,3] row_mask:0xf bank_mask:0xf
	s_waitcnt lgkmcnt(13)
	v_fmac_f32_dpp v81, v244, v36 quad_perm:[0,0,0,0] row_mask:0xf bank_mask:0xf
	v_fmac_f32_dpp v98, v244, v37 quad_perm:[1,1,1,1] row_mask:0xf bank_mask:0xf
	v_fmac_f32_dpp v99, v244, v38 quad_perm:[2,2,2,2] row_mask:0xf bank_mask:0xf
	v_fmac_f32_dpp v100, v244, v39 quad_perm:[3,3,3,3] row_mask:0xf bank_mask:0xf
	s_waitcnt lgkmcnt(12)
	v_fmac_f32_dpp v81, v245, v40 quad_perm:[0,0,0,0] row_mask:0xf bank_mask:0xf
	v_fmac_f32_dpp v98, v245, v41 quad_perm:[1,1,1,1] row_mask:0xf bank_mask:0xf
	v_fmac_f32_dpp v99, v245, v42 quad_perm:[2,2,2,2] row_mask:0xf bank_mask:0xf
	v_fmac_f32_dpp v100, v245, v43 quad_perm:[3,3,3,3] row_mask:0xf bank_mask:0xf
	s_waitcnt lgkmcnt(11)
	v_fmac_f32_dpp v81, v246, v44 quad_perm:[0,0,0,0] row_mask:0xf bank_mask:0xf
	v_fmac_f32_dpp v98, v246, v45 quad_perm:[1,1,1,1] row_mask:0xf bank_mask:0xf
	v_fmac_f32_dpp v99, v246, v46 quad_perm:[2,2,2,2] row_mask:0xf bank_mask:0xf
	v_fmac_f32_dpp v100, v246, v47 quad_perm:[3,3,3,3] row_mask:0xf bank_mask:0xf
	s_waitcnt lgkmcnt(10)
	v_fmac_f32_dpp v81, v247, v48 quad_perm:[0,0,0,0] row_mask:0xf bank_mask:0xf
	v_fmac_f32_dpp v98, v247, v49 quad_perm:[1,1,1,1] row_mask:0xf bank_mask:0xf
	v_fmac_f32_dpp v99, v247, v50 quad_perm:[2,2,2,2] row_mask:0xf bank_mask:0xf
	v_fmac_f32_dpp v100, v247, v51 quad_perm:[3,3,3,3] row_mask:0xf bank_mask:0xf
	s_waitcnt lgkmcnt(9)
	v_fmac_f32_dpp v81, v248, v52 quad_perm:[0,0,0,0] row_mask:0xf bank_mask:0xf
	v_fmac_f32_dpp v98, v248, v53 quad_perm:[1,1,1,1] row_mask:0xf bank_mask:0xf
	v_fmac_f32_dpp v99, v248, v54 quad_perm:[2,2,2,2] row_mask:0xf bank_mask:0xf
	v_fmac_f32_dpp v100, v248, v55 quad_perm:[3,3,3,3] row_mask:0xf bank_mask:0xf
	s_waitcnt lgkmcnt(8)
	v_fmac_f32_dpp v81, v249, v56 quad_perm:[0,0,0,0] row_mask:0xf bank_mask:0xf
	v_fmac_f32_dpp v98, v249, v57 quad_perm:[1,1,1,1] row_mask:0xf bank_mask:0xf
	v_fmac_f32_dpp v99, v249, v58 quad_perm:[2,2,2,2] row_mask:0xf bank_mask:0xf
	v_fmac_f32_dpp v100, v249, v59 quad_perm:[3,3,3,3] row_mask:0xf bank_mask:0xf
	s_waitcnt lgkmcnt(7)
	v_fmac_f32_dpp v81, v250, v60 quad_perm:[0,0,0,0] row_mask:0xf bank_mask:0xf
	v_fmac_f32_dpp v98, v250, v61 quad_perm:[1,1,1,1] row_mask:0xf bank_mask:0xf
	v_fmac_f32_dpp v99, v250, v62 quad_perm:[2,2,2,2] row_mask:0xf bank_mask:0xf
	v_fmac_f32_dpp v100, v250, v63 quad_perm:[3,3,3,3] row_mask:0xf bank_mask:0xf
	s_waitcnt lgkmcnt(6)
	v_fmac_f32_dpp v81, v251, v64 quad_perm:[0,0,0,0] row_mask:0xf bank_mask:0xf
	v_fmac_f32_dpp v98, v251, v65 quad_perm:[1,1,1,1] row_mask:0xf bank_mask:0xf
	v_fmac_f32_dpp v99, v251, v66 quad_perm:[2,2,2,2] row_mask:0xf bank_mask:0xf
	v_fmac_f32_dpp v100, v251, v67 quad_perm:[3,3,3,3] row_mask:0xf bank_mask:0xf
	s_waitcnt lgkmcnt(2)
	v_fmac_f32_dpp v81, v240, v68 quad_perm:[0,0,0,0] row_mask:0xf bank_mask:0xf
	v_fmac_f32_dpp v98, v240, v69 quad_perm:[1,1,1,1] row_mask:0xf bank_mask:0xf
	v_fmac_f32_dpp v99, v240, v70 quad_perm:[2,2,2,2] row_mask:0xf bank_mask:0xf
	v_fmac_f32_dpp v100, v240, v71 quad_perm:[3,3,3,3] row_mask:0xf bank_mask:0xf
	s_waitcnt lgkmcnt(1)
	v_fmac_f32_dpp v81, v241, v72 quad_perm:[0,0,0,0] row_mask:0xf bank_mask:0xf
	v_fmac_f32_dpp v98, v241, v73 quad_perm:[1,1,1,1] row_mask:0xf bank_mask:0xf
	v_fmac_f32_dpp v99, v241, v74 quad_perm:[2,2,2,2] row_mask:0xf bank_mask:0xf
	v_fmac_f32_dpp v100, v241, v75 quad_perm:[3,3,3,3] row_mask:0xf bank_mask:0xf
	s_waitcnt lgkmcnt(0)
	v_fmac_f32_dpp v81, v242, v76 quad_perm:[0,0,0,0] row_mask:0xf bank_mask:0xf
	v_fmac_f32_dpp v98, v242, v77 quad_perm:[1,1,1,1] row_mask:0xf bank_mask:0xf
	v_fmac_f32_dpp v99, v242, v78 quad_perm:[2,2,2,2] row_mask:0xf bank_mask:0xf
	v_fmac_f32_dpp v100, v242, v79 quad_perm:[3,3,3,3] row_mask:0xf bank_mask:0xf
	ds_read_b32 v240, v255 offset:15616
	ds_read_b32 v241, v255 offset:15632
	ds_read_b32 v242, v255 offset:15648
	ds_read_b32 v243, v255 offset:15664
	ds_read_b32 v244, v255 offset:15680
	ds_read_b32 v245, v255 offset:15696
	ds_read_b32 v246, v255 offset:15712
	ds_read_b32 v247, v255 offset:15728
	ds_read_b32 v248, v255 offset:15744
	ds_read_b32 v249, v255 offset:15760
	ds_read_b32 v250, v255 offset:15776
	ds_read_b32 v251, v255 offset:15792
	v_add_f32_e32 v81, v81, v98
	v_add_f32_e32 v82, v99, v100
	v_add_f32_e32 v81, v81, v82
	v_sub_f32_e32 v80, v80, v81
	v_lshlrev_b32_e32 v81, 16, v238
	v_mul_f32_e32 v81, v239, v81
	s_and_saveexec_b64 s[0:1], s[16:17]
	s_cbranch_execz .LBB0_927
	v_mul_f32_e32 v81, v81, v254
.LBB0_927:
	s_or_b64 exec, exec, s[0:1]
	ds_read_u16 v238, v18 offset:16864
	ds_read_b32 v239, v16 offset:248
	ds_read_b32 v254, v15 offset:248
	s_waitcnt lgkmcnt(14)
	v_mul_f32_dpp v98, v240, v2 quad_perm:[0,0,0,0] row_mask:0xf bank_mask:0xf
	v_mul_f32_dpp v99, v240, v3 quad_perm:[1,1,1,1] row_mask:0xf bank_mask:0xf
	v_mul_f32_dpp v100, v240, v4 quad_perm:[2,2,2,2] row_mask:0xf bank_mask:0xf
	v_mul_f32_dpp v101, v240, v5 quad_perm:[3,3,3,3] row_mask:0xf bank_mask:0xf
	ds_read_b32 v240, v255 offset:15808
	s_waitcnt lgkmcnt(14)
	v_fmac_f32_dpp v98, v241, v6 quad_perm:[0,0,0,0] row_mask:0xf bank_mask:0xf
	v_fmac_f32_dpp v99, v241, v7 quad_perm:[1,1,1,1] row_mask:0xf bank_mask:0xf
	v_fmac_f32_dpp v100, v241, v8 quad_perm:[2,2,2,2] row_mask:0xf bank_mask:0xf
	v_fmac_f32_dpp v101, v241, v9 quad_perm:[3,3,3,3] row_mask:0xf bank_mask:0xf
	ds_read_b32 v241, v255 offset:15824
	s_waitcnt lgkmcnt(14)
	v_fmac_f32_dpp v98, v242, v10 quad_perm:[0,0,0,0] row_mask:0xf bank_mask:0xf
	v_fmac_f32_dpp v99, v242, v12 quad_perm:[1,1,1,1] row_mask:0xf bank_mask:0xf
	v_fmac_f32_dpp v100, v242, v13 quad_perm:[2,2,2,2] row_mask:0xf bank_mask:0xf
	v_fmac_f32_dpp v101, v242, v14 quad_perm:[3,3,3,3] row_mask:0xf bank_mask:0xf
	ds_read_b32 v242, v255 offset:15840
	s_waitcnt lgkmcnt(14)
	v_fmac_f32_dpp v98, v243, v17 quad_perm:[0,0,0,0] row_mask:0xf bank_mask:0xf
	v_fmac_f32_dpp v99, v243, v19 quad_perm:[1,1,1,1] row_mask:0xf bank_mask:0xf
	v_fmac_f32_dpp v100, v243, v28 quad_perm:[2,2,2,2] row_mask:0xf bank_mask:0xf
	v_fmac_f32_dpp v101, v243, v35 quad_perm:[3,3,3,3] row_mask:0xf bank_mask:0xf
	ds_read_b32 v243, v255 offset:15856
	s_waitcnt lgkmcnt(14)
	v_fmac_f32_dpp v98, v244, v36 quad_perm:[0,0,0,0] row_mask:0xf bank_mask:0xf
	v_fmac_f32_dpp v99, v244, v37 quad_perm:[1,1,1,1] row_mask:0xf bank_mask:0xf
	v_fmac_f32_dpp v100, v244, v38 quad_perm:[2,2,2,2] row_mask:0xf bank_mask:0xf
	v_fmac_f32_dpp v101, v244, v39 quad_perm:[3,3,3,3] row_mask:0xf bank_mask:0xf
	s_waitcnt lgkmcnt(13)
	v_fmac_f32_dpp v98, v245, v40 quad_perm:[0,0,0,0] row_mask:0xf bank_mask:0xf
	v_fmac_f32_dpp v99, v245, v41 quad_perm:[1,1,1,1] row_mask:0xf bank_mask:0xf
	v_fmac_f32_dpp v100, v245, v42 quad_perm:[2,2,2,2] row_mask:0xf bank_mask:0xf
	v_fmac_f32_dpp v101, v245, v43 quad_perm:[3,3,3,3] row_mask:0xf bank_mask:0xf
	s_waitcnt lgkmcnt(12)
	v_fmac_f32_dpp v98, v246, v44 quad_perm:[0,0,0,0] row_mask:0xf bank_mask:0xf
	v_fmac_f32_dpp v99, v246, v45 quad_perm:[1,1,1,1] row_mask:0xf bank_mask:0xf
	v_fmac_f32_dpp v100, v246, v46 quad_perm:[2,2,2,2] row_mask:0xf bank_mask:0xf
	v_fmac_f32_dpp v101, v246, v47 quad_perm:[3,3,3,3] row_mask:0xf bank_mask:0xf
	s_waitcnt lgkmcnt(11)
	v_fmac_f32_dpp v98, v247, v48 quad_perm:[0,0,0,0] row_mask:0xf bank_mask:0xf
	v_fmac_f32_dpp v99, v247, v49 quad_perm:[1,1,1,1] row_mask:0xf bank_mask:0xf
	v_fmac_f32_dpp v100, v247, v50 quad_perm:[2,2,2,2] row_mask:0xf bank_mask:0xf
	v_fmac_f32_dpp v101, v247, v51 quad_perm:[3,3,3,3] row_mask:0xf bank_mask:0xf
	s_waitcnt lgkmcnt(10)
	v_fmac_f32_dpp v98, v248, v52 quad_perm:[0,0,0,0] row_mask:0xf bank_mask:0xf
	v_fmac_f32_dpp v99, v248, v53 quad_perm:[1,1,1,1] row_mask:0xf bank_mask:0xf
	v_fmac_f32_dpp v100, v248, v54 quad_perm:[2,2,2,2] row_mask:0xf bank_mask:0xf
	v_fmac_f32_dpp v101, v248, v55 quad_perm:[3,3,3,3] row_mask:0xf bank_mask:0xf
	s_waitcnt lgkmcnt(9)
	v_fmac_f32_dpp v98, v249, v56 quad_perm:[0,0,0,0] row_mask:0xf bank_mask:0xf
	v_fmac_f32_dpp v99, v249, v57 quad_perm:[1,1,1,1] row_mask:0xf bank_mask:0xf
	v_fmac_f32_dpp v100, v249, v58 quad_perm:[2,2,2,2] row_mask:0xf bank_mask:0xf
	v_fmac_f32_dpp v101, v249, v59 quad_perm:[3,3,3,3] row_mask:0xf bank_mask:0xf
	s_waitcnt lgkmcnt(8)
	v_fmac_f32_dpp v98, v250, v60 quad_perm:[0,0,0,0] row_mask:0xf bank_mask:0xf
	v_fmac_f32_dpp v99, v250, v61 quad_perm:[1,1,1,1] row_mask:0xf bank_mask:0xf
	v_fmac_f32_dpp v100, v250, v62 quad_perm:[2,2,2,2] row_mask:0xf bank_mask:0xf
	v_fmac_f32_dpp v101, v250, v63 quad_perm:[3,3,3,3] row_mask:0xf bank_mask:0xf
	s_waitcnt lgkmcnt(7)
	v_fmac_f32_dpp v98, v251, v64 quad_perm:[0,0,0,0] row_mask:0xf bank_mask:0xf
	v_fmac_f32_dpp v99, v251, v65 quad_perm:[1,1,1,1] row_mask:0xf bank_mask:0xf
	v_fmac_f32_dpp v100, v251, v66 quad_perm:[2,2,2,2] row_mask:0xf bank_mask:0xf
	v_fmac_f32_dpp v101, v251, v67 quad_perm:[3,3,3,3] row_mask:0xf bank_mask:0xf
	s_waitcnt lgkmcnt(3)
	v_fmac_f32_dpp v98, v240, v68 quad_perm:[0,0,0,0] row_mask:0xf bank_mask:0xf
	v_fmac_f32_dpp v99, v240, v69 quad_perm:[1,1,1,1] row_mask:0xf bank_mask:0xf
	v_fmac_f32_dpp v100, v240, v70 quad_perm:[2,2,2,2] row_mask:0xf bank_mask:0xf
	v_fmac_f32_dpp v101, v240, v71 quad_perm:[3,3,3,3] row_mask:0xf bank_mask:0xf
	s_waitcnt lgkmcnt(2)
	v_fmac_f32_dpp v98, v241, v72 quad_perm:[0,0,0,0] row_mask:0xf bank_mask:0xf
	v_fmac_f32_dpp v99, v241, v73 quad_perm:[1,1,1,1] row_mask:0xf bank_mask:0xf
	v_fmac_f32_dpp v100, v241, v74 quad_perm:[2,2,2,2] row_mask:0xf bank_mask:0xf
	v_fmac_f32_dpp v101, v241, v75 quad_perm:[3,3,3,3] row_mask:0xf bank_mask:0xf
	s_waitcnt lgkmcnt(1)
	v_fmac_f32_dpp v98, v242, v76 quad_perm:[0,0,0,0] row_mask:0xf bank_mask:0xf
	v_fmac_f32_dpp v99, v242, v77 quad_perm:[1,1,1,1] row_mask:0xf bank_mask:0xf
	v_fmac_f32_dpp v100, v242, v78 quad_perm:[2,2,2,2] row_mask:0xf bank_mask:0xf
	v_fmac_f32_dpp v101, v242, v79 quad_perm:[3,3,3,3] row_mask:0xf bank_mask:0xf
	s_waitcnt lgkmcnt(0)
	v_fmac_f32_dpp v98, v243, v80 quad_perm:[0,0,0,0] row_mask:0xf bank_mask:0xf
	ds_read_b32 v240, v255 offset:15872
	ds_read_b32 v241, v255 offset:15888
	ds_read_b32 v242, v255 offset:15904
	ds_read_b32 v243, v255 offset:15920
	ds_read_b32 v244, v255 offset:15936
	ds_read_b32 v245, v255 offset:15952
	ds_read_b32 v246, v255 offset:15968
	ds_read_b32 v247, v255 offset:15984
	ds_read_b32 v248, v255 offset:16000
	ds_read_b32 v249, v255 offset:16016
	ds_read_b32 v250, v255 offset:16032
	ds_read_b32 v251, v255 offset:16048
	v_add_f32_e32 v82, v99, v98
	v_add_f32_e32 v83, v100, v101
	v_add_f32_e32 v82, v83, v82
	v_sub_f32_e32 v81, v81, v82
	v_lshlrev_b32_e32 v82, 16, v238
	v_mul_f32_e32 v82, v239, v82
	s_and_saveexec_b64 s[0:1], s[16:17]
	s_cbranch_execz .LBB0_929
	v_mul_f32_e32 v82, v82, v254
.LBB0_929:
	s_or_b64 exec, exec, s[0:1]
	ds_read_u16 v238, v18 offset:17136
	ds_read_b32 v239, v16 offset:252
	ds_read_b32 v254, v15 offset:252
	s_waitcnt lgkmcnt(14)
	v_mul_f32_dpp v83, v240, v2 quad_perm:[0,0,0,0] row_mask:0xf bank_mask:0xf
	v_mul_f32_dpp v100, v240, v3 quad_perm:[1,1,1,1] row_mask:0xf bank_mask:0xf
	v_mul_f32_dpp v101, v240, v4 quad_perm:[2,2,2,2] row_mask:0xf bank_mask:0xf
	v_mul_f32_dpp v102, v240, v5 quad_perm:[3,3,3,3] row_mask:0xf bank_mask:0xf
	ds_read_b32 v240, v255 offset:16064
	s_waitcnt lgkmcnt(14)
	v_fmac_f32_dpp v83, v241, v6 quad_perm:[0,0,0,0] row_mask:0xf bank_mask:0xf
	v_fmac_f32_dpp v100, v241, v7 quad_perm:[1,1,1,1] row_mask:0xf bank_mask:0xf
	v_fmac_f32_dpp v101, v241, v8 quad_perm:[2,2,2,2] row_mask:0xf bank_mask:0xf
	v_fmac_f32_dpp v102, v241, v9 quad_perm:[3,3,3,3] row_mask:0xf bank_mask:0xf
	ds_read_b32 v241, v255 offset:16080
	s_waitcnt lgkmcnt(14)
	v_fmac_f32_dpp v83, v242, v10 quad_perm:[0,0,0,0] row_mask:0xf bank_mask:0xf
	v_fmac_f32_dpp v100, v242, v12 quad_perm:[1,1,1,1] row_mask:0xf bank_mask:0xf
	v_fmac_f32_dpp v101, v242, v13 quad_perm:[2,2,2,2] row_mask:0xf bank_mask:0xf
	v_fmac_f32_dpp v102, v242, v14 quad_perm:[3,3,3,3] row_mask:0xf bank_mask:0xf
	ds_read_b32 v242, v255 offset:16096
	s_waitcnt lgkmcnt(14)
	v_fmac_f32_dpp v83, v243, v17 quad_perm:[0,0,0,0] row_mask:0xf bank_mask:0xf
	v_fmac_f32_dpp v100, v243, v19 quad_perm:[1,1,1,1] row_mask:0xf bank_mask:0xf
	v_fmac_f32_dpp v101, v243, v28 quad_perm:[2,2,2,2] row_mask:0xf bank_mask:0xf
	v_fmac_f32_dpp v102, v243, v35 quad_perm:[3,3,3,3] row_mask:0xf bank_mask:0xf
	ds_read_b32 v243, v255 offset:16112
	s_waitcnt lgkmcnt(14)
	v_fmac_f32_dpp v83, v244, v36 quad_perm:[0,0,0,0] row_mask:0xf bank_mask:0xf
	v_fmac_f32_dpp v100, v244, v37 quad_perm:[1,1,1,1] row_mask:0xf bank_mask:0xf
	v_fmac_f32_dpp v101, v244, v38 quad_perm:[2,2,2,2] row_mask:0xf bank_mask:0xf
	v_fmac_f32_dpp v102, v244, v39 quad_perm:[3,3,3,3] row_mask:0xf bank_mask:0xf
	s_waitcnt lgkmcnt(13)
	v_fmac_f32_dpp v83, v245, v40 quad_perm:[0,0,0,0] row_mask:0xf bank_mask:0xf
	v_fmac_f32_dpp v100, v245, v41 quad_perm:[1,1,1,1] row_mask:0xf bank_mask:0xf
	v_fmac_f32_dpp v101, v245, v42 quad_perm:[2,2,2,2] row_mask:0xf bank_mask:0xf
	v_fmac_f32_dpp v102, v245, v43 quad_perm:[3,3,3,3] row_mask:0xf bank_mask:0xf
	s_waitcnt lgkmcnt(12)
	v_fmac_f32_dpp v83, v246, v44 quad_perm:[0,0,0,0] row_mask:0xf bank_mask:0xf
	v_fmac_f32_dpp v100, v246, v45 quad_perm:[1,1,1,1] row_mask:0xf bank_mask:0xf
	v_fmac_f32_dpp v101, v246, v46 quad_perm:[2,2,2,2] row_mask:0xf bank_mask:0xf
	v_fmac_f32_dpp v102, v246, v47 quad_perm:[3,3,3,3] row_mask:0xf bank_mask:0xf
	s_waitcnt lgkmcnt(11)
	v_fmac_f32_dpp v83, v247, v48 quad_perm:[0,0,0,0] row_mask:0xf bank_mask:0xf
	v_fmac_f32_dpp v100, v247, v49 quad_perm:[1,1,1,1] row_mask:0xf bank_mask:0xf
	v_fmac_f32_dpp v101, v247, v50 quad_perm:[2,2,2,2] row_mask:0xf bank_mask:0xf
	v_fmac_f32_dpp v102, v247, v51 quad_perm:[3,3,3,3] row_mask:0xf bank_mask:0xf
	s_waitcnt lgkmcnt(10)
	v_fmac_f32_dpp v83, v248, v52 quad_perm:[0,0,0,0] row_mask:0xf bank_mask:0xf
	v_fmac_f32_dpp v100, v248, v53 quad_perm:[1,1,1,1] row_mask:0xf bank_mask:0xf
	v_fmac_f32_dpp v101, v248, v54 quad_perm:[2,2,2,2] row_mask:0xf bank_mask:0xf
	v_fmac_f32_dpp v102, v248, v55 quad_perm:[3,3,3,3] row_mask:0xf bank_mask:0xf
	s_waitcnt lgkmcnt(9)
	v_fmac_f32_dpp v83, v249, v56 quad_perm:[0,0,0,0] row_mask:0xf bank_mask:0xf
	v_fmac_f32_dpp v100, v249, v57 quad_perm:[1,1,1,1] row_mask:0xf bank_mask:0xf
	v_fmac_f32_dpp v101, v249, v58 quad_perm:[2,2,2,2] row_mask:0xf bank_mask:0xf
	v_fmac_f32_dpp v102, v249, v59 quad_perm:[3,3,3,3] row_mask:0xf bank_mask:0xf
	s_waitcnt lgkmcnt(8)
	v_fmac_f32_dpp v83, v250, v60 quad_perm:[0,0,0,0] row_mask:0xf bank_mask:0xf
	v_fmac_f32_dpp v100, v250, v61 quad_perm:[1,1,1,1] row_mask:0xf bank_mask:0xf
	v_fmac_f32_dpp v101, v250, v62 quad_perm:[2,2,2,2] row_mask:0xf bank_mask:0xf
	v_fmac_f32_dpp v102, v250, v63 quad_perm:[3,3,3,3] row_mask:0xf bank_mask:0xf
	s_waitcnt lgkmcnt(7)
	v_fmac_f32_dpp v83, v251, v64 quad_perm:[0,0,0,0] row_mask:0xf bank_mask:0xf
	v_fmac_f32_dpp v100, v251, v65 quad_perm:[1,1,1,1] row_mask:0xf bank_mask:0xf
	v_fmac_f32_dpp v101, v251, v66 quad_perm:[2,2,2,2] row_mask:0xf bank_mask:0xf
	v_fmac_f32_dpp v102, v251, v67 quad_perm:[3,3,3,3] row_mask:0xf bank_mask:0xf
	s_waitcnt lgkmcnt(3)
	v_fmac_f32_dpp v83, v240, v68 quad_perm:[0,0,0,0] row_mask:0xf bank_mask:0xf
	v_fmac_f32_dpp v100, v240, v69 quad_perm:[1,1,1,1] row_mask:0xf bank_mask:0xf
	v_fmac_f32_dpp v101, v240, v70 quad_perm:[2,2,2,2] row_mask:0xf bank_mask:0xf
	v_fmac_f32_dpp v102, v240, v71 quad_perm:[3,3,3,3] row_mask:0xf bank_mask:0xf
	s_waitcnt lgkmcnt(2)
	v_fmac_f32_dpp v83, v241, v72 quad_perm:[0,0,0,0] row_mask:0xf bank_mask:0xf
	v_fmac_f32_dpp v100, v241, v73 quad_perm:[1,1,1,1] row_mask:0xf bank_mask:0xf
	v_fmac_f32_dpp v101, v241, v74 quad_perm:[2,2,2,2] row_mask:0xf bank_mask:0xf
	v_fmac_f32_dpp v102, v241, v75 quad_perm:[3,3,3,3] row_mask:0xf bank_mask:0xf
	s_waitcnt lgkmcnt(1)
	v_fmac_f32_dpp v83, v242, v76 quad_perm:[0,0,0,0] row_mask:0xf bank_mask:0xf
	v_fmac_f32_dpp v100, v242, v77 quad_perm:[1,1,1,1] row_mask:0xf bank_mask:0xf
	v_fmac_f32_dpp v101, v242, v78 quad_perm:[2,2,2,2] row_mask:0xf bank_mask:0xf
	v_fmac_f32_dpp v102, v242, v79 quad_perm:[3,3,3,3] row_mask:0xf bank_mask:0xf
	s_waitcnt lgkmcnt(0)
	v_fmac_f32_dpp v83, v243, v80 quad_perm:[0,0,0,0] row_mask:0xf bank_mask:0xf
	v_fmac_f32_dpp v100, v243, v81 quad_perm:[1,1,1,1] row_mask:0xf bank_mask:0xf
	ds_read_b32 v240, v255 offset:16128
	ds_read_b32 v241, v255 offset:16144
	ds_read_b32 v242, v255 offset:16160
	ds_read_b32 v243, v255 offset:16176
	ds_read_b32 v244, v255 offset:16192
	ds_read_b32 v245, v255 offset:16208
	ds_read_b32 v246, v255 offset:16224
	ds_read_b32 v247, v255 offset:16240
	ds_read_b32 v248, v255 offset:16256
	ds_read_b32 v249, v255 offset:16272
	ds_read_b32 v250, v255 offset:16288
	ds_read_b32 v251, v255 offset:16304
	v_add_f32_e32 v83, v83, v100
	v_add_f32_e32 v84, v101, v102
	v_add_f32_e32 v83, v84, v83
	v_sub_f32_e32 v82, v82, v83
	v_lshlrev_b32_e32 v18, 16, v238
	v_mul_f32_e32 v16, v239, v18
	s_and_saveexec_b64 s[0:1], s[16:17]
	s_cbranch_execz .LBB0_931
	v_mul_f32_e32 v16, v16, v254
.LBB0_931:
	s_or_b64 exec, exec, s[0:1]
	s_waitcnt lgkmcnt(11)
	v_mul_f32_dpp v15, v240, v2 quad_perm:[0,0,0,0] row_mask:0xf bank_mask:0xf
	v_mul_f32_dpp v18, v240, v3 quad_perm:[1,1,1,1] row_mask:0xf bank_mask:0xf
	v_mul_f32_dpp v83, v240, v4 quad_perm:[2,2,2,2] row_mask:0xf bank_mask:0xf
	v_mul_f32_dpp v100, v240, v5 quad_perm:[3,3,3,3] row_mask:0xf bank_mask:0xf
	ds_read_b32 v240, v255 offset:16320
	s_waitcnt lgkmcnt(11)
	v_fmac_f32_dpp v15, v241, v6 quad_perm:[0,0,0,0] row_mask:0xf bank_mask:0xf
	v_fmac_f32_dpp v18, v241, v7 quad_perm:[1,1,1,1] row_mask:0xf bank_mask:0xf
	v_fmac_f32_dpp v83, v241, v8 quad_perm:[2,2,2,2] row_mask:0xf bank_mask:0xf
	v_fmac_f32_dpp v100, v241, v9 quad_perm:[3,3,3,3] row_mask:0xf bank_mask:0xf
	ds_read_b32 v241, v255 offset:16336
	s_waitcnt lgkmcnt(11)
	v_fmac_f32_dpp v15, v242, v10 quad_perm:[0,0,0,0] row_mask:0xf bank_mask:0xf
	v_fmac_f32_dpp v18, v242, v12 quad_perm:[1,1,1,1] row_mask:0xf bank_mask:0xf
	v_fmac_f32_dpp v83, v242, v13 quad_perm:[2,2,2,2] row_mask:0xf bank_mask:0xf
	v_fmac_f32_dpp v100, v242, v14 quad_perm:[3,3,3,3] row_mask:0xf bank_mask:0xf
	ds_read_b32 v242, v255 offset:16352
	s_waitcnt lgkmcnt(11)
	v_fmac_f32_dpp v15, v243, v17 quad_perm:[0,0,0,0] row_mask:0xf bank_mask:0xf
	v_fmac_f32_dpp v18, v243, v19 quad_perm:[1,1,1,1] row_mask:0xf bank_mask:0xf
	v_fmac_f32_dpp v83, v243, v28 quad_perm:[2,2,2,2] row_mask:0xf bank_mask:0xf
	v_fmac_f32_dpp v100, v243, v35 quad_perm:[3,3,3,3] row_mask:0xf bank_mask:0xf
	ds_read_b32 v243, v255 offset:16368
	s_waitcnt lgkmcnt(11)
	v_fmac_f32_dpp v15, v244, v36 quad_perm:[0,0,0,0] row_mask:0xf bank_mask:0xf
	v_fmac_f32_dpp v18, v244, v37 quad_perm:[1,1,1,1] row_mask:0xf bank_mask:0xf
	v_fmac_f32_dpp v83, v244, v38 quad_perm:[2,2,2,2] row_mask:0xf bank_mask:0xf
	v_fmac_f32_dpp v100, v244, v39 quad_perm:[3,3,3,3] row_mask:0xf bank_mask:0xf
	s_waitcnt lgkmcnt(10)
	v_fmac_f32_dpp v15, v245, v40 quad_perm:[0,0,0,0] row_mask:0xf bank_mask:0xf
	v_fmac_f32_dpp v18, v245, v41 quad_perm:[1,1,1,1] row_mask:0xf bank_mask:0xf
	v_fmac_f32_dpp v83, v245, v42 quad_perm:[2,2,2,2] row_mask:0xf bank_mask:0xf
	v_fmac_f32_dpp v100, v245, v43 quad_perm:[3,3,3,3] row_mask:0xf bank_mask:0xf
	s_waitcnt lgkmcnt(9)
	v_fmac_f32_dpp v15, v246, v44 quad_perm:[0,0,0,0] row_mask:0xf bank_mask:0xf
	v_fmac_f32_dpp v18, v246, v45 quad_perm:[1,1,1,1] row_mask:0xf bank_mask:0xf
	v_fmac_f32_dpp v83, v246, v46 quad_perm:[2,2,2,2] row_mask:0xf bank_mask:0xf
	v_fmac_f32_dpp v100, v246, v47 quad_perm:[3,3,3,3] row_mask:0xf bank_mask:0xf
	s_waitcnt lgkmcnt(8)
	v_fmac_f32_dpp v15, v247, v48 quad_perm:[0,0,0,0] row_mask:0xf bank_mask:0xf
	v_fmac_f32_dpp v18, v247, v49 quad_perm:[1,1,1,1] row_mask:0xf bank_mask:0xf
	v_fmac_f32_dpp v83, v247, v50 quad_perm:[2,2,2,2] row_mask:0xf bank_mask:0xf
	v_fmac_f32_dpp v100, v247, v51 quad_perm:[3,3,3,3] row_mask:0xf bank_mask:0xf
	s_waitcnt lgkmcnt(7)
	v_fmac_f32_dpp v15, v248, v52 quad_perm:[0,0,0,0] row_mask:0xf bank_mask:0xf
	v_fmac_f32_dpp v18, v248, v53 quad_perm:[1,1,1,1] row_mask:0xf bank_mask:0xf
	v_fmac_f32_dpp v83, v248, v54 quad_perm:[2,2,2,2] row_mask:0xf bank_mask:0xf
	v_fmac_f32_dpp v100, v248, v55 quad_perm:[3,3,3,3] row_mask:0xf bank_mask:0xf
	s_waitcnt lgkmcnt(6)
	v_fmac_f32_dpp v15, v249, v56 quad_perm:[0,0,0,0] row_mask:0xf bank_mask:0xf
	v_fmac_f32_dpp v18, v249, v57 quad_perm:[1,1,1,1] row_mask:0xf bank_mask:0xf
	v_fmac_f32_dpp v83, v249, v58 quad_perm:[2,2,2,2] row_mask:0xf bank_mask:0xf
	v_fmac_f32_dpp v100, v249, v59 quad_perm:[3,3,3,3] row_mask:0xf bank_mask:0xf
	s_waitcnt lgkmcnt(5)
	v_fmac_f32_dpp v15, v250, v60 quad_perm:[0,0,0,0] row_mask:0xf bank_mask:0xf
	v_fmac_f32_dpp v18, v250, v61 quad_perm:[1,1,1,1] row_mask:0xf bank_mask:0xf
	v_fmac_f32_dpp v83, v250, v62 quad_perm:[2,2,2,2] row_mask:0xf bank_mask:0xf
	v_fmac_f32_dpp v100, v250, v63 quad_perm:[3,3,3,3] row_mask:0xf bank_mask:0xf
	s_waitcnt lgkmcnt(4)
	v_fmac_f32_dpp v15, v251, v64 quad_perm:[0,0,0,0] row_mask:0xf bank_mask:0xf
	v_fmac_f32_dpp v18, v251, v65 quad_perm:[1,1,1,1] row_mask:0xf bank_mask:0xf
	v_fmac_f32_dpp v83, v251, v66 quad_perm:[2,2,2,2] row_mask:0xf bank_mask:0xf
	v_fmac_f32_dpp v100, v251, v67 quad_perm:[3,3,3,3] row_mask:0xf bank_mask:0xf
	s_waitcnt lgkmcnt(3)
	v_fmac_f32_dpp v15, v240, v68 quad_perm:[0,0,0,0] row_mask:0xf bank_mask:0xf
	v_fmac_f32_dpp v18, v240, v69 quad_perm:[1,1,1,1] row_mask:0xf bank_mask:0xf
	v_fmac_f32_dpp v83, v240, v70 quad_perm:[2,2,2,2] row_mask:0xf bank_mask:0xf
	v_fmac_f32_dpp v100, v240, v71 quad_perm:[3,3,3,3] row_mask:0xf bank_mask:0xf
	s_waitcnt lgkmcnt(2)
	v_fmac_f32_dpp v15, v241, v72 quad_perm:[0,0,0,0] row_mask:0xf bank_mask:0xf
	v_fmac_f32_dpp v18, v241, v73 quad_perm:[1,1,1,1] row_mask:0xf bank_mask:0xf
	v_fmac_f32_dpp v83, v241, v74 quad_perm:[2,2,2,2] row_mask:0xf bank_mask:0xf
	v_fmac_f32_dpp v100, v241, v75 quad_perm:[3,3,3,3] row_mask:0xf bank_mask:0xf
	s_waitcnt lgkmcnt(1)
	v_fmac_f32_dpp v15, v242, v76 quad_perm:[0,0,0,0] row_mask:0xf bank_mask:0xf
	v_fmac_f32_dpp v18, v242, v77 quad_perm:[1,1,1,1] row_mask:0xf bank_mask:0xf
	v_fmac_f32_dpp v83, v242, v78 quad_perm:[2,2,2,2] row_mask:0xf bank_mask:0xf
	v_fmac_f32_dpp v100, v242, v79 quad_perm:[3,3,3,3] row_mask:0xf bank_mask:0xf
	s_waitcnt lgkmcnt(0)
	v_fmac_f32_dpp v15, v243, v80 quad_perm:[0,0,0,0] row_mask:0xf bank_mask:0xf
	v_fmac_f32_dpp v18, v243, v81 quad_perm:[1,1,1,1] row_mask:0xf bank_mask:0xf
	v_fmac_f32_dpp v83, v243, v82 quad_perm:[2,2,2,2] row_mask:0xf bank_mask:0xf
	v_add_f32_e32 v11, v15, v18
	v_add_f32_e32 v15, v100, v83
	v_add_f32_e32 v11, v11, v15
	v_sub_f32_e32 v11, v16, v11
	s_and_saveexec_b64 s[0:1], s[16:17]
	s_xor_b64 s[0:1], exec, s[0:1]
	s_cbranch_execz .LBB0_941
	v_lshl_add_u64 v[84:85], v[22:23], 1, s[70:71]
	v_add_co_u32_e32 v88, vcc, 0x4000, v84
	v_cvt_pk_bf16_f32 v2, v2, s0
	s_mov_b64 s[24:25], 0x4000
	v_addc_co_u32_e32 v89, vcc, 0, v85, vcc
	v_lshl_add_u64 v[86:87], v[84:85], 0, s[24:25]
	global_store_short v[88:89], v2, off
	v_cvt_pk_bf16_f32 v2, v3, s0
	global_store_short v[86:87], v2, off offset:256
	v_cvt_pk_bf16_f32 v2, v4, s0
	global_store_short v[86:87], v2, off offset:512
	v_cvt_pk_bf16_f32 v2, v5, s0
	global_store_short v[86:87], v2, off offset:768
	v_cvt_pk_bf16_f32 v2, v6, s0
	global_store_short v[86:87], v2, off offset:1024
	v_cvt_pk_bf16_f32 v2, v7, s0
	global_store_short v[86:87], v2, off offset:1280
	v_cvt_pk_bf16_f32 v2, v8, s0
	global_store_short v[86:87], v2, off offset:1536
	v_cvt_pk_bf16_f32 v2, v9, s0
	global_store_short v[86:87], v2, off offset:1792
	v_cvt_pk_bf16_f32 v2, v10, s0
	global_store_short v[86:87], v2, off offset:2048
	v_cvt_pk_bf16_f32 v2, v12, s0
	global_store_short v[86:87], v2, off offset:2304
	v_cvt_pk_bf16_f32 v2, v13, s0
	global_store_short v[86:87], v2, off offset:2560
	v_cvt_pk_bf16_f32 v2, v14, s0
	global_store_short v[86:87], v2, off offset:2816
	v_cvt_pk_bf16_f32 v2, v17, s0
	global_store_short v[86:87], v2, off offset:3072
	v_cvt_pk_bf16_f32 v2, v19, s0
	global_store_short v[86:87], v2, off offset:3328
	v_cvt_pk_bf16_f32 v2, v28, s0
	global_store_short v[86:87], v2, off offset:3584
	v_cvt_pk_bf16_f32 v2, v35, s0
	s_movk_i32 s24, 0x5000
	global_store_short v[86:87], v2, off offset:3840
	v_add_co_u32_e32 v2, vcc, s24, v84
	s_movk_i32 s24, 0x6000
	s_nop 0
	v_addc_co_u32_e32 v3, vcc, 0, v85, vcc
	v_add_co_u32_e32 v4, vcc, s24, v84
	v_cvt_pk_bf16_f32 v6, v36, s0
	s_nop 0
	v_addc_co_u32_e32 v5, vcc, 0, v85, vcc
	global_store_short v[4:5], v6, off offset:-4096
	v_cvt_pk_bf16_f32 v6, v37, s0
	global_store_short v[2:3], v6, off offset:256
	v_cvt_pk_bf16_f32 v6, v38, s0
	global_store_short v[2:3], v6, off offset:512
	v_cvt_pk_bf16_f32 v6, v39, s0
	global_store_short v[2:3], v6, off offset:768
	v_cvt_pk_bf16_f32 v6, v40, s0
	global_store_short v[2:3], v6, off offset:1024
	v_cvt_pk_bf16_f32 v6, v41, s0
	global_store_short v[2:3], v6, off offset:1280
	v_cvt_pk_bf16_f32 v6, v42, s0
	global_store_short v[2:3], v6, off offset:1536
	v_cvt_pk_bf16_f32 v6, v43, s0
	global_store_short v[2:3], v6, off offset:1792
	v_cvt_pk_bf16_f32 v6, v44, s0
	global_store_short v[2:3], v6, off offset:2048
	v_cvt_pk_bf16_f32 v6, v45, s0
	global_store_short v[2:3], v6, off offset:2304
	v_cvt_pk_bf16_f32 v6, v46, s0
	global_store_short v[2:3], v6, off offset:2560
	v_cvt_pk_bf16_f32 v6, v47, s0
	global_store_short v[2:3], v6, off offset:2816
	v_cvt_pk_bf16_f32 v6, v48, s0
	global_store_short v[2:3], v6, off offset:3072
	v_cvt_pk_bf16_f32 v6, v49, s0
	global_store_short v[2:3], v6, off offset:3328
	v_cvt_pk_bf16_f32 v6, v50, s0
	global_store_short v[2:3], v6, off offset:3584
	v_cvt_pk_bf16_f32 v6, v51, s0
	global_store_short v[2:3], v6, off offset:3840
	v_cvt_pk_bf16_f32 v2, v52, s0
	global_store_short v[4:5], v2, off
	v_cvt_pk_bf16_f32 v2, v53, s0
	global_store_short v[4:5], v2, off offset:256
	v_cvt_pk_bf16_f32 v2, v54, s0
	global_store_short v[4:5], v2, off offset:512
	v_cvt_pk_bf16_f32 v2, v55, s0
	global_store_short v[4:5], v2, off offset:768
	v_cvt_pk_bf16_f32 v2, v56, s0
	global_store_short v[4:5], v2, off offset:1024
	v_cvt_pk_bf16_f32 v2, v57, s0
	global_store_short v[4:5], v2, off offset:1280
	v_cvt_pk_bf16_f32 v2, v58, s0
	global_store_short v[4:5], v2, off offset:1536
	v_cvt_pk_bf16_f32 v2, v59, s0
	global_store_short v[4:5], v2, off offset:1792
	v_cvt_pk_bf16_f32 v2, v60, s0
	global_store_short v[4:5], v2, off offset:2048
	v_cvt_pk_bf16_f32 v2, v61, s0
	global_store_short v[4:5], v2, off offset:2304
	v_cvt_pk_bf16_f32 v2, v62, s0
	global_store_short v[4:5], v2, off offset:2560
	v_cvt_pk_bf16_f32 v2, v63, s0
	global_store_short v[4:5], v2, off offset:2816
	v_cvt_pk_bf16_f32 v2, v64, s0
	global_store_short v[4:5], v2, off offset:3072
	v_cvt_pk_bf16_f32 v2, v65, s0
	global_store_short v[4:5], v2, off offset:3328
	v_cvt_pk_bf16_f32 v2, v66, s0
	global_store_short v[4:5], v2, off offset:3584
	v_cvt_pk_bf16_f32 v2, v67, s0
	s_movk_i32 s24, 0x7000
	global_store_short v[4:5], v2, off offset:3840
	v_add_co_u32_e32 v2, vcc, s24, v84
	v_cvt_pk_bf16_f32 v4, v68, s0
	s_nop 0
	v_addc_co_u32_e32 v3, vcc, 0, v85, vcc
	global_store_short v[2:3], v4, off
	v_cvt_pk_bf16_f32 v4, v69, s0
	global_store_short v[2:3], v4, off offset:256
	v_cvt_pk_bf16_f32 v4, v70, s0
	global_store_short v[2:3], v4, off offset:512
	v_cvt_pk_bf16_f32 v4, v71, s0
	global_store_short v[2:3], v4, off offset:768
	v_cvt_pk_bf16_f32 v4, v72, s0
	global_store_short v[2:3], v4, off offset:1024
	v_cvt_pk_bf16_f32 v4, v73, s0
	global_store_short v[2:3], v4, off offset:1280
	v_cvt_pk_bf16_f32 v4, v74, s0
	global_store_short v[2:3], v4, off offset:1536
	v_cvt_pk_bf16_f32 v4, v75, s0
	global_store_short v[2:3], v4, off offset:1792
	v_cvt_pk_bf16_f32 v4, v76, s0
	global_store_short v[2:3], v4, off offset:2048
	v_cvt_pk_bf16_f32 v4, v77, s0
	global_store_short v[2:3], v4, off offset:2304
	v_cvt_pk_bf16_f32 v4, v78, s0
	global_store_short v[2:3], v4, off offset:2560
	v_cvt_pk_bf16_f32 v4, v79, s0
	global_store_short v[2:3], v4, off offset:2816
	v_cvt_pk_bf16_f32 v4, v80, s0
	global_store_short v[2:3], v4, off offset:3072
	v_cvt_pk_bf16_f32 v4, v81, s0
	global_store_short v[2:3], v4, off offset:3328
	v_cvt_pk_bf16_f32 v4, v82, s0
	global_store_short v[2:3], v4, off offset:3584
	v_cvt_pk_bf16_f32 v4, v11, s0
	global_store_short v[2:3], v4, off offset:3840
	s_andn2_saveexec_b64 s[0:1], s[0:1]
	s_cbranch_execnz .LBB0_942
